# v57 + K-loop load segments: s_nop after m0 write replaced by a moved ds_read_b128 (62 slots)
# baseline (speedup 1.0000x reference)
; #define PG8_SCHED __builtin_amdgcn_sched_barrier(0)
;     ...
;         for (int t = 0; t < nt; t += 2) {
;             const bool last = (t == nt - 2);
;             const char* a1 = cA + (size_t)(t + 1) * kstep;
;             const char* a2 = last ? nA : cA + (size_t)(t + 2) * kstep; const char* b2 = last ? nB : cB + (size_t)(t + 2) * kstep;
;             const char* a3 = a2 + kstep; const char* b3 = b2 + kstep;
;             if (last && has_next) S.a_ready(nxt);
;             if constexpr (SP2) {
;             PG8_LDB(B0, 0, 0); PG8_LDB(B1, 0, 1); PG8_SCHED; PG8_LDA(At, 0, 0); PG8_STAGE(PG8_SA(1, 1), a1 + hstepA, voffA);
.LBB0_317:
	s_add_u32 s98, s14, 0x80
	s_addc_u32 s99, s15, 0
	s_mov_b32 m0, s49
	ds_read_b128 v[128:131], v155
	global_load_lds_dwordx4 v252, s[98:99]
	s_mov_b32 m0, s50
	ds_read_b128 v[132:135], v155 offset:1024
	global_load_lds_dwordx4 v146, s[98:99]


; #define PG8_SCHED __builtin_amdgcn_sched_barrier(0)
;     ...
;             const bool last = (t == nt - 2);
;             const char* a1 = cA + (size_t)(t + 1) * kstep;
;             const char* a2 = last ? nA : cA + (size_t)(t + 2) * kstep; const char* b2 = last ? nB : cB + (size_t)(t + 2) * kstep;
;             const char* a3 = a2 + kstep; const char* b3 = b2 + kstep;
;             if (last && has_next) S.a_ready(nxt);
;             if constexpr (SP2) {
;             PG8_LDB(B0, 0, 0); PG8_LDB(B1, 0, 1); PG8_SCHED; PG8_LDA(At, 0, 0); PG8_STAGE(PG8_SA(1, 1), a1 + hstepA, voffA);
	ds_read_b128 v[164:167], v155 offset:2048
	ds_read_b128 v[168:171], v155 offset:3072
	ds_read_b128 v[172:175], v156
	ds_read_b128 v[176:179], v156 offset:1024
	ds_read_b128 v[180:183], v156 offset:2048
	ds_read_b128 v[184:187], v156 offset:3072
	s_add_u32 s30, s14, 0x100
	s_addc_u32 s31, s15, 0
	s_cmp_eq_u32 s58, 28
	s_cselect_b32 s38, s23, s30
	s_cselect_b32 s39, s7, s31
	s_cselect_b32 s36, s55, s56
	s_cselect_b32 s37, s21, s57
	s_add_u32 s34, s38, 0x80
	s_addc_u32 s35, s39, 0
	s_add_u32 s14, s14, 0x80080
	s_addc_u32 s15, s15, 0
	s_add_i32 m0, s29, 0xc000
	ds_read_b128 v[188:191], v157
	ds_read_b128 v[192:195], v157 offset:1024
	ds_read_b128 v[196:199], v157 offset:2048
	ds_read_b128 v[200:203], v157 offset:3072
	ds_read_b128 v[204:207], v157 offset:4096
	ds_read_b128 v[208:211], v157 offset:5120
	ds_read_b128 v[212:215], v157 offset:6144

; #define PG8_WAIT_V(n) asm volatile("s_waitcnt vmcnt(" #n ")" ::: "memory")
; #define PG8_WAIT_L(n) asm volatile("s_waitcnt lgkmcnt(" #n ")" ::: "memory")
; #define PG8_BAR __builtin_amdgcn_s_barrier()
; #define PG8_SCHED __builtin_amdgcn_sched_barrier(0)
;     ...
;             PG8_LDB(B0, 0, 0); PG8_LDB(B1, 0, 1); PG8_SCHED; PG8_LDA(At, 0, 0); PG8_STAGE(PG8_SA(1, 1), a1 + hstepA, voffA);
;             PG8_WAIT_V(8); PG8_WAIT_L(0); PG8_BAR; PG8_MMA(0, 0, At, B0); PG8_MMA(0, 1, At, B1); PG8_BAR; PG8_SCHED;
;             if constexpr (!HALFU) PG8_LDA(At, 0, 1); PG8_STAGE(PG8_SB(0, 0), b2, voffB); PG8_STAGE(PG8_SB(0, 1), b2 + hstep, voffB); PG8_STAGE(PG8_SA(0, 0), a2, voffA);
	global_load_lds_dwordx4 v252, s[14:15]
	s_add_i32 m0, s29, 0xe000
	ds_read_b128 v[216:219], v157 offset:7168
	global_load_lds_dwordx4 v146, s[14:15]
	s_waitcnt vmcnt(8)
	s_waitcnt lgkmcnt(0)
	s_setprio 1
	s_barrier
	v_mfma_scale_f32_16x16x128_f8f6f4 v[124:127], v[128:135], v[188:195], v[124:127], v158, v158 op_sel_hi:[0,0,0]
	v_mfma_scale_f32_16x16x128_f8f6f4 v[120:123], v[164:171], v[188:195], v[120:123], v158, v158 op_sel_hi:[0,0,0]
	v_mfma_scale_f32_16x16x128_f8f6f4 v[108:111], v[128:135], v[196:203], v[108:111], v158, v158 op_sel_hi:[0,0,0]
	v_mfma_scale_f32_16x16x128_f8f6f4 v[104:107], v[164:171], v[196:203], v[104:107], v158, v158 op_sel_hi:[0,0,0]
	v_mfma_scale_f32_16x16x128_f8f6f4 v[136:139], v[128:135], v[204:211], v[92:95], v158, v158 op_sel_hi:[0,0,0]
	v_mfma_scale_f32_16x16x128_f8f6f4 v[220:223], v[164:171], v[204:211], v[88:91], v158, v158 op_sel_hi:[0,0,0]
	v_mfma_scale_f32_16x16x128_f8f6f4 v[224:227], v[128:135], v[212:219], v[76:79], v158, v158 op_sel_hi:[0,0,0]
	v_mfma_scale_f32_16x16x128_f8f6f4 v[228:231], v[164:171], v[212:219], v[72:75], v158, v158 op_sel_hi:[0,0,0]
	v_mfma_scale_f32_16x16x128_f8f6f4 v[116:119], v[172:179], v[188:195], v[116:119], v158, v158 op_sel_hi:[0,0,0]
	v_mfma_scale_f32_16x16x128_f8f6f4 v[112:115], v[180:187], v[188:195], v[112:115], v158, v158 op_sel_hi:[0,0,0]
	v_mfma_scale_f32_16x16x128_f8f6f4 v[100:103], v[172:179], v[196:203], v[100:103], v158, v158 op_sel_hi:[0,0,0]
	v_mfma_scale_f32_16x16x128_f8f6f4 v[96:99], v[180:187], v[196:203], v[96:99], v158, v158 op_sel_hi:[0,0,0]
	v_mfma_scale_f32_16x16x128_f8f6f4 v[188:191], v[172:179], v[204:211], v[84:87], v158, v158 op_sel_hi:[0,0,0]
	v_mfma_scale_f32_16x16x128_f8f6f4 v[192:195], v[180:187], v[204:211], v[80:83], v158, v158 op_sel_hi:[0,0,0]
	v_mfma_scale_f32_16x16x128_f8f6f4 v[196:199], v[172:179], v[212:219], v[68:71], v158, v158 op_sel_hi:[0,0,0]
	v_mfma_scale_f32_16x16x128_f8f6f4 v[200:203], v[180:187], v[212:219], v[64:67], v158, v158 op_sel_hi:[0,0,0]
	s_barrier
	s_setprio 0
	s_add_i32 s14, s53, s40
	s_mov_b32 m0, s14
	s_nop 1
	ds_read_b128 v[64:67], v157 offset:16384
	ds_read_b128 v[68:71], v157 offset:17408
	ds_read_b128 v[72:75], v157 offset:18432
	ds_read_b128 v[76:79], v157 offset:19456
	ds_read_b128 v[80:83], v157 offset:20480
	ds_read_b128 v[84:87], v157 offset:21504
	ds_read_b128 v[88:91], v157 offset:22528

; #define PG8_WAIT_V(n) asm volatile("s_waitcnt vmcnt(" #n ")" ::: "memory")
; #define PG8_WAIT_L(n) asm volatile("s_waitcnt lgkmcnt(" #n ")" ::: "memory")
; #define PG8_BAR __builtin_amdgcn_s_barrier()
; #define PG8_SCHED __builtin_amdgcn_sched_barrier(0)
;     ...
;             if constexpr (!HALFU) PG8_LDA(At, 0, 1); PG8_STAGE(PG8_SB(0, 0), b2, voffB); PG8_STAGE(PG8_SB(0, 1), b2 + hstep, voffB); PG8_STAGE(PG8_SA(0, 0), a2, voffA);
;             PG8_WAIT_V(8); PG8_WAIT_L(0); PG8_BAR; if constexpr (!HALFU) { PG8_MMA(1, 0, At, B0); PG8_MMA(1, 1, At, B1); } PG8_BAR; PG8_SCHED;
;             PG8_LDB(B0, 1, 0); PG8_LDB(B1, 1, 1); PG8_SCHED; PG8_LDA(At, 1, 0); PG8_STAGE(PG8_SA(0, 1), a2 + hstepA, voffA);
	global_load_lds_dwordx4 v144, s[36:37]
	s_add_i32 m0, s14, 0x2000
	s_add_u32 s14, s36, 0x80000
	s_addc_u32 s15, s37, 0
	s_add_i32 s59, s54, s40
	global_load_lds_dwordx4 v148, s[36:37]
	s_mov_b32 m0, s59
	ds_read_b128 v[92:95], v157 offset:23552
	global_load_lds_dwordx4 v144, s[14:15]
	s_add_i32 m0, s59, 0x2000
	s_nop 0
	global_load_lds_dwordx4 v148, s[14:15]
	s_waitcnt vmcnt(4)
	s_waitcnt lgkmcnt(0)
	s_setprio 1
	s_barrier
	v_mfma_scale_f32_16x16x128_f8f6f4 v[60:63], v[128:135], v[64:71], v[60:63], v158, v158 op_sel_hi:[0,0,0]
	v_mfma_scale_f32_16x16x128_f8f6f4 v[56:59], v[164:171], v[64:71], v[56:59], v158, v158 op_sel_hi:[0,0,0]
	v_mfma_scale_f32_16x16x128_f8f6f4 v[204:207], v[128:135], v[72:79], v[44:47], v158, v158 op_sel_hi:[0,0,0]
	v_mfma_scale_f32_16x16x128_f8f6f4 v[208:211], v[164:171], v[72:79], v[40:43], v158, v158 op_sel_hi:[0,0,0]
	v_mfma_scale_f32_16x16x128_f8f6f4 v[212:215], v[128:135], v[80:87], v[28:31], v158, v158 op_sel_hi:[0,0,0]
	v_mfma_scale_f32_16x16x128_f8f6f4 v[216:219], v[164:171], v[80:87], v[24:27], v158, v158 op_sel_hi:[0,0,0]
	v_mfma_scale_f32_16x16x128_f8f6f4 v[232:235], v[128:135], v[88:95], v[12:15], v158, v158 op_sel_hi:[0,0,0]
	v_mfma_scale_f32_16x16x128_f8f6f4 v[236:239], v[164:171], v[88:95], v[8:11], v158, v158 op_sel_hi:[0,0,0]
	v_mfma_scale_f32_16x16x128_f8f6f4 v[52:55], v[172:179], v[64:71], v[52:55], v158, v158 op_sel_hi:[0,0,0]
	v_mfma_scale_f32_16x16x128_f8f6f4 v[48:51], v[180:187], v[64:71], v[48:51], v158, v158 op_sel_hi:[0,0,0]
	v_mfma_scale_f32_16x16x128_f8f6f4 v[240:243], v[172:179], v[72:79], v[36:39], v158, v158 op_sel_hi:[0,0,0]
	v_mfma_scale_f32_16x16x128_f8f6f4 v[244:247], v[180:187], v[72:79], v[32:35], v158, v158 op_sel_hi:[0,0,0]
	v_mfma_scale_f32_16x16x128_f8f6f4 v[248:251], v[172:179], v[80:87], v[20:23], v158, v158 op_sel_hi:[0,0,0]
	v_mfma_scale_f32_16x16x128_f8f6f4 v[150:153], v[180:187], v[80:87], v[16:19], v158, v158 op_sel_hi:[0,0,0]
	v_mfma_scale_f32_16x16x128_f8f6f4 v[160:163], v[172:179], v[88:95], v[4:7], v158, v158 op_sel_hi:[0,0,0]
	v_mfma_scale_f32_16x16x128_f8f6f4 v[140:143], v[180:187], v[88:95], v[0:3], v158, v158 op_sel_hi:[0,0,0]
	s_barrier
	s_setprio 0
	s_mov_b32 m0, s29
	s_nop 0
	global_load_lds_dwordx4 v252, s[38:39]
	s_mov_b32 m0, s41
	s_nop 0
	global_load_lds_dwordx4 v146, s[38:39]
	s_add_i32 s59, 0, 0x18000
	v_add_u32_e32 v8, s59, v154
	s_add_i32 s60, 0, 0x1c000
	s_nop 1
	ds_read_b128 v[0:3], v8
	ds_read_b128 v[4:7], v8 offset:1024
	ds_read_b128 v[16:19], v8 offset:2048
	ds_read_b128 v[20:23], v8 offset:3072
	v_add_u32_e32 v8, s60, v154
	ds_read_b128 v[128:131], v8
	ds_read_b128 v[132:135], v8 offset:1024
	ds_read_b128 v[164:167], v8 offset:2048
	ds_read_b128 v[168:171], v8 offset:3072
	s_add_u32 s14, s38, 0x80000
	s_addc_u32 s15, s39, 0
	s_mov_b32 m0, s42
	ds_read_b128 v[8:11], v157 offset:32768
	ds_read_b128 v[12:15], v157 offset:33792
	ds_read_b128 v[24:27], v157 offset:34816
	ds_read_b128 v[28:31], v157 offset:35840
	ds_read_b128 v[32:35], v157 offset:36864
	ds_read_b128 v[36:39], v157 offset:37888
	ds_read_b128 v[40:43], v157 offset:38912

; #define PG8_WAIT_V(n) asm volatile("s_waitcnt vmcnt(" #n ")" ::: "memory")
; #define PG8_WAIT_L(n) asm volatile("s_waitcnt lgkmcnt(" #n ")" ::: "memory")
; #define PG8_BAR __builtin_amdgcn_s_barrier()
; #define PG8_SCHED __builtin_amdgcn_sched_barrier(0)
;     ...
;             PG8_LDB(B0, 1, 0); PG8_LDB(B1, 1, 1); PG8_SCHED; PG8_LDA(At, 1, 0); PG8_STAGE(PG8_SA(0, 1), a2 + hstepA, voffA);
;             PG8_WAIT_V(8); PG8_WAIT_L(0); PG8_BAR; PG8_MMA(0, 0, At, B0); PG8_MMA(0, 1, At, B1); PG8_BAR; PG8_SCHED;
;             if constexpr (!HALFU) PG8_LDA(At, 1, 1); PG8_STAGE(PG8_SB(1, 0), b3, voffB); PG8_STAGE(PG8_SB(1, 1), b3 + hstep, voffB); PG8_STAGE(PG8_SA(1, 0), a3, voffA);
	global_load_lds_dwordx4 v252, s[14:15]
	s_mov_b32 m0, s43
	ds_read_b128 v[44:47], v157 offset:39936
	global_load_lds_dwordx4 v146, s[14:15]
	s_waitcnt vmcnt(8)
	s_waitcnt lgkmcnt(0)
	s_setprio 1
	s_barrier
	v_mfma_scale_f32_16x16x128_f8f6f4 v[124:127], v[0:7], v[8:15], v[124:127], v158, v158 op_sel_hi:[0,0,0]
	v_mfma_scale_f32_16x16x128_f8f6f4 v[120:123], v[16:23], v[8:15], v[120:123], v158, v158 op_sel_hi:[0,0,0]
	v_mfma_scale_f32_16x16x128_f8f6f4 v[108:111], v[0:7], v[24:31], v[108:111], v158, v158 op_sel_hi:[0,0,0]
	v_mfma_scale_f32_16x16x128_f8f6f4 v[104:107], v[16:23], v[24:31], v[104:107], v158, v158 op_sel_hi:[0,0,0]
	v_mfma_scale_f32_16x16x128_f8f6f4 v[92:95], v[0:7], v[32:39], v[136:139], v158, v158 op_sel_hi:[0,0,0]
	v_mfma_scale_f32_16x16x128_f8f6f4 v[88:91], v[16:23], v[32:39], v[220:223], v158, v158 op_sel_hi:[0,0,0]
	v_mfma_scale_f32_16x16x128_f8f6f4 v[76:79], v[0:7], v[40:47], v[224:227], v158, v158 op_sel_hi:[0,0,0]
	v_mfma_scale_f32_16x16x128_f8f6f4 v[72:75], v[16:23], v[40:47], v[228:231], v158, v158 op_sel_hi:[0,0,0]
	v_mfma_scale_f32_16x16x128_f8f6f4 v[116:119], v[128:135], v[8:15], v[116:119], v158, v158 op_sel_hi:[0,0,0]
	v_mfma_scale_f32_16x16x128_f8f6f4 v[112:115], v[164:171], v[8:15], v[112:115], v158, v158 op_sel_hi:[0,0,0]
	v_mfma_scale_f32_16x16x128_f8f6f4 v[100:103], v[128:135], v[24:31], v[100:103], v158, v158 op_sel_hi:[0,0,0]
	v_mfma_scale_f32_16x16x128_f8f6f4 v[96:99], v[164:171], v[24:31], v[96:99], v158, v158 op_sel_hi:[0,0,0]
	v_mfma_scale_f32_16x16x128_f8f6f4 v[84:87], v[128:135], v[32:39], v[188:191], v158, v158 op_sel_hi:[0,0,0]
	v_mfma_scale_f32_16x16x128_f8f6f4 v[80:83], v[164:171], v[32:39], v[192:195], v158, v158 op_sel_hi:[0,0,0]
	v_mfma_scale_f32_16x16x128_f8f6f4 v[68:71], v[128:135], v[40:47], v[196:199], v158, v158 op_sel_hi:[0,0,0]
	v_mfma_scale_f32_16x16x128_f8f6f4 v[64:67], v[164:171], v[40:47], v[200:203], v158, v158 op_sel_hi:[0,0,0]
	s_barrier
	s_setprio 0
	s_add_u32 s14, s36, 0x80
	s_addc_u32 s15, s37, 0
	s_add_i32 s38, s59, s40
	s_mov_b32 m0, s38
	ds_read_b128 v[32:35], v157 offset:49152
	ds_read_b128 v[36:39], v157 offset:50176
	ds_read_b128 v[172:175], v157 offset:51200
	ds_read_b128 v[176:179], v157 offset:52224
	ds_read_b128 v[180:183], v157 offset:53248
	ds_read_b128 v[184:187], v157 offset:54272
	ds_read_b128 v[188:191], v157 offset:55296

; #define PG8_WAIT_V(n) asm volatile("s_waitcnt vmcnt(" #n ")" ::: "memory")
; #define PG8_WAIT_L(n) asm volatile("s_waitcnt lgkmcnt(" #n ")" ::: "memory")
; #define PG8_BAR __builtin_amdgcn_s_barrier()
; #define PG8_SCHED __builtin_amdgcn_sched_barrier(0)
;     ...
;             if constexpr (!HALFU) PG8_LDA(At, 1, 1); PG8_STAGE(PG8_SB(1, 0), b3, voffB); PG8_STAGE(PG8_SB(1, 1), b3 + hstep, voffB); PG8_STAGE(PG8_SA(1, 0), a3, voffA);
;             PG8_WAIT_V(8); PG8_WAIT_L(0); PG8_BAR; if constexpr (!HALFU) { PG8_MMA(1, 0, At, B0); PG8_MMA(1, 1, At, B1); } PG8_BAR; PG8_SCHED;
;     ...
;         if constexpr (ALIGN_EPI) { if (wr == 0) PG8_BAR; }
	global_load_lds_dwordx4 v144, s[14:15]
	s_add_i32 m0, s38, 0x2000
	v_lshl_add_u64 v[8:9], s[14:15], 0, v[148:149]
	s_add_u32 s14, s36, 0x80080
	s_addc_u32 s15, s37, 0
	s_add_i32 s36, s60, s40
	global_load_lds_dwordx4 v[8:9], off
	s_mov_b32 m0, s36
	ds_read_b128 v[192:195], v157 offset:56320
	global_load_lds_dwordx4 v144, s[14:15]
	s_add_i32 m0, s36, 0x2000
	s_nop 0
	global_load_lds_dwordx4 v148, s[14:15]
	s_waitcnt vmcnt(4)
	s_waitcnt lgkmcnt(0)
	s_setprio 1
	s_barrier
	v_mfma_scale_f32_16x16x128_f8f6f4 v[60:63], v[0:7], v[32:39], v[60:63], v158, v158 op_sel_hi:[0,0,0]
	v_mfma_scale_f32_16x16x128_f8f6f4 v[56:59], v[16:23], v[32:39], v[56:59], v158, v158 op_sel_hi:[0,0,0]
	v_mfma_scale_f32_16x16x128_f8f6f4 v[44:47], v[0:7], v[172:179], v[204:207], v158, v158 op_sel_hi:[0,0,0]
	v_mfma_scale_f32_16x16x128_f8f6f4 v[40:43], v[16:23], v[172:179], v[208:211], v158, v158 op_sel_hi:[0,0,0]
	v_mfma_scale_f32_16x16x128_f8f6f4 v[28:31], v[0:7], v[180:187], v[212:215], v158, v158 op_sel_hi:[0,0,0]
	v_mfma_scale_f32_16x16x128_f8f6f4 v[24:27], v[16:23], v[180:187], v[216:219], v158, v158 op_sel_hi:[0,0,0]
	v_mfma_scale_f32_16x16x128_f8f6f4 v[12:15], v[0:7], v[188:195], v[232:235], v158, v158 op_sel_hi:[0,0,0]
	v_mfma_scale_f32_16x16x128_f8f6f4 v[8:11], v[16:23], v[188:195], v[236:239], v158, v158 op_sel_hi:[0,0,0]
	v_mfma_scale_f32_16x16x128_f8f6f4 v[52:55], v[128:135], v[32:39], v[52:55], v158, v158 op_sel_hi:[0,0,0]
	v_mfma_scale_f32_16x16x128_f8f6f4 v[48:51], v[164:171], v[32:39], v[48:51], v158, v158 op_sel_hi:[0,0,0]
	v_mfma_scale_f32_16x16x128_f8f6f4 v[36:39], v[128:135], v[172:179], v[240:243], v158, v158 op_sel_hi:[0,0,0]
	v_mfma_scale_f32_16x16x128_f8f6f4 v[32:35], v[164:171], v[172:179], v[244:247], v158, v158 op_sel_hi:[0,0,0]
	v_mfma_scale_f32_16x16x128_f8f6f4 v[20:23], v[128:135], v[180:187], v[248:251], v158, v158 op_sel_hi:[0,0,0]
	v_mfma_scale_f32_16x16x128_f8f6f4 v[16:19], v[164:171], v[180:187], v[150:153], v158, v158 op_sel_hi:[0,0,0]
	v_mfma_scale_f32_16x16x128_f8f6f4 v[4:7], v[128:135], v[188:195], v[160:163], v158, v158 op_sel_hi:[0,0,0]
	v_mfma_scale_f32_16x16x128_f8f6f4 v[0:3], v[164:171], v[188:195], v[140:143], v158, v158 op_sel_hi:[0,0,0]
	s_barrier
	s_setprio 0
	s_add_i32 s58, s58, 2
	s_add_u32 s56, s56, 0x100
	s_addc_u32 s57, s57, 0
	s_cmp_gt_u32 s58, 29
	s_mov_b64 s[14:15], s[30:31]
	s_cbranch_scc0 .LBB0_317
	s_and_b64 vcc, exec, s[16:17]
	s_cbranch_vccz .LBB0_320
	s_barrier

; #define PG8_SCHED __builtin_amdgcn_sched_barrier(0)
;     ...
;         for (int t = 0; t < nt; t += 2) {
;             const bool last = (t == nt - 2);
;             const char* a1 = cA + (size_t)(t + 1) * kstep;
;             const char* a2 = last ? nA : cA + (size_t)(t + 2) * kstep; const char* b2 = last ? nB : cB + (size_t)(t + 2) * kstep;
;             const char* a3 = a2 + kstep; const char* b3 = b2 + kstep;
;             if (last && has_next) S.a_ready(nxt);
;             if constexpr (SP2) {
;             PG8_LDB(B0, 0, 0); PG8_LDB(B1, 0, 1); PG8_SCHED; PG8_LDA(At, 0, 0); PG8_STAGE(PG8_SA(1, 1), a1 + hstepA, voffA);
.LBB0_542:
	s_add_u32 s98, s28, 0x80
	s_addc_u32 s99, s29, 0
	s_mov_b32 m0, s53
	ds_read_b128 v[142:145], v137
	global_load_lds_dwordx4 v128, s[98:99]
	s_mov_b32 m0, s54
	ds_read_b128 v[146:149], v137 offset:1024
	global_load_lds_dwordx4 v130, s[98:99]


; #define PG8_SCHED __builtin_amdgcn_sched_barrier(0)
;     ...
;             const bool last = (t == nt - 2);
;             const char* a1 = cA + (size_t)(t + 1) * kstep;
;             const char* a2 = last ? nA : cA + (size_t)(t + 2) * kstep; const char* b2 = last ? nB : cB + (size_t)(t + 2) * kstep;
;             const char* a3 = a2 + kstep; const char* b3 = b2 + kstep;
;             if (last && has_next) S.a_ready(nxt);
;             if constexpr (SP2) {
;             PG8_LDB(B0, 0, 0); PG8_LDB(B1, 0, 1); PG8_SCHED; PG8_LDA(At, 0, 0); PG8_STAGE(PG8_SA(1, 1), a1 + hstepA, voffA);
	ds_read_b128 v[150:153], v137 offset:2048
	ds_read_b128 v[154:157], v137 offset:3072
	ds_read_b128 v[158:161], v138
	ds_read_b128 v[162:165], v138 offset:1024
	ds_read_b128 v[166:169], v138 offset:2048
	ds_read_b128 v[170:173], v138 offset:3072
	s_add_u32 s30, s28, 0x100
	s_addc_u32 s31, s29, 0
	s_cmp_eq_u32 s61, 12
	s_cselect_b32 s40, s57, s30
	s_cselect_b32 s41, s23, s31
	s_cselect_b32 s38, s58, s59
	s_cselect_b32 s39, s21, s60
	s_add_u32 s36, s40, 0x80
	s_addc_u32 s37, s41, 0
	s_add_u32 s28, s28, 0x40080
	s_addc_u32 s29, s29, 0
	s_add_i32 m0, s45, 0xc000
	ds_read_b128 v[174:177], v139
	ds_read_b128 v[178:181], v139 offset:1024
	ds_read_b128 v[182:185], v139 offset:2048
	ds_read_b128 v[186:189], v139 offset:3072
	ds_read_b128 v[190:193], v139 offset:4096
	ds_read_b128 v[194:197], v139 offset:5120
	ds_read_b128 v[198:201], v139 offset:6144

; #define PG8_WAIT_V(n) asm volatile("s_waitcnt vmcnt(" #n ")" ::: "memory")
; #define PG8_WAIT_L(n) asm volatile("s_waitcnt lgkmcnt(" #n ")" ::: "memory")
; #define PG8_BAR __builtin_amdgcn_s_barrier()
; #define PG8_SCHED __builtin_amdgcn_sched_barrier(0)
;     ...
;             PG8_LDB(B0, 0, 0); PG8_LDB(B1, 0, 1); PG8_SCHED; PG8_LDA(At, 0, 0); PG8_STAGE(PG8_SA(1, 1), a1 + hstepA, voffA);
;             PG8_WAIT_V(8); PG8_WAIT_L(0); PG8_BAR; PG8_MMA(0, 0, At, B0); PG8_MMA(0, 1, At, B1); PG8_BAR; PG8_SCHED;
;             if constexpr (!HALFU) PG8_LDA(At, 0, 1); PG8_STAGE(PG8_SB(0, 0), b2, voffB); PG8_STAGE(PG8_SB(0, 1), b2 + hstep, voffB); PG8_STAGE(PG8_SA(0, 0), a2, voffA);
	global_load_lds_dwordx4 v128, s[28:29]
	s_add_i32 m0, s45, 0xe000
	ds_read_b128 v[202:205], v139 offset:7168
	global_load_lds_dwordx4 v130, s[28:29]
	s_waitcnt vmcnt(8)
	s_waitcnt lgkmcnt(0)
	s_setprio 1
	s_barrier
	v_mfma_scale_f32_16x16x128_f8f6f4 v[124:127], v[142:149], v[174:181], v[124:127], v140, v140 op_sel_hi:[0,0,0]
	v_mfma_scale_f32_16x16x128_f8f6f4 v[120:123], v[150:157], v[174:181], v[120:123], v140, v140 op_sel_hi:[0,0,0]
	v_mfma_scale_f32_16x16x128_f8f6f4 v[108:111], v[142:149], v[182:189], v[108:111], v140, v140 op_sel_hi:[0,0,0]
	v_mfma_scale_f32_16x16x128_f8f6f4 v[104:107], v[150:157], v[182:189], v[104:107], v140, v140 op_sel_hi:[0,0,0]
	v_mfma_scale_f32_16x16x128_f8f6f4 v[96:99], v[142:149], v[190:197], v[96:99], v140, v140 op_sel_hi:[0,0,0]
	v_mfma_scale_f32_16x16x128_f8f6f4 v[206:209], v[150:157], v[190:197], v[88:91], v140, v140 op_sel_hi:[0,0,0]
	v_mfma_scale_f32_16x16x128_f8f6f4 v[210:213], v[142:149], v[198:205], v[80:83], v140, v140 op_sel_hi:[0,0,0]
	v_mfma_scale_f32_16x16x128_f8f6f4 v[214:217], v[150:157], v[198:205], v[72:75], v140, v140 op_sel_hi:[0,0,0]
	v_mfma_scale_f32_16x16x128_f8f6f4 v[116:119], v[158:165], v[174:181], v[116:119], v140, v140 op_sel_hi:[0,0,0]
	v_mfma_scale_f32_16x16x128_f8f6f4 v[112:115], v[166:173], v[174:181], v[112:115], v140, v140 op_sel_hi:[0,0,0]
	v_mfma_scale_f32_16x16x128_f8f6f4 v[100:103], v[158:165], v[182:189], v[100:103], v140, v140 op_sel_hi:[0,0,0]
	v_mfma_scale_f32_16x16x128_f8f6f4 v[174:177], v[166:173], v[182:189], v[92:95], v140, v140 op_sel_hi:[0,0,0]
	v_mfma_scale_f32_16x16x128_f8f6f4 v[178:181], v[158:165], v[190:197], v[84:87], v140, v140 op_sel_hi:[0,0,0]
	v_mfma_scale_f32_16x16x128_f8f6f4 v[182:185], v[166:173], v[190:197], v[76:79], v140, v140 op_sel_hi:[0,0,0]
	v_mfma_scale_f32_16x16x128_f8f6f4 v[186:189], v[158:165], v[198:205], v[68:71], v140, v140 op_sel_hi:[0,0,0]
	v_mfma_scale_f32_16x16x128_f8f6f4 v[190:193], v[166:173], v[198:205], v[64:67], v140, v140 op_sel_hi:[0,0,0]
	s_barrier
	s_setprio 0
	s_add_i32 s28, s55, s43
	s_mov_b32 m0, s28
	s_nop 1
	ds_read_b128 v[64:67], v139 offset:16384
	ds_read_b128 v[68:71], v139 offset:17408
	ds_read_b128 v[72:75], v139 offset:18432
	ds_read_b128 v[76:79], v139 offset:19456
	ds_read_b128 v[80:83], v139 offset:20480
	ds_read_b128 v[84:87], v139 offset:21504
	ds_read_b128 v[88:91], v139 offset:22528

; #define PG8_WAIT_V(n) asm volatile("s_waitcnt vmcnt(" #n ")" ::: "memory")
; #define PG8_WAIT_L(n) asm volatile("s_waitcnt lgkmcnt(" #n ")" ::: "memory")
; #define PG8_BAR __builtin_amdgcn_s_barrier()
; #define PG8_SCHED __builtin_amdgcn_sched_barrier(0)
;     ...
;             if constexpr (!HALFU) PG8_LDA(At, 0, 1); PG8_STAGE(PG8_SB(0, 0), b2, voffB); PG8_STAGE(PG8_SB(0, 1), b2 + hstep, voffB); PG8_STAGE(PG8_SA(0, 0), a2, voffA);
;             PG8_WAIT_V(8); PG8_WAIT_L(0); PG8_BAR; if constexpr (!HALFU) { PG8_MMA(1, 0, At, B0); PG8_MMA(1, 1, At, B1); } PG8_BAR; PG8_SCHED;
;             PG8_LDB(B0, 1, 0); PG8_LDB(B1, 1, 1); PG8_SCHED; PG8_LDA(At, 1, 0); PG8_STAGE(PG8_SA(0, 1), a2 + hstepA, voffA);
	global_load_lds_dwordx4 v128, s[38:39]
	s_add_i32 m0, s28, 0x2000
	s_add_u32 s28, s38, 0x40000
	s_addc_u32 s29, s39, 0
	s_add_i32 s62, s56, s43
	global_load_lds_dwordx4 v130, s[38:39]
	s_mov_b32 m0, s62
	ds_read_b128 v[92:95], v139 offset:23552
	global_load_lds_dwordx4 v128, s[28:29]
	s_add_i32 m0, s62, 0x2000
	s_nop 0
	global_load_lds_dwordx4 v130, s[28:29]
	s_waitcnt vmcnt(4)
	s_waitcnt lgkmcnt(0)
	s_setprio 1
	s_barrier
	v_mfma_scale_f32_16x16x128_f8f6f4 v[60:63], v[142:149], v[64:71], v[60:63], v140, v140 op_sel_hi:[0,0,0]
	v_mfma_scale_f32_16x16x128_f8f6f4 v[56:59], v[150:157], v[64:71], v[56:59], v140, v140 op_sel_hi:[0,0,0]
	v_mfma_scale_f32_16x16x128_f8f6f4 v[48:51], v[142:149], v[72:79], v[48:51], v140, v140 op_sel_hi:[0,0,0]
	v_mfma_scale_f32_16x16x128_f8f6f4 v[194:197], v[150:157], v[72:79], v[40:43], v140, v140 op_sel_hi:[0,0,0]
	v_mfma_scale_f32_16x16x128_f8f6f4 v[198:201], v[142:149], v[80:87], v[32:35], v140, v140 op_sel_hi:[0,0,0]
	v_mfma_scale_f32_16x16x128_f8f6f4 v[202:205], v[150:157], v[80:87], v[24:27], v140, v140 op_sel_hi:[0,0,0]
	v_mfma_scale_f32_16x16x128_f8f6f4 v[218:221], v[142:149], v[88:95], v[16:19], v140, v140 op_sel_hi:[0,0,0]
	v_mfma_scale_f32_16x16x128_f8f6f4 v[222:225], v[150:157], v[88:95], v[8:11], v140, v140 op_sel_hi:[0,0,0]
	v_mfma_scale_f32_16x16x128_f8f6f4 v[52:55], v[158:165], v[64:71], v[52:55], v140, v140 op_sel_hi:[0,0,0]
	v_mfma_scale_f32_16x16x128_f8f6f4 v[226:229], v[166:173], v[64:71], v[44:47], v140, v140 op_sel_hi:[0,0,0]
	v_mfma_scale_f32_16x16x128_f8f6f4 v[230:233], v[158:165], v[72:79], v[36:39], v140, v140 op_sel_hi:[0,0,0]
	v_mfma_scale_f32_16x16x128_f8f6f4 v[234:237], v[166:173], v[72:79], v[28:31], v140, v140 op_sel_hi:[0,0,0]
	v_mfma_scale_f32_16x16x128_f8f6f4 v[238:241], v[158:165], v[80:87], v[20:23], v140, v140 op_sel_hi:[0,0,0]
	v_mfma_scale_f32_16x16x128_f8f6f4 v[242:245], v[166:173], v[80:87], v[12:15], v140, v140 op_sel_hi:[0,0,0]
	v_mfma_scale_f32_16x16x128_f8f6f4 v[246:249], v[158:165], v[88:95], v[4:7], v140, v140 op_sel_hi:[0,0,0]
	v_mfma_scale_f32_16x16x128_f8f6f4 v[250:253], v[166:173], v[88:95], v[0:3], v140, v140 op_sel_hi:[0,0,0]
	s_barrier
	s_setprio 0
	s_mov_b32 m0, s45
	s_nop 0
	global_load_lds_dwordx4 v128, s[40:41]
	s_mov_b32 m0, s46
	s_nop 0
	global_load_lds_dwordx4 v130, s[40:41]
	s_add_i32 s62, 0, 0x18000
	s_add_i32 s63, 0, 0x1c000
	s_nop 0
	v_add_u32_e32 v12, s62, v136
	v_add_u32_e32 v16, s63, v136
	ds_read_b128 v[0:3], v12
	ds_read_b128 v[4:7], v12 offset:1024
	ds_read_b128 v[8:11], v12 offset:2048
	ds_read_b128 v[12:15], v12 offset:3072
	ds_read_b128 v[142:145], v16
	ds_read_b128 v[146:149], v16 offset:1024
	ds_read_b128 v[150:153], v16 offset:2048
	ds_read_b128 v[154:157], v16 offset:3072
	s_add_u32 s28, s40, 0x40000
	s_addc_u32 s29, s41, 0
	s_mov_b32 m0, s47
	ds_read_b128 v[16:19], v139 offset:32768
	ds_read_b128 v[20:23], v139 offset:33792
	ds_read_b128 v[24:27], v139 offset:34816
	ds_read_b128 v[28:31], v139 offset:35840
	ds_read_b128 v[32:35], v139 offset:36864
	ds_read_b128 v[36:39], v139 offset:37888
	ds_read_b128 v[40:43], v139 offset:38912

; #define PG8_WAIT_V(n) asm volatile("s_waitcnt vmcnt(" #n ")" ::: "memory")
; #define PG8_WAIT_L(n) asm volatile("s_waitcnt lgkmcnt(" #n ")" ::: "memory")
; #define PG8_BAR __builtin_amdgcn_s_barrier()
; #define PG8_SCHED __builtin_amdgcn_sched_barrier(0)
;     ...
;             PG8_LDB(B0, 1, 0); PG8_LDB(B1, 1, 1); PG8_SCHED; PG8_LDA(At, 1, 0); PG8_STAGE(PG8_SA(0, 1), a2 + hstepA, voffA);
;             PG8_WAIT_V(8); PG8_WAIT_L(0); PG8_BAR; PG8_MMA(0, 0, At, B0); PG8_MMA(0, 1, At, B1); PG8_BAR; PG8_SCHED;
;             if constexpr (!HALFU) PG8_LDA(At, 1, 1); PG8_STAGE(PG8_SB(1, 0), b3, voffB); PG8_STAGE(PG8_SB(1, 1), b3 + hstep, voffB); PG8_STAGE(PG8_SA(1, 0), a3, voffA);
	global_load_lds_dwordx4 v128, s[28:29]
	s_mov_b32 m0, s48
	ds_read_b128 v[44:47], v139 offset:39936
	global_load_lds_dwordx4 v130, s[28:29]
	s_waitcnt vmcnt(8)
	s_waitcnt lgkmcnt(0)
	s_setprio 1
	s_barrier
	v_mfma_scale_f32_16x16x128_f8f6f4 v[124:127], v[0:7], v[16:23], v[124:127], v140, v140 op_sel_hi:[0,0,0]
	v_mfma_scale_f32_16x16x128_f8f6f4 v[120:123], v[8:15], v[16:23], v[120:123], v140, v140 op_sel_hi:[0,0,0]
	v_mfma_scale_f32_16x16x128_f8f6f4 v[108:111], v[0:7], v[24:31], v[108:111], v140, v140 op_sel_hi:[0,0,0]
	v_mfma_scale_f32_16x16x128_f8f6f4 v[104:107], v[8:15], v[24:31], v[104:107], v140, v140 op_sel_hi:[0,0,0]
	v_mfma_scale_f32_16x16x128_f8f6f4 v[96:99], v[0:7], v[32:39], v[96:99], v140, v140 op_sel_hi:[0,0,0]
	v_mfma_scale_f32_16x16x128_f8f6f4 v[88:91], v[8:15], v[32:39], v[206:209], v140, v140 op_sel_hi:[0,0,0]
	v_mfma_scale_f32_16x16x128_f8f6f4 v[80:83], v[0:7], v[40:47], v[210:213], v140, v140 op_sel_hi:[0,0,0]
	v_mfma_scale_f32_16x16x128_f8f6f4 v[72:75], v[8:15], v[40:47], v[214:217], v140, v140 op_sel_hi:[0,0,0]
	v_mfma_scale_f32_16x16x128_f8f6f4 v[116:119], v[142:149], v[16:23], v[116:119], v140, v140 op_sel_hi:[0,0,0]
	v_mfma_scale_f32_16x16x128_f8f6f4 v[112:115], v[150:157], v[16:23], v[112:115], v140, v140 op_sel_hi:[0,0,0]
	v_mfma_scale_f32_16x16x128_f8f6f4 v[100:103], v[142:149], v[24:31], v[100:103], v140, v140 op_sel_hi:[0,0,0]
	v_mfma_scale_f32_16x16x128_f8f6f4 v[92:95], v[150:157], v[24:31], v[174:177], v140, v140 op_sel_hi:[0,0,0]
	v_mfma_scale_f32_16x16x128_f8f6f4 v[84:87], v[142:149], v[32:39], v[178:181], v140, v140 op_sel_hi:[0,0,0]
	v_mfma_scale_f32_16x16x128_f8f6f4 v[76:79], v[150:157], v[32:39], v[182:185], v140, v140 op_sel_hi:[0,0,0]
	v_mfma_scale_f32_16x16x128_f8f6f4 v[68:71], v[142:149], v[40:47], v[186:189], v140, v140 op_sel_hi:[0,0,0]
	v_mfma_scale_f32_16x16x128_f8f6f4 v[64:67], v[150:157], v[40:47], v[190:193], v140, v140 op_sel_hi:[0,0,0]
	s_barrier
	s_setprio 0
	s_add_u32 s28, s38, 0x80
	s_addc_u32 s29, s39, 0
	s_add_i32 s40, s62, s43
	s_mov_b32 m0, s40
	ds_read_b128 v[158:161], v139 offset:49152
	ds_read_b128 v[162:165], v139 offset:50176
	ds_read_b128 v[166:169], v139 offset:51200
	ds_read_b128 v[170:173], v139 offset:52224
	ds_read_b128 v[174:177], v139 offset:53248
	ds_read_b128 v[178:181], v139 offset:54272
	ds_read_b128 v[182:185], v139 offset:55296

; #define PG8_WAIT_V(n) asm volatile("s_waitcnt vmcnt(" #n ")" ::: "memory")
; #define PG8_WAIT_L(n) asm volatile("s_waitcnt lgkmcnt(" #n ")" ::: "memory")
; #define PG8_BAR __builtin_amdgcn_s_barrier()
; #define PG8_SCHED __builtin_amdgcn_sched_barrier(0)
;     ...
;             if constexpr (!HALFU) PG8_LDA(At, 1, 1); PG8_STAGE(PG8_SB(1, 0), b3, voffB); PG8_STAGE(PG8_SB(1, 1), b3 + hstep, voffB); PG8_STAGE(PG8_SA(1, 0), a3, voffA);
;             PG8_WAIT_V(8); PG8_WAIT_L(0); PG8_BAR; if constexpr (!HALFU) { PG8_MMA(1, 0, At, B0); PG8_MMA(1, 1, At, B1); } PG8_BAR; PG8_SCHED;
;     ...
;         if constexpr (ALIGN_EPI) { if (wr == 0) PG8_BAR; }
	global_load_lds_dwordx4 v128, s[28:29]
	s_add_i32 m0, s40, 0x2000
	v_lshl_add_u64 v[16:17], s[28:29], 0, v[130:131]
	s_add_u32 s28, s38, 0x40080
	s_addc_u32 s29, s39, 0
	s_add_i32 s38, s63, s43
	global_load_lds_dwordx4 v[16:17], off
	s_mov_b32 m0, s38
	ds_read_b128 v[186:189], v139 offset:56320
	global_load_lds_dwordx4 v128, s[28:29]
	s_add_i32 m0, s38, 0x2000
	s_nop 0
	global_load_lds_dwordx4 v130, s[28:29]
	s_waitcnt vmcnt(4)
	s_waitcnt lgkmcnt(0)
	s_setprio 1
	s_barrier
	v_mfma_scale_f32_16x16x128_f8f6f4 v[60:63], v[0:7], v[158:165], v[60:63], v140, v140 op_sel_hi:[0,0,0]
	v_mfma_scale_f32_16x16x128_f8f6f4 v[56:59], v[8:15], v[158:165], v[56:59], v140, v140 op_sel_hi:[0,0,0]
	v_mfma_scale_f32_16x16x128_f8f6f4 v[48:51], v[0:7], v[166:173], v[48:51], v140, v140 op_sel_hi:[0,0,0]
	v_mfma_scale_f32_16x16x128_f8f6f4 v[40:43], v[8:15], v[166:173], v[194:197], v140, v140 op_sel_hi:[0,0,0]
	v_mfma_scale_f32_16x16x128_f8f6f4 v[32:35], v[0:7], v[174:181], v[198:201], v140, v140 op_sel_hi:[0,0,0]
	v_mfma_scale_f32_16x16x128_f8f6f4 v[24:27], v[8:15], v[174:181], v[202:205], v140, v140 op_sel_hi:[0,0,0]
	v_mfma_scale_f32_16x16x128_f8f6f4 v[16:19], v[0:7], v[182:189], v[218:221], v140, v140 op_sel_hi:[0,0,0]
	v_mfma_scale_f32_16x16x128_f8f6f4 v[8:11], v[8:15], v[182:189], v[222:225], v140, v140 op_sel_hi:[0,0,0]
	v_mfma_scale_f32_16x16x128_f8f6f4 v[52:55], v[142:149], v[158:165], v[52:55], v140, v140 op_sel_hi:[0,0,0]
	v_mfma_scale_f32_16x16x128_f8f6f4 v[44:47], v[150:157], v[158:165], v[226:229], v140, v140 op_sel_hi:[0,0,0]
	v_mfma_scale_f32_16x16x128_f8f6f4 v[36:39], v[142:149], v[166:173], v[230:233], v140, v140 op_sel_hi:[0,0,0]
	v_mfma_scale_f32_16x16x128_f8f6f4 v[28:31], v[150:157], v[166:173], v[234:237], v140, v140 op_sel_hi:[0,0,0]
	v_mfma_scale_f32_16x16x128_f8f6f4 v[20:23], v[142:149], v[174:181], v[238:241], v140, v140 op_sel_hi:[0,0,0]
	v_mfma_scale_f32_16x16x128_f8f6f4 v[12:15], v[150:157], v[174:181], v[242:245], v140, v140 op_sel_hi:[0,0,0]
	v_mfma_scale_f32_16x16x128_f8f6f4 v[4:7], v[142:149], v[182:189], v[246:249], v140, v140 op_sel_hi:[0,0,0]
	v_mfma_scale_f32_16x16x128_f8f6f4 v[0:3], v[150:157], v[182:189], v[250:253], v140, v140 op_sel_hi:[0,0,0]
	s_barrier
	s_setprio 0
	s_add_i32 s61, s61, 2
	s_add_u32 s59, s59, 0x100
	s_addc_u32 s60, s60, 0
	s_cmp_gt_u32 s61, 13
	s_mov_b64 s[28:29], s[30:31]
	s_cbranch_scc0 .LBB0_542
	s_and_b64 vcc, exec, s[6:7]
	s_cbranch_vccz .LBB0_545
	s_barrier

; #define PG8_SCHED __builtin_amdgcn_sched_barrier(0)
;     ...
;         for (int t = 0; t < nt; t += 2) {
;             const bool last = (t == nt - 2);
;             const char* a1 = cA + (size_t)(t + 1) * kstep;
;             const char* a2 = last ? nA : cA + (size_t)(t + 2) * kstep; const char* b2 = last ? nB : cB + (size_t)(t + 2) * kstep;
;             const char* a3 = a2 + kstep; const char* b3 = b2 + kstep;
;             if (last && has_next) S.a_ready(nxt);
;             if constexpr (SP2) {
;             PG8_LDB(B0, 0, 0); PG8_LDB(B1, 0, 1); PG8_SCHED; PG8_LDA(At, 0, 0); PG8_STAGE(PG8_SA(1, 1), a1 + hstepA, voffA);
.LBB0_670:
	s_add_u32 s98, s18, 0x80
	s_addc_u32 s99, s19, 0
	s_mov_b32 m0, s43
	ds_read_b128 v[144:147], v141
	global_load_lds_dwordx4 v134, s[98:99]
	s_mov_b32 m0, s44
	ds_read_b128 v[148:151], v141 offset:1024
	global_load_lds_dwordx4 v132, s[98:99]


; #define PG8_SCHED __builtin_amdgcn_sched_barrier(0)
;     ...
;             const bool last = (t == nt - 2);
;             const char* a1 = cA + (size_t)(t + 1) * kstep;
;             const char* a2 = last ? nA : cA + (size_t)(t + 2) * kstep; const char* b2 = last ? nB : cB + (size_t)(t + 2) * kstep;
;             const char* a3 = a2 + kstep; const char* b3 = b2 + kstep;
;             if (last && has_next) S.a_ready(nxt);
;             if constexpr (SP2) {
;             PG8_LDB(B0, 0, 0); PG8_LDB(B1, 0, 1); PG8_SCHED; PG8_LDA(At, 0, 0); PG8_STAGE(PG8_SA(1, 1), a1 + hstepA, voffA);
	ds_read_b128 v[152:155], v141 offset:2048
	ds_read_b128 v[156:159], v141 offset:3072
	ds_read_b128 v[160:163], v142
	ds_read_b128 v[164:167], v142 offset:1024
	ds_read_b128 v[168:171], v142 offset:2048
	ds_read_b128 v[172:175], v142 offset:3072
	s_add_u32 s20, s18, 0x100
	s_addc_u32 s21, s19, 0
	s_cmp_eq_u32 s53, 60
	s_cselect_b32 s26, s49, s20
	s_cselect_b32 s27, s11, s21
	s_cselect_b32 s24, s50, s51
	s_cselect_b32 s25, s9, s52
	s_add_u32 s22, s26, 0x80
	s_addc_u32 s23, s27, 0
	s_add_u32 s18, s18, 0x100080
	s_addc_u32 s19, s19, 0
	s_add_i32 m0, s17, 0xc000
	ds_read_b128 v[176:179], v143
	ds_read_b128 v[180:183], v143 offset:1024
	ds_read_b128 v[184:187], v143 offset:2048
	ds_read_b128 v[188:191], v143 offset:3072
	ds_read_b128 v[192:195], v143 offset:4096
	ds_read_b128 v[196:199], v143 offset:5120
	ds_read_b128 v[200:203], v143 offset:6144

; #define PG8_WAIT_V(n) asm volatile("s_waitcnt vmcnt(" #n ")" ::: "memory")
; #define PG8_WAIT_L(n) asm volatile("s_waitcnt lgkmcnt(" #n ")" ::: "memory")
; #define PG8_BAR __builtin_amdgcn_s_barrier()
; #define PG8_SCHED __builtin_amdgcn_sched_barrier(0)
;     ...
;             PG8_LDB(B0, 0, 0); PG8_LDB(B1, 0, 1); PG8_SCHED; PG8_LDA(At, 0, 0); PG8_STAGE(PG8_SA(1, 1), a1 + hstepA, voffA);
;             PG8_WAIT_V(8); PG8_WAIT_L(0); PG8_BAR; PG8_MMA(0, 0, At, B0); PG8_MMA(0, 1, At, B1); PG8_BAR; PG8_SCHED;
;             if constexpr (!HALFU) PG8_LDA(At, 0, 1); PG8_STAGE(PG8_SB(0, 0), b2, voffB); PG8_STAGE(PG8_SB(0, 1), b2 + hstep, voffB); PG8_STAGE(PG8_SA(0, 0), a2, voffA);
	global_load_lds_dwordx4 v134, s[18:19]
	s_add_i32 m0, s17, 0xe000
	ds_read_b128 v[204:207], v143 offset:7168
	global_load_lds_dwordx4 v132, s[18:19]
	s_waitcnt vmcnt(8)
	s_waitcnt lgkmcnt(0)
	s_setprio 1
	s_barrier
	v_mfma_f32_16x16x32_bf16 v[124:127], v[144:147], v[176:179], v[124:127]
	v_mfma_f32_16x16x32_bf16 v[120:123], v[152:155], v[176:179], v[120:123]
	v_mfma_f32_16x16x32_bf16 v[108:111], v[144:147], v[184:187], v[108:111]
	v_mfma_f32_16x16x32_bf16 v[104:107], v[152:155], v[184:187], v[104:107]
	v_mfma_f32_16x16x32_bf16 v[92:95], v[144:147], v[192:195], v[92:95]
	v_mfma_f32_16x16x32_bf16 v[88:91], v[152:155], v[192:195], v[88:91]
	v_mfma_f32_16x16x32_bf16 v[76:79], v[144:147], v[200:203], v[76:79]
	v_mfma_f32_16x16x32_bf16 v[72:75], v[152:155], v[200:203], v[72:75]
	v_mfma_f32_16x16x32_bf16 v[124:127], v[148:151], v[180:183], v[124:127]
	v_mfma_f32_16x16x32_bf16 v[120:123], v[156:159], v[180:183], v[120:123]
	v_mfma_f32_16x16x32_bf16 v[108:111], v[148:151], v[188:191], v[108:111]
	v_mfma_f32_16x16x32_bf16 v[104:107], v[156:159], v[188:191], v[104:107]
	v_mfma_f32_16x16x32_bf16 v[92:95], v[148:151], v[196:199], v[92:95]
	v_mfma_f32_16x16x32_bf16 v[88:91], v[156:159], v[196:199], v[88:91]
	v_mfma_f32_16x16x32_bf16 v[76:79], v[148:151], v[204:207], v[76:79]
	v_mfma_f32_16x16x32_bf16 v[72:75], v[156:159], v[204:207], v[72:75]
	v_mfma_f32_16x16x32_bf16 v[116:119], v[160:163], v[176:179], v[116:119]
	v_mfma_f32_16x16x32_bf16 v[112:115], v[168:171], v[176:179], v[112:115]
	v_mfma_f32_16x16x32_bf16 v[100:103], v[160:163], v[184:187], v[100:103]
	v_mfma_f32_16x16x32_bf16 v[96:99], v[168:171], v[184:187], v[96:99]
	v_mfma_f32_16x16x32_bf16 v[84:87], v[160:163], v[192:195], v[84:87]
	v_mfma_f32_16x16x32_bf16 v[80:83], v[168:171], v[192:195], v[80:83]
	v_mfma_f32_16x16x32_bf16 v[68:71], v[160:163], v[200:203], v[68:71]
	v_mfma_f32_16x16x32_bf16 v[64:67], v[168:171], v[200:203], v[64:67]
	v_mfma_f32_16x16x32_bf16 v[116:119], v[164:167], v[180:183], v[116:119]
	v_mfma_f32_16x16x32_bf16 v[112:115], v[172:175], v[180:183], v[112:115]
	v_mfma_f32_16x16x32_bf16 v[100:103], v[164:167], v[188:191], v[100:103]
	v_mfma_f32_16x16x32_bf16 v[96:99], v[172:175], v[188:191], v[96:99]
	v_mfma_f32_16x16x32_bf16 v[84:87], v[164:167], v[196:199], v[84:87]
	v_mfma_f32_16x16x32_bf16 v[80:83], v[172:175], v[196:199], v[80:83]
	v_mfma_f32_16x16x32_bf16 v[68:71], v[164:167], v[204:207], v[68:71]
	v_mfma_f32_16x16x32_bf16 v[64:67], v[172:175], v[204:207], v[64:67]
	s_barrier
	s_setprio 0
	s_add_i32 s18, s45, s30
	s_mov_b32 m0, s18
	ds_read_b128 v[176:179], v143 offset:16384
	ds_read_b128 v[180:183], v143 offset:17408
	ds_read_b128 v[184:187], v143 offset:18432
	ds_read_b128 v[188:191], v143 offset:19456
	ds_read_b128 v[192:195], v143 offset:20480
	ds_read_b128 v[196:199], v143 offset:21504
	ds_read_b128 v[200:203], v143 offset:22528

; #define PG8_WAIT_V(n) asm volatile("s_waitcnt vmcnt(" #n ")" ::: "memory")
; #define PG8_WAIT_L(n) asm volatile("s_waitcnt lgkmcnt(" #n ")" ::: "memory")
; #define PG8_BAR __builtin_amdgcn_s_barrier()
; #define PG8_SCHED __builtin_amdgcn_sched_barrier(0)
;     ...
;             if constexpr (!HALFU) PG8_LDA(At, 0, 1); PG8_STAGE(PG8_SB(0, 0), b2, voffB); PG8_STAGE(PG8_SB(0, 1), b2 + hstep, voffB); PG8_STAGE(PG8_SA(0, 0), a2, voffA);
;             PG8_WAIT_V(8); PG8_WAIT_L(0); PG8_BAR; if constexpr (!HALFU) { PG8_MMA(1, 0, At, B0); PG8_MMA(1, 1, At, B1); } PG8_BAR; PG8_SCHED;
;             PG8_LDB(B0, 1, 0); PG8_LDB(B1, 1, 1); PG8_SCHED; PG8_LDA(At, 1, 0); PG8_STAGE(PG8_SA(0, 1), a2 + hstepA, voffA);
	global_load_lds_dwordx4 v128, s[24:25]
	s_add_i32 m0, s18, 0x2000
	s_add_u32 s18, s24, 0x100000
	s_addc_u32 s19, s25, 0
	s_add_i32 s54, s46, s30
	global_load_lds_dwordx4 v130, s[24:25]
	s_mov_b32 m0, s54
	ds_read_b128 v[204:207], v143 offset:23552
	global_load_lds_dwordx4 v128, s[18:19]
	s_add_i32 m0, s54, 0x2000
	s_nop 0
	global_load_lds_dwordx4 v130, s[18:19]
	s_waitcnt vmcnt(4)
	s_waitcnt lgkmcnt(0)
	s_setprio 1
	s_barrier
	v_mfma_f32_16x16x32_bf16 v[60:63], v[144:147], v[176:179], v[60:63]
	v_mfma_f32_16x16x32_bf16 v[56:59], v[152:155], v[176:179], v[56:59]
	v_mfma_f32_16x16x32_bf16 v[44:47], v[144:147], v[184:187], v[44:47]
	v_mfma_f32_16x16x32_bf16 v[40:43], v[152:155], v[184:187], v[40:43]
	v_mfma_f32_16x16x32_bf16 v[28:31], v[144:147], v[192:195], v[28:31]
	v_mfma_f32_16x16x32_bf16 v[24:27], v[152:155], v[192:195], v[24:27]
	v_mfma_f32_16x16x32_bf16 v[12:15], v[144:147], v[200:203], v[12:15]
	v_mfma_f32_16x16x32_bf16 v[8:11], v[152:155], v[200:203], v[8:11]
	v_mfma_f32_16x16x32_bf16 v[60:63], v[148:151], v[180:183], v[60:63]
	v_mfma_f32_16x16x32_bf16 v[56:59], v[156:159], v[180:183], v[56:59]
	v_mfma_f32_16x16x32_bf16 v[44:47], v[148:151], v[188:191], v[44:47]
	v_mfma_f32_16x16x32_bf16 v[40:43], v[156:159], v[188:191], v[40:43]
	v_mfma_f32_16x16x32_bf16 v[28:31], v[148:151], v[196:199], v[28:31]
	v_mfma_f32_16x16x32_bf16 v[24:27], v[156:159], v[196:199], v[24:27]
	v_mfma_f32_16x16x32_bf16 v[12:15], v[148:151], v[204:207], v[12:15]
	v_mfma_f32_16x16x32_bf16 v[8:11], v[156:159], v[204:207], v[8:11]
	v_mfma_f32_16x16x32_bf16 v[52:55], v[160:163], v[176:179], v[52:55]
	v_mfma_f32_16x16x32_bf16 v[48:51], v[168:171], v[176:179], v[48:51]
	v_mfma_f32_16x16x32_bf16 v[36:39], v[160:163], v[184:187], v[36:39]
	v_mfma_f32_16x16x32_bf16 v[32:35], v[168:171], v[184:187], v[32:35]
	v_mfma_f32_16x16x32_bf16 v[20:23], v[160:163], v[192:195], v[20:23]
	v_mfma_f32_16x16x32_bf16 v[16:19], v[168:171], v[192:195], v[16:19]
	v_mfma_f32_16x16x32_bf16 v[4:7], v[160:163], v[200:203], v[4:7]
	v_mfma_f32_16x16x32_bf16 v[0:3], v[168:171], v[200:203], v[0:3]
	v_mfma_f32_16x16x32_bf16 v[52:55], v[164:167], v[180:183], v[52:55]
	v_mfma_f32_16x16x32_bf16 v[48:51], v[172:175], v[180:183], v[48:51]
	v_mfma_f32_16x16x32_bf16 v[36:39], v[164:167], v[188:191], v[36:39]
	v_mfma_f32_16x16x32_bf16 v[32:35], v[172:175], v[188:191], v[32:35]
	v_mfma_f32_16x16x32_bf16 v[20:23], v[164:167], v[196:199], v[20:23]
	v_mfma_f32_16x16x32_bf16 v[16:19], v[172:175], v[196:199], v[16:19]
	v_mfma_f32_16x16x32_bf16 v[4:7], v[164:167], v[204:207], v[4:7]
	v_mfma_f32_16x16x32_bf16 v[0:3], v[172:175], v[204:207], v[0:3]
	s_barrier
	s_setprio 0
	s_mov_b32 m0, s17
	ds_read_b128 v[176:179], v143 offset:32768
	global_load_lds_dwordx4 v134, s[26:27]
	s_mov_b32 m0, s36
	ds_read_b128 v[180:183], v143 offset:33792
	global_load_lds_dwordx4 v132, s[26:27]
	s_add_i32 s54, 0, 0x18000
	s_add_i32 s55, 0, 0x1c000
	v_add_u32_e32 v156, s54, v140
	v_add_u32_e32 v172, s55, v140
	ds_read_b128 v[144:147], v156
	ds_read_b128 v[148:151], v156 offset:1024
	ds_read_b128 v[152:155], v156 offset:2048
	ds_read_b128 v[156:159], v156 offset:3072
	ds_read_b128 v[160:163], v172
	ds_read_b128 v[164:167], v172 offset:1024
	ds_read_b128 v[168:171], v172 offset:2048
	ds_read_b128 v[172:175], v172 offset:3072
	s_add_u32 s18, s26, 0x100000
	s_addc_u32 s19, s27, 0
	s_mov_b32 m0, s37


; #define PG8_SCHED __builtin_amdgcn_sched_barrier(0)
;     ...
;             PG8_LDB(B0, 1, 0); PG8_LDB(B1, 1, 1); PG8_SCHED; PG8_LDA(At, 1, 0); PG8_STAGE(PG8_SA(0, 1), a2 + hstepA, voffA);
	ds_read_b128 v[184:187], v143 offset:34816
	ds_read_b128 v[188:191], v143 offset:35840
	ds_read_b128 v[192:195], v143 offset:36864
	ds_read_b128 v[196:199], v143 offset:37888
	ds_read_b128 v[200:203], v143 offset:38912

; #define PG8_WAIT_V(n) asm volatile("s_waitcnt vmcnt(" #n ")" ::: "memory")
; #define PG8_WAIT_L(n) asm volatile("s_waitcnt lgkmcnt(" #n ")" ::: "memory")
; #define PG8_BAR __builtin_amdgcn_s_barrier()
; #define PG8_SCHED __builtin_amdgcn_sched_barrier(0)
;     ...
;             PG8_LDB(B0, 1, 0); PG8_LDB(B1, 1, 1); PG8_SCHED; PG8_LDA(At, 1, 0); PG8_STAGE(PG8_SA(0, 1), a2 + hstepA, voffA);
;             PG8_WAIT_V(8); PG8_WAIT_L(0); PG8_BAR; PG8_MMA(0, 0, At, B0); PG8_MMA(0, 1, At, B1); PG8_BAR; PG8_SCHED;
;             if constexpr (!HALFU) PG8_LDA(At, 1, 1); PG8_STAGE(PG8_SB(1, 0), b3, voffB); PG8_STAGE(PG8_SB(1, 1), b3 + hstep, voffB); PG8_STAGE(PG8_SA(1, 0), a3, voffA);
	global_load_lds_dwordx4 v134, s[18:19]
	s_mov_b32 m0, s38
	ds_read_b128 v[204:207], v143 offset:39936
	global_load_lds_dwordx4 v132, s[18:19]
	s_waitcnt vmcnt(8)
	s_waitcnt lgkmcnt(0)
	s_setprio 1
	s_barrier
	v_mfma_f32_16x16x32_bf16 v[124:127], v[144:147], v[176:179], v[124:127]
	v_mfma_f32_16x16x32_bf16 v[120:123], v[152:155], v[176:179], v[120:123]
	v_mfma_f32_16x16x32_bf16 v[108:111], v[144:147], v[184:187], v[108:111]
	v_mfma_f32_16x16x32_bf16 v[104:107], v[152:155], v[184:187], v[104:107]
	v_mfma_f32_16x16x32_bf16 v[92:95], v[144:147], v[192:195], v[92:95]
	v_mfma_f32_16x16x32_bf16 v[88:91], v[152:155], v[192:195], v[88:91]
	v_mfma_f32_16x16x32_bf16 v[76:79], v[144:147], v[200:203], v[76:79]
	v_mfma_f32_16x16x32_bf16 v[72:75], v[152:155], v[200:203], v[72:75]
	v_mfma_f32_16x16x32_bf16 v[124:127], v[148:151], v[180:183], v[124:127]
	v_mfma_f32_16x16x32_bf16 v[120:123], v[156:159], v[180:183], v[120:123]
	v_mfma_f32_16x16x32_bf16 v[108:111], v[148:151], v[188:191], v[108:111]
	v_mfma_f32_16x16x32_bf16 v[104:107], v[156:159], v[188:191], v[104:107]
	v_mfma_f32_16x16x32_bf16 v[92:95], v[148:151], v[196:199], v[92:95]
	v_mfma_f32_16x16x32_bf16 v[88:91], v[156:159], v[196:199], v[88:91]
	v_mfma_f32_16x16x32_bf16 v[76:79], v[148:151], v[204:207], v[76:79]
	v_mfma_f32_16x16x32_bf16 v[72:75], v[156:159], v[204:207], v[72:75]
	v_mfma_f32_16x16x32_bf16 v[116:119], v[160:163], v[176:179], v[116:119]
	v_mfma_f32_16x16x32_bf16 v[112:115], v[168:171], v[176:179], v[112:115]
	v_mfma_f32_16x16x32_bf16 v[100:103], v[160:163], v[184:187], v[100:103]
	v_mfma_f32_16x16x32_bf16 v[96:99], v[168:171], v[184:187], v[96:99]
	v_mfma_f32_16x16x32_bf16 v[84:87], v[160:163], v[192:195], v[84:87]
	v_mfma_f32_16x16x32_bf16 v[80:83], v[168:171], v[192:195], v[80:83]
	v_mfma_f32_16x16x32_bf16 v[68:71], v[160:163], v[200:203], v[68:71]
	v_mfma_f32_16x16x32_bf16 v[64:67], v[168:171], v[200:203], v[64:67]
	v_mfma_f32_16x16x32_bf16 v[116:119], v[164:167], v[180:183], v[116:119]
	v_mfma_f32_16x16x32_bf16 v[112:115], v[172:175], v[180:183], v[112:115]
	v_mfma_f32_16x16x32_bf16 v[100:103], v[164:167], v[188:191], v[100:103]
	v_mfma_f32_16x16x32_bf16 v[96:99], v[172:175], v[188:191], v[96:99]
	v_mfma_f32_16x16x32_bf16 v[84:87], v[164:167], v[196:199], v[84:87]
	v_mfma_f32_16x16x32_bf16 v[80:83], v[172:175], v[196:199], v[80:83]
	v_mfma_f32_16x16x32_bf16 v[68:71], v[164:167], v[204:207], v[68:71]
	v_mfma_f32_16x16x32_bf16 v[64:67], v[172:175], v[204:207], v[64:67]
	s_barrier
	s_setprio 0
	s_add_u32 s18, s24, 0x80
	s_addc_u32 s19, s25, 0
	s_add_i32 s26, s54, s30
	s_mov_b32 m0, s26
	ds_read_b128 v[176:179], v143 offset:49152
	ds_read_b128 v[180:183], v143 offset:50176
	ds_read_b128 v[184:187], v143 offset:51200
	ds_read_b128 v[188:191], v143 offset:52224
	ds_read_b128 v[192:195], v143 offset:53248
	ds_read_b128 v[196:199], v143 offset:54272
	ds_read_b128 v[200:203], v143 offset:55296

; #define PG8_WAIT_V(n) asm volatile("s_waitcnt vmcnt(" #n ")" ::: "memory")
; #define PG8_WAIT_L(n) asm volatile("s_waitcnt lgkmcnt(" #n ")" ::: "memory")
; #define PG8_BAR __builtin_amdgcn_s_barrier()
; #define PG8_SCHED __builtin_amdgcn_sched_barrier(0)
;     ...
;             if constexpr (!HALFU) PG8_LDA(At, 1, 1); PG8_STAGE(PG8_SB(1, 0), b3, voffB); PG8_STAGE(PG8_SB(1, 1), b3 + hstep, voffB); PG8_STAGE(PG8_SA(1, 0), a3, voffA);
;             PG8_WAIT_V(8); PG8_WAIT_L(0); PG8_BAR; if constexpr (!HALFU) { PG8_MMA(1, 0, At, B0); PG8_MMA(1, 1, At, B1); } PG8_BAR; PG8_SCHED;
;     ...
;         if constexpr (ALIGN_EPI) { if (wr == 0) PG8_BAR; }
	global_load_lds_dwordx4 v128, s[18:19]
	s_add_i32 m0, s26, 0x2000
	v_lshl_add_u64 v[208:209], s[18:19], 0, v[130:131]
	s_add_u32 s18, s24, 0x100080
	s_addc_u32 s19, s25, 0
	s_add_i32 s24, s55, s30
	global_load_lds_dwordx4 v[208:209], off
	s_mov_b32 m0, s24
	ds_read_b128 v[204:207], v143 offset:56320
	global_load_lds_dwordx4 v128, s[18:19]
	s_add_i32 m0, s24, 0x2000
	s_nop 0
	global_load_lds_dwordx4 v130, s[18:19]
	s_waitcnt vmcnt(4)
	s_waitcnt lgkmcnt(0)
	s_setprio 1
	s_barrier
	v_mfma_f32_16x16x32_bf16 v[60:63], v[144:147], v[176:179], v[60:63]
	v_mfma_f32_16x16x32_bf16 v[56:59], v[152:155], v[176:179], v[56:59]
	v_mfma_f32_16x16x32_bf16 v[44:47], v[144:147], v[184:187], v[44:47]
	v_mfma_f32_16x16x32_bf16 v[40:43], v[152:155], v[184:187], v[40:43]
	v_mfma_f32_16x16x32_bf16 v[28:31], v[144:147], v[192:195], v[28:31]
	v_mfma_f32_16x16x32_bf16 v[24:27], v[152:155], v[192:195], v[24:27]
	v_mfma_f32_16x16x32_bf16 v[12:15], v[144:147], v[200:203], v[12:15]
	v_mfma_f32_16x16x32_bf16 v[8:11], v[152:155], v[200:203], v[8:11]
	v_mfma_f32_16x16x32_bf16 v[60:63], v[148:151], v[180:183], v[60:63]
	v_mfma_f32_16x16x32_bf16 v[56:59], v[156:159], v[180:183], v[56:59]
	v_mfma_f32_16x16x32_bf16 v[44:47], v[148:151], v[188:191], v[44:47]
	v_mfma_f32_16x16x32_bf16 v[40:43], v[156:159], v[188:191], v[40:43]
	v_mfma_f32_16x16x32_bf16 v[28:31], v[148:151], v[196:199], v[28:31]
	v_mfma_f32_16x16x32_bf16 v[24:27], v[156:159], v[196:199], v[24:27]
	v_mfma_f32_16x16x32_bf16 v[12:15], v[148:151], v[204:207], v[12:15]
	v_mfma_f32_16x16x32_bf16 v[8:11], v[156:159], v[204:207], v[8:11]
	v_mfma_f32_16x16x32_bf16 v[52:55], v[160:163], v[176:179], v[52:55]
	v_mfma_f32_16x16x32_bf16 v[48:51], v[168:171], v[176:179], v[48:51]
	v_mfma_f32_16x16x32_bf16 v[36:39], v[160:163], v[184:187], v[36:39]
	v_mfma_f32_16x16x32_bf16 v[32:35], v[168:171], v[184:187], v[32:35]
	v_mfma_f32_16x16x32_bf16 v[20:23], v[160:163], v[192:195], v[20:23]
	v_mfma_f32_16x16x32_bf16 v[16:19], v[168:171], v[192:195], v[16:19]
	v_mfma_f32_16x16x32_bf16 v[4:7], v[160:163], v[200:203], v[4:7]
	v_mfma_f32_16x16x32_bf16 v[0:3], v[168:171], v[200:203], v[0:3]
	v_mfma_f32_16x16x32_bf16 v[52:55], v[164:167], v[180:183], v[52:55]
	v_mfma_f32_16x16x32_bf16 v[48:51], v[172:175], v[180:183], v[48:51]
	v_mfma_f32_16x16x32_bf16 v[36:39], v[164:167], v[188:191], v[36:39]
	v_mfma_f32_16x16x32_bf16 v[32:35], v[172:175], v[188:191], v[32:35]
	v_mfma_f32_16x16x32_bf16 v[20:23], v[164:167], v[196:199], v[20:23]
	v_mfma_f32_16x16x32_bf16 v[16:19], v[172:175], v[196:199], v[16:19]
	v_mfma_f32_16x16x32_bf16 v[4:7], v[164:167], v[204:207], v[4:7]
	v_mfma_f32_16x16x32_bf16 v[0:3], v[172:175], v[204:207], v[0:3]
	s_barrier
	s_setprio 0
	s_add_i32 s53, s53, 2
	s_add_u32 s51, s51, 0x100
	s_addc_u32 s52, s52, 0
	s_cmp_gt_u32 s53, 61
	s_mov_b64 s[18:19], s[20:21]
	s_cbranch_scc0 .LBB0_670
	s_and_b64 vcc, exec, s[6:7]
	s_cbranch_vccz .LBB0_673
	s_barrier

; #define PG8_SCHED __builtin_amdgcn_sched_barrier(0)
;     ...
;         for (int t = 0; t < nt; t += 2) {
;             const bool last = (t == nt - 2);
;             const char* a1 = cA + (size_t)(t + 1) * kstep;
;             const char* a2 = last ? nA : cA + (size_t)(t + 2) * kstep; const char* b2 = last ? nB : cB + (size_t)(t + 2) * kstep;
;             const char* a3 = a2 + kstep; const char* b3 = b2 + kstep;
;             if (last && has_next) S.a_ready(nxt);
;             if constexpr (SP2) {
;             PG8_LDB(B0, 0, 0); PG8_LDB(B1, 0, 1); PG8_SCHED; PG8_LDA(At, 0, 0); PG8_STAGE(PG8_SA(1, 1), a1 + hstepA, voffA);
.LBB0_793:
	s_add_u32 s98, s10, 0x80
	s_addc_u32 s99, s11, 0
	s_mov_b32 m0, s43
	ds_read_b128 v[140:143], v137
	global_load_lds_dwordx4 v128, s[98:99]
	s_mov_b32 m0, s44
	ds_read_b128 v[144:147], v137 offset:1024
	global_load_lds_dwordx4 v130, s[98:99]


; #define PG8_SCHED __builtin_amdgcn_sched_barrier(0)
;     ...
;             const bool last = (t == nt - 2);
;             const char* a1 = cA + (size_t)(t + 1) * kstep;
;             const char* a2 = last ? nA : cA + (size_t)(t + 2) * kstep; const char* b2 = last ? nB : cB + (size_t)(t + 2) * kstep;
;             const char* a3 = a2 + kstep; const char* b3 = b2 + kstep;
;             if (last && has_next) S.a_ready(nxt);
;             if constexpr (SP2) {
;             PG8_LDB(B0, 0, 0); PG8_LDB(B1, 0, 1); PG8_SCHED; PG8_LDA(At, 0, 0); PG8_STAGE(PG8_SA(1, 1), a1 + hstepA, voffA);
	ds_read_b128 v[148:151], v137 offset:2048
	ds_read_b128 v[152:155], v137 offset:3072
	ds_read_b128 v[156:159], v138
	ds_read_b128 v[160:163], v138 offset:1024
	ds_read_b128 v[164:167], v138 offset:2048
	ds_read_b128 v[168:171], v138 offset:3072
	s_add_u32 s22, s10, 0x100
	s_addc_u32 s23, s11, 0
	s_cmpk_eq_i32 s54, 0xa8
	s_cselect_b32 s28, s6, s22
	s_cselect_b32 s29, s7, s23
	s_cselect_b32 s26, s20, s52
	s_cselect_b32 s27, s21, s53
	s_add_u32 s24, s28, 0x80
	s_addc_u32 s25, s29, 0
	s_add_u32 s10, s10, 0x2b0080
	s_addc_u32 s11, s11, 0
	s_add_i32 m0, s36, 0xc000
	ds_read_b128 v[172:175], v139
	ds_read_b128 v[176:179], v139 offset:1024
	ds_read_b128 v[180:183], v139 offset:2048
	ds_read_b128 v[184:187], v139 offset:3072
	ds_read_b128 v[188:191], v139 offset:4096
	ds_read_b128 v[192:195], v139 offset:5120
	ds_read_b128 v[196:199], v139 offset:6144

; #define PG8_WAIT_V(n) asm volatile("s_waitcnt vmcnt(" #n ")" ::: "memory")
; #define PG8_WAIT_L(n) asm volatile("s_waitcnt lgkmcnt(" #n ")" ::: "memory")
; #define PG8_BAR __builtin_amdgcn_s_barrier()
; #define PG8_SCHED __builtin_amdgcn_sched_barrier(0)
;     ...
;             PG8_LDB(B0, 0, 0); PG8_LDB(B1, 0, 1); PG8_SCHED; PG8_LDA(At, 0, 0); PG8_STAGE(PG8_SA(1, 1), a1 + hstepA, voffA);
;             PG8_WAIT_V(8); PG8_WAIT_L(0); PG8_BAR; PG8_MMA(0, 0, At, B0); PG8_MMA(0, 1, At, B1); PG8_BAR; PG8_SCHED;
;             if constexpr (!HALFU) PG8_LDA(At, 0, 1); PG8_STAGE(PG8_SB(0, 0), b2, voffB); PG8_STAGE(PG8_SB(0, 1), b2 + hstep, voffB); PG8_STAGE(PG8_SA(0, 0), a2, voffA);
	global_load_lds_dwordx4 v128, s[10:11]
	s_add_i32 m0, s36, 0xe000
	ds_read_b128 v[200:203], v139 offset:7168
	global_load_lds_dwordx4 v130, s[10:11]
	s_waitcnt vmcnt(8)
	s_waitcnt lgkmcnt(0)
	s_setprio 1
	s_barrier
	v_mfma_f32_16x16x32_bf16 v[124:127], v[140:143], v[172:175], v[124:127]
	v_mfma_f32_16x16x32_bf16 v[120:123], v[148:151], v[172:175], v[120:123]
	v_mfma_f32_16x16x32_bf16 v[112:115], v[140:143], v[180:183], v[112:115]
	v_mfma_f32_16x16x32_bf16 v[104:107], v[148:151], v[180:183], v[104:107]
	v_mfma_f32_16x16x32_bf16 v[96:99], v[140:143], v[188:191], v[96:99]
	v_mfma_f32_16x16x32_bf16 v[88:91], v[148:151], v[188:191], v[88:91]
	v_mfma_f32_16x16x32_bf16 v[80:83], v[140:143], v[196:199], v[80:83]
	v_mfma_f32_16x16x32_bf16 v[72:75], v[148:151], v[196:199], v[72:75]
	v_mfma_f32_16x16x32_bf16 v[124:127], v[144:147], v[176:179], v[124:127]
	v_mfma_f32_16x16x32_bf16 v[120:123], v[152:155], v[176:179], v[120:123]
	v_mfma_f32_16x16x32_bf16 v[112:115], v[144:147], v[184:187], v[112:115]
	v_mfma_f32_16x16x32_bf16 v[104:107], v[152:155], v[184:187], v[104:107]
	v_mfma_f32_16x16x32_bf16 v[96:99], v[144:147], v[192:195], v[96:99]
	v_mfma_f32_16x16x32_bf16 v[88:91], v[152:155], v[192:195], v[88:91]
	v_mfma_f32_16x16x32_bf16 v[80:83], v[144:147], v[200:203], v[80:83]
	v_mfma_f32_16x16x32_bf16 v[72:75], v[152:155], v[200:203], v[72:75]
	v_mfma_f32_16x16x32_bf16 v[116:119], v[156:159], v[172:175], v[116:119]
	v_mfma_f32_16x16x32_bf16 v[108:111], v[164:167], v[172:175], v[108:111]
	v_mfma_f32_16x16x32_bf16 v[100:103], v[156:159], v[180:183], v[100:103]
	v_mfma_f32_16x16x32_bf16 v[92:95], v[164:167], v[180:183], v[92:95]
	v_mfma_f32_16x16x32_bf16 v[84:87], v[156:159], v[188:191], v[84:87]
	v_mfma_f32_16x16x32_bf16 v[76:79], v[164:167], v[188:191], v[76:79]
	v_mfma_f32_16x16x32_bf16 v[68:71], v[156:159], v[196:199], v[68:71]
	v_mfma_f32_16x16x32_bf16 v[64:67], v[164:167], v[196:199], v[64:67]
	v_mfma_f32_16x16x32_bf16 v[116:119], v[160:163], v[176:179], v[116:119]
	v_mfma_f32_16x16x32_bf16 v[108:111], v[168:171], v[176:179], v[108:111]
	v_mfma_f32_16x16x32_bf16 v[100:103], v[160:163], v[184:187], v[100:103]
	v_mfma_f32_16x16x32_bf16 v[92:95], v[168:171], v[184:187], v[92:95]
	v_mfma_f32_16x16x32_bf16 v[84:87], v[160:163], v[192:195], v[84:87]
	v_mfma_f32_16x16x32_bf16 v[76:79], v[168:171], v[192:195], v[76:79]
	v_mfma_f32_16x16x32_bf16 v[68:71], v[160:163], v[200:203], v[68:71]
	v_mfma_f32_16x16x32_bf16 v[64:67], v[168:171], v[200:203], v[64:67]
	s_barrier
	s_setprio 0
	s_add_i32 s10, s46, s31
	s_mov_b32 m0, s10
	ds_read_b128 v[172:175], v139 offset:16384
	ds_read_b128 v[176:179], v139 offset:17408
	ds_read_b128 v[180:183], v139 offset:18432
	ds_read_b128 v[184:187], v139 offset:19456
	ds_read_b128 v[188:191], v139 offset:20480
	ds_read_b128 v[192:195], v139 offset:21504
	ds_read_b128 v[196:199], v139 offset:22528

; #define PG8_WAIT_V(n) asm volatile("s_waitcnt vmcnt(" #n ")" ::: "memory")
; #define PG8_WAIT_L(n) asm volatile("s_waitcnt lgkmcnt(" #n ")" ::: "memory")
; #define PG8_BAR __builtin_amdgcn_s_barrier()
; #define PG8_SCHED __builtin_amdgcn_sched_barrier(0)
;     ...
;             if constexpr (!HALFU) PG8_LDA(At, 0, 1); PG8_STAGE(PG8_SB(0, 0), b2, voffB); PG8_STAGE(PG8_SB(0, 1), b2 + hstep, voffB); PG8_STAGE(PG8_SA(0, 0), a2, voffA);
;             PG8_WAIT_V(8); PG8_WAIT_L(0); PG8_BAR; if constexpr (!HALFU) { PG8_MMA(1, 0, At, B0); PG8_MMA(1, 1, At, B1); } PG8_BAR; PG8_SCHED;
;             PG8_LDB(B0, 1, 0); PG8_LDB(B1, 1, 1); PG8_SCHED; PG8_LDA(At, 1, 0); PG8_STAGE(PG8_SA(0, 1), a2 + hstepA, voffA);
	global_load_lds_dwordx4 v128, s[26:27]
	s_add_i32 m0, s10, 0x2000
	s_add_u32 s10, s26, 0x2b0000
	s_addc_u32 s11, s27, 0
	s_add_i32 s55, s47, s31
	global_load_lds_dwordx4 v130, s[26:27]
	s_mov_b32 m0, s55
	ds_read_b128 v[200:203], v139 offset:23552
	global_load_lds_dwordx4 v128, s[10:11]
	s_add_i32 m0, s55, 0x2000
	s_nop 0
	global_load_lds_dwordx4 v130, s[10:11]
	s_waitcnt vmcnt(4)
	s_waitcnt lgkmcnt(0)
	s_setprio 1
	s_barrier
	v_mfma_f32_16x16x32_bf16 v[60:63], v[140:143], v[172:175], v[60:63]
	v_mfma_f32_16x16x32_bf16 v[56:59], v[148:151], v[172:175], v[56:59]
	v_mfma_f32_16x16x32_bf16 v[48:51], v[140:143], v[180:183], v[48:51]
	v_mfma_f32_16x16x32_bf16 v[40:43], v[148:151], v[180:183], v[40:43]
	v_mfma_f32_16x16x32_bf16 v[32:35], v[140:143], v[188:191], v[32:35]
	v_mfma_f32_16x16x32_bf16 v[24:27], v[148:151], v[188:191], v[24:27]
	v_mfma_f32_16x16x32_bf16 v[16:19], v[140:143], v[196:199], v[16:19]
	v_mfma_f32_16x16x32_bf16 v[8:11], v[148:151], v[196:199], v[8:11]
	v_mfma_f32_16x16x32_bf16 v[60:63], v[144:147], v[176:179], v[60:63]
	v_mfma_f32_16x16x32_bf16 v[56:59], v[152:155], v[176:179], v[56:59]
	v_mfma_f32_16x16x32_bf16 v[48:51], v[144:147], v[184:187], v[48:51]
	v_mfma_f32_16x16x32_bf16 v[40:43], v[152:155], v[184:187], v[40:43]
	v_mfma_f32_16x16x32_bf16 v[32:35], v[144:147], v[192:195], v[32:35]
	v_mfma_f32_16x16x32_bf16 v[24:27], v[152:155], v[192:195], v[24:27]
	v_mfma_f32_16x16x32_bf16 v[16:19], v[144:147], v[200:203], v[16:19]
	v_mfma_f32_16x16x32_bf16 v[8:11], v[152:155], v[200:203], v[8:11]
	v_mfma_f32_16x16x32_bf16 v[52:55], v[156:159], v[172:175], v[52:55]
	v_mfma_f32_16x16x32_bf16 v[44:47], v[164:167], v[172:175], v[44:47]
	v_mfma_f32_16x16x32_bf16 v[36:39], v[156:159], v[180:183], v[36:39]
	v_mfma_f32_16x16x32_bf16 v[28:31], v[164:167], v[180:183], v[28:31]
	v_mfma_f32_16x16x32_bf16 v[20:23], v[156:159], v[188:191], v[20:23]
	v_mfma_f32_16x16x32_bf16 v[12:15], v[164:167], v[188:191], v[12:15]
	v_mfma_f32_16x16x32_bf16 v[4:7], v[156:159], v[196:199], v[4:7]
	v_mfma_f32_16x16x32_bf16 v[0:3], v[164:167], v[196:199], v[0:3]
	v_mfma_f32_16x16x32_bf16 v[52:55], v[160:163], v[176:179], v[52:55]
	v_mfma_f32_16x16x32_bf16 v[44:47], v[168:171], v[176:179], v[44:47]
	v_mfma_f32_16x16x32_bf16 v[36:39], v[160:163], v[184:187], v[36:39]
	v_mfma_f32_16x16x32_bf16 v[28:31], v[168:171], v[184:187], v[28:31]
	v_mfma_f32_16x16x32_bf16 v[20:23], v[160:163], v[192:195], v[20:23]
	v_mfma_f32_16x16x32_bf16 v[12:15], v[168:171], v[192:195], v[12:15]
	v_mfma_f32_16x16x32_bf16 v[4:7], v[160:163], v[200:203], v[4:7]
	v_mfma_f32_16x16x32_bf16 v[0:3], v[168:171], v[200:203], v[0:3]
	s_barrier
	s_setprio 0
	s_mov_b32 m0, s36
	ds_read_b128 v[172:175], v139 offset:32768
	global_load_lds_dwordx4 v128, s[28:29]
	s_mov_b32 m0, s37
	ds_read_b128 v[176:179], v139 offset:33792
	global_load_lds_dwordx4 v130, s[28:29]
	s_add_i32 s55, 0, 0x18000
	s_add_i32 s56, 0, 0x1c000
	v_add_u32_e32 v152, s55, v136
	v_add_u32_e32 v168, s56, v136
	ds_read_b128 v[140:143], v152
	ds_read_b128 v[144:147], v152 offset:1024
	ds_read_b128 v[148:151], v152 offset:2048
	ds_read_b128 v[152:155], v152 offset:3072
	ds_read_b128 v[156:159], v168
	ds_read_b128 v[160:163], v168 offset:1024
	ds_read_b128 v[164:167], v168 offset:2048
	ds_read_b128 v[168:171], v168 offset:3072
	s_add_u32 s10, s28, 0x2b0000
	s_addc_u32 s11, s29, 0
	s_mov_b32 m0, s38


; #define PG8_SCHED __builtin_amdgcn_sched_barrier(0)
;     ...
;             PG8_LDB(B0, 1, 0); PG8_LDB(B1, 1, 1); PG8_SCHED; PG8_LDA(At, 1, 0); PG8_STAGE(PG8_SA(0, 1), a2 + hstepA, voffA);
	ds_read_b128 v[180:183], v139 offset:34816
	ds_read_b128 v[184:187], v139 offset:35840
	ds_read_b128 v[188:191], v139 offset:36864
	ds_read_b128 v[192:195], v139 offset:37888
	ds_read_b128 v[196:199], v139 offset:38912

; #define PG8_WAIT_V(n) asm volatile("s_waitcnt vmcnt(" #n ")" ::: "memory")
; #define PG8_WAIT_L(n) asm volatile("s_waitcnt lgkmcnt(" #n ")" ::: "memory")
; #define PG8_BAR __builtin_amdgcn_s_barrier()
; #define PG8_SCHED __builtin_amdgcn_sched_barrier(0)
;     ...
;             PG8_LDB(B0, 1, 0); PG8_LDB(B1, 1, 1); PG8_SCHED; PG8_LDA(At, 1, 0); PG8_STAGE(PG8_SA(0, 1), a2 + hstepA, voffA);
;             PG8_WAIT_V(8); PG8_WAIT_L(0); PG8_BAR; PG8_MMA(0, 0, At, B0); PG8_MMA(0, 1, At, B1); PG8_BAR; PG8_SCHED;
;             if constexpr (!HALFU) PG8_LDA(At, 1, 1); PG8_STAGE(PG8_SB(1, 0), b3, voffB); PG8_STAGE(PG8_SB(1, 1), b3 + hstep, voffB); PG8_STAGE(PG8_SA(1, 0), a3, voffA);
	global_load_lds_dwordx4 v128, s[10:11]
	s_mov_b32 m0, s39
	ds_read_b128 v[200:203], v139 offset:39936
	global_load_lds_dwordx4 v130, s[10:11]
	s_waitcnt vmcnt(8)
	s_waitcnt lgkmcnt(0)
	s_setprio 1
	s_barrier
	v_mfma_f32_16x16x32_bf16 v[124:127], v[140:143], v[172:175], v[124:127]
	v_mfma_f32_16x16x32_bf16 v[120:123], v[148:151], v[172:175], v[120:123]
	v_mfma_f32_16x16x32_bf16 v[112:115], v[140:143], v[180:183], v[112:115]
	v_mfma_f32_16x16x32_bf16 v[104:107], v[148:151], v[180:183], v[104:107]
	v_mfma_f32_16x16x32_bf16 v[96:99], v[140:143], v[188:191], v[96:99]
	v_mfma_f32_16x16x32_bf16 v[88:91], v[148:151], v[188:191], v[88:91]
	v_mfma_f32_16x16x32_bf16 v[80:83], v[140:143], v[196:199], v[80:83]
	v_mfma_f32_16x16x32_bf16 v[72:75], v[148:151], v[196:199], v[72:75]
	v_mfma_f32_16x16x32_bf16 v[124:127], v[144:147], v[176:179], v[124:127]
	v_mfma_f32_16x16x32_bf16 v[120:123], v[152:155], v[176:179], v[120:123]
	v_mfma_f32_16x16x32_bf16 v[112:115], v[144:147], v[184:187], v[112:115]
	v_mfma_f32_16x16x32_bf16 v[104:107], v[152:155], v[184:187], v[104:107]
	v_mfma_f32_16x16x32_bf16 v[96:99], v[144:147], v[192:195], v[96:99]
	v_mfma_f32_16x16x32_bf16 v[88:91], v[152:155], v[192:195], v[88:91]
	v_mfma_f32_16x16x32_bf16 v[80:83], v[144:147], v[200:203], v[80:83]
	v_mfma_f32_16x16x32_bf16 v[72:75], v[152:155], v[200:203], v[72:75]
	v_mfma_f32_16x16x32_bf16 v[116:119], v[156:159], v[172:175], v[116:119]
	v_mfma_f32_16x16x32_bf16 v[108:111], v[164:167], v[172:175], v[108:111]
	v_mfma_f32_16x16x32_bf16 v[100:103], v[156:159], v[180:183], v[100:103]
	v_mfma_f32_16x16x32_bf16 v[92:95], v[164:167], v[180:183], v[92:95]
	v_mfma_f32_16x16x32_bf16 v[84:87], v[156:159], v[188:191], v[84:87]
	v_mfma_f32_16x16x32_bf16 v[76:79], v[164:167], v[188:191], v[76:79]
	v_mfma_f32_16x16x32_bf16 v[68:71], v[156:159], v[196:199], v[68:71]
	v_mfma_f32_16x16x32_bf16 v[64:67], v[164:167], v[196:199], v[64:67]
	v_mfma_f32_16x16x32_bf16 v[116:119], v[160:163], v[176:179], v[116:119]
	v_mfma_f32_16x16x32_bf16 v[108:111], v[168:171], v[176:179], v[108:111]
	v_mfma_f32_16x16x32_bf16 v[100:103], v[160:163], v[184:187], v[100:103]
	v_mfma_f32_16x16x32_bf16 v[92:95], v[168:171], v[184:187], v[92:95]
	v_mfma_f32_16x16x32_bf16 v[84:87], v[160:163], v[192:195], v[84:87]
	v_mfma_f32_16x16x32_bf16 v[76:79], v[168:171], v[192:195], v[76:79]
	v_mfma_f32_16x16x32_bf16 v[68:71], v[160:163], v[200:203], v[68:71]
	v_mfma_f32_16x16x32_bf16 v[64:67], v[168:171], v[200:203], v[64:67]
	s_barrier
	s_setprio 0
	s_add_u32 s10, s26, 0x80
	s_addc_u32 s11, s27, 0
	s_add_i32 s28, s55, s31
	s_mov_b32 m0, s28
	ds_read_b128 v[172:175], v139 offset:49152
	ds_read_b128 v[176:179], v139 offset:50176
	ds_read_b128 v[180:183], v139 offset:51200
	ds_read_b128 v[184:187], v139 offset:52224
	ds_read_b128 v[188:191], v139 offset:53248
	ds_read_b128 v[192:195], v139 offset:54272
	ds_read_b128 v[196:199], v139 offset:55296

; #define PG8_WAIT_V(n) asm volatile("s_waitcnt vmcnt(" #n ")" ::: "memory")
; #define PG8_WAIT_L(n) asm volatile("s_waitcnt lgkmcnt(" #n ")" ::: "memory")
; #define PG8_BAR __builtin_amdgcn_s_barrier()
; #define PG8_SCHED __builtin_amdgcn_sched_barrier(0)
;     ...
;             if constexpr (!HALFU) PG8_LDA(At, 1, 1); PG8_STAGE(PG8_SB(1, 0), b3, voffB); PG8_STAGE(PG8_SB(1, 1), b3 + hstep, voffB); PG8_STAGE(PG8_SA(1, 0), a3, voffA);
;             PG8_WAIT_V(8); PG8_WAIT_L(0); PG8_BAR; if constexpr (!HALFU) { PG8_MMA(1, 0, At, B0); PG8_MMA(1, 1, At, B1); } PG8_BAR; PG8_SCHED;
;     ...
;         if constexpr (ALIGN_EPI) { if (wr == 0) PG8_BAR; }
	global_load_lds_dwordx4 v128, s[10:11]
	s_add_i32 m0, s28, 0x2000
	v_lshl_add_u64 v[204:205], s[10:11], 0, v[130:131]
	s_add_u32 s10, s26, 0x2b0080
	s_addc_u32 s11, s27, 0
	s_add_i32 s26, s56, s31
	global_load_lds_dwordx4 v[204:205], off
	s_mov_b32 m0, s26
	ds_read_b128 v[200:203], v139 offset:56320
	global_load_lds_dwordx4 v128, s[10:11]
	s_add_i32 m0, s26, 0x2000
	s_nop 0
	global_load_lds_dwordx4 v130, s[10:11]
	s_waitcnt vmcnt(4)
	s_waitcnt lgkmcnt(0)
	s_setprio 1
	s_barrier
	v_mfma_f32_16x16x32_bf16 v[60:63], v[140:143], v[172:175], v[60:63]
	v_mfma_f32_16x16x32_bf16 v[56:59], v[148:151], v[172:175], v[56:59]
	v_mfma_f32_16x16x32_bf16 v[48:51], v[140:143], v[180:183], v[48:51]
	v_mfma_f32_16x16x32_bf16 v[40:43], v[148:151], v[180:183], v[40:43]
	v_mfma_f32_16x16x32_bf16 v[32:35], v[140:143], v[188:191], v[32:35]
	v_mfma_f32_16x16x32_bf16 v[24:27], v[148:151], v[188:191], v[24:27]
	v_mfma_f32_16x16x32_bf16 v[16:19], v[140:143], v[196:199], v[16:19]
	v_mfma_f32_16x16x32_bf16 v[8:11], v[148:151], v[196:199], v[8:11]
	v_mfma_f32_16x16x32_bf16 v[60:63], v[144:147], v[176:179], v[60:63]
	v_mfma_f32_16x16x32_bf16 v[56:59], v[152:155], v[176:179], v[56:59]
	v_mfma_f32_16x16x32_bf16 v[48:51], v[144:147], v[184:187], v[48:51]
	v_mfma_f32_16x16x32_bf16 v[40:43], v[152:155], v[184:187], v[40:43]
	v_mfma_f32_16x16x32_bf16 v[32:35], v[144:147], v[192:195], v[32:35]
	v_mfma_f32_16x16x32_bf16 v[24:27], v[152:155], v[192:195], v[24:27]
	v_mfma_f32_16x16x32_bf16 v[16:19], v[144:147], v[200:203], v[16:19]
	v_mfma_f32_16x16x32_bf16 v[8:11], v[152:155], v[200:203], v[8:11]
	v_mfma_f32_16x16x32_bf16 v[52:55], v[156:159], v[172:175], v[52:55]
	v_mfma_f32_16x16x32_bf16 v[44:47], v[164:167], v[172:175], v[44:47]
	v_mfma_f32_16x16x32_bf16 v[36:39], v[156:159], v[180:183], v[36:39]
	v_mfma_f32_16x16x32_bf16 v[28:31], v[164:167], v[180:183], v[28:31]
	v_mfma_f32_16x16x32_bf16 v[20:23], v[156:159], v[188:191], v[20:23]
	v_mfma_f32_16x16x32_bf16 v[12:15], v[164:167], v[188:191], v[12:15]
	v_mfma_f32_16x16x32_bf16 v[4:7], v[156:159], v[196:199], v[4:7]
	v_mfma_f32_16x16x32_bf16 v[0:3], v[164:167], v[196:199], v[0:3]
	v_mfma_f32_16x16x32_bf16 v[52:55], v[160:163], v[176:179], v[52:55]
	v_mfma_f32_16x16x32_bf16 v[44:47], v[168:171], v[176:179], v[44:47]
	v_mfma_f32_16x16x32_bf16 v[36:39], v[160:163], v[184:187], v[36:39]
	v_mfma_f32_16x16x32_bf16 v[28:31], v[168:171], v[184:187], v[28:31]
	v_mfma_f32_16x16x32_bf16 v[20:23], v[160:163], v[192:195], v[20:23]
	v_mfma_f32_16x16x32_bf16 v[12:15], v[168:171], v[192:195], v[12:15]
	v_mfma_f32_16x16x32_bf16 v[4:7], v[160:163], v[200:203], v[4:7]
	v_mfma_f32_16x16x32_bf16 v[0:3], v[168:171], v[200:203], v[0:3]
	s_barrier
	s_setprio 0
	s_add_i32 s54, s54, 2
	s_add_u32 s52, s52, 0x100
	s_addc_u32 s53, s53, 0
	s_cmpk_gt_u32 s54, 0xa9
	s_mov_b64 s[10:11], s[22:23]
	s_cbranch_scc0 .LBB0_793
	s_and_b64 vcc, exec, s[12:13]
	s_cbranch_vccz .LBB0_796
	s_barrier

; #define PG8_SCHED __builtin_amdgcn_sched_barrier(0)
;     ...
;         for (int t = 0; t < nt; t += 2) {
;             const bool last = (t == nt - 2);
;             const char* a1 = cA + (size_t)(t + 1) * kstep;
;             const char* a2 = last ? nA : cA + (size_t)(t + 2) * kstep; const char* b2 = last ? nB : cB + (size_t)(t + 2) * kstep;
;             const char* a3 = a2 + kstep; const char* b3 = b2 + kstep;
;             if (last && has_next) S.a_ready(nxt);
;             if constexpr (SP2) {
;             PG8_LDB(B0, 0, 0); PG8_LDB(B1, 0, 1); PG8_SCHED; PG8_LDA(At, 0, 0); PG8_STAGE(PG8_SA(1, 1), a1 + hstepA, voffA);
.LBB0_1200:
	s_add_u32 s98, s10, 0x80
	s_addc_u32 s99, s11, 0
	s_mov_b32 m0, s68
	ds_read_b128 v[128:131], v149
	global_load_lds_dwordx4 v136, s[98:99]
	s_mov_b32 m0, s69
	ds_read_b128 v[132:135], v149 offset:1024
	global_load_lds_dwordx4 v140, s[98:99]


; #define PG8_SCHED __builtin_amdgcn_sched_barrier(0)
;     ...
;             const bool last = (t == nt - 2);
;             const char* a1 = cA + (size_t)(t + 1) * kstep;
;             const char* a2 = last ? nA : cA + (size_t)(t + 2) * kstep; const char* b2 = last ? nB : cB + (size_t)(t + 2) * kstep;
;             const char* a3 = a2 + kstep; const char* b3 = b2 + kstep;
;             if (last && has_next) S.a_ready(nxt);
;             if constexpr (SP2) {
;             PG8_LDB(B0, 0, 0); PG8_LDB(B1, 0, 1); PG8_SCHED; PG8_LDA(At, 0, 0); PG8_STAGE(PG8_SA(1, 1), a1 + hstepA, voffA);
	ds_read_b128 v[154:157], v149 offset:2048
	ds_read_b128 v[158:161], v149 offset:3072
	ds_read_b128 v[162:165], v150
	ds_read_b128 v[166:169], v150 offset:1024
	ds_read_b128 v[170:173], v150 offset:2048
	ds_read_b128 v[174:177], v150 offset:3072
	s_add_u32 s26, s10, 0x100
	s_addc_u32 s27, s11, 0
	s_cmp_eq_u32 s76, 28
	s_cselect_b32 s50, s9, s26
	s_cselect_b32 s51, s7, s27
	s_cselect_b32 s48, s43, s74
	s_cselect_b32 s49, s41, s75
	s_add_u32 s30, s50, 0x80
	s_addc_u32 s31, s51, 0
	s_add_u32 s10, s10, 0x80080
	s_addc_u32 s11, s11, 0
	s_add_i32 m0, s57, 0xc000
	ds_read_b128 v[178:181], v151
	ds_read_b128 v[182:185], v151 offset:1024
	ds_read_b128 v[186:189], v151 offset:2048
	ds_read_b128 v[190:193], v151 offset:3072
	ds_read_b128 v[194:197], v151 offset:4096
	ds_read_b128 v[198:201], v151 offset:5120
	ds_read_b128 v[202:205], v151 offset:6144

; #define PG8_WAIT_V(n) asm volatile("s_waitcnt vmcnt(" #n ")" ::: "memory")
; #define PG8_WAIT_L(n) asm volatile("s_waitcnt lgkmcnt(" #n ")" ::: "memory")
; #define PG8_BAR __builtin_amdgcn_s_barrier()
; #define PG8_SCHED __builtin_amdgcn_sched_barrier(0)
;     ...
;             PG8_LDB(B0, 0, 0); PG8_LDB(B1, 0, 1); PG8_SCHED; PG8_LDA(At, 0, 0); PG8_STAGE(PG8_SA(1, 1), a1 + hstepA, voffA);
;             PG8_WAIT_V(8); PG8_WAIT_L(0); PG8_BAR; PG8_MMA(0, 0, At, B0); PG8_MMA(0, 1, At, B1); PG8_BAR; PG8_SCHED;
;             if constexpr (!HALFU) PG8_LDA(At, 0, 1); PG8_STAGE(PG8_SB(0, 0), b2, voffB); PG8_STAGE(PG8_SB(0, 1), b2 + hstep, voffB); PG8_STAGE(PG8_SA(0, 0), a2, voffA);
	global_load_lds_dwordx4 v136, s[10:11]
	s_add_i32 m0, s57, 0xe000
	ds_read_b128 v[206:209], v151 offset:7168
	global_load_lds_dwordx4 v140, s[10:11]
	s_waitcnt vmcnt(8)
	s_waitcnt lgkmcnt(0)
	s_setprio 1
	s_barrier
	v_mfma_scale_f32_16x16x128_f8f6f4 v[124:127], v[128:135], v[178:185], v[124:127], v152, v152 op_sel_hi:[0,0,0]
	v_mfma_scale_f32_16x16x128_f8f6f4 v[120:123], v[154:161], v[178:185], v[120:123], v152, v152 op_sel_hi:[0,0,0]
	v_mfma_scale_f32_16x16x128_f8f6f4 v[108:111], v[128:135], v[186:193], v[108:111], v152, v152 op_sel_hi:[0,0,0]
	v_mfma_scale_f32_16x16x128_f8f6f4 v[104:107], v[154:161], v[186:193], v[104:107], v152, v152 op_sel_hi:[0,0,0]
	v_mfma_scale_f32_16x16x128_f8f6f4 v[210:213], v[128:135], v[194:201], v[92:95], v152, v152 op_sel_hi:[0,0,0]
	v_mfma_scale_f32_16x16x128_f8f6f4 v[214:217], v[154:161], v[194:201], v[88:91], v152, v152 op_sel_hi:[0,0,0]
	v_mfma_scale_f32_16x16x128_f8f6f4 v[218:221], v[128:135], v[202:209], v[76:79], v152, v152 op_sel_hi:[0,0,0]
	v_mfma_scale_f32_16x16x128_f8f6f4 v[222:225], v[154:161], v[202:209], v[72:75], v152, v152 op_sel_hi:[0,0,0]
	v_mfma_scale_f32_16x16x128_f8f6f4 v[116:119], v[162:169], v[178:185], v[116:119], v152, v152 op_sel_hi:[0,0,0]
	v_mfma_scale_f32_16x16x128_f8f6f4 v[112:115], v[170:177], v[178:185], v[112:115], v152, v152 op_sel_hi:[0,0,0]
	v_mfma_scale_f32_16x16x128_f8f6f4 v[100:103], v[162:169], v[186:193], v[100:103], v152, v152 op_sel_hi:[0,0,0]
	v_mfma_scale_f32_16x16x128_f8f6f4 v[96:99], v[170:177], v[186:193], v[96:99], v152, v152 op_sel_hi:[0,0,0]
	v_mfma_scale_f32_16x16x128_f8f6f4 v[178:181], v[162:169], v[194:201], v[84:87], v152, v152 op_sel_hi:[0,0,0]
	v_mfma_scale_f32_16x16x128_f8f6f4 v[182:185], v[170:177], v[194:201], v[80:83], v152, v152 op_sel_hi:[0,0,0]
	v_mfma_scale_f32_16x16x128_f8f6f4 v[186:189], v[162:169], v[202:209], v[68:71], v152, v152 op_sel_hi:[0,0,0]
	v_mfma_scale_f32_16x16x128_f8f6f4 v[190:193], v[170:177], v[202:209], v[64:67], v152, v152 op_sel_hi:[0,0,0]
	s_barrier
	s_setprio 0
	s_add_i32 s10, s71, s56
	s_mov_b32 m0, s10
	s_nop 1
	ds_read_b128 v[64:67], v151 offset:16384
	ds_read_b128 v[68:71], v151 offset:17408
	ds_read_b128 v[72:75], v151 offset:18432
	ds_read_b128 v[76:79], v151 offset:19456
	ds_read_b128 v[80:83], v151 offset:20480
	ds_read_b128 v[84:87], v151 offset:21504
	ds_read_b128 v[88:91], v151 offset:22528

; #define PG8_WAIT_V(n) asm volatile("s_waitcnt vmcnt(" #n ")" ::: "memory")
; #define PG8_WAIT_L(n) asm volatile("s_waitcnt lgkmcnt(" #n ")" ::: "memory")
; #define PG8_BAR __builtin_amdgcn_s_barrier()
; #define PG8_SCHED __builtin_amdgcn_sched_barrier(0)
;     ...
;             if constexpr (!HALFU) PG8_LDA(At, 0, 1); PG8_STAGE(PG8_SB(0, 0), b2, voffB); PG8_STAGE(PG8_SB(0, 1), b2 + hstep, voffB); PG8_STAGE(PG8_SA(0, 0), a2, voffA);
;             PG8_WAIT_V(8); PG8_WAIT_L(0); PG8_BAR; if constexpr (!HALFU) { PG8_MMA(1, 0, At, B0); PG8_MMA(1, 1, At, B1); } PG8_BAR; PG8_SCHED;
;             PG8_LDB(B0, 1, 0); PG8_LDB(B1, 1, 1); PG8_SCHED; PG8_LDA(At, 1, 0); PG8_STAGE(PG8_SA(0, 1), a2 + hstepA, voffA);
	global_load_lds_dwordx4 v138, s[48:49]
	s_add_i32 m0, s10, 0x2000
	s_add_u32 s10, s48, 0x80000
	s_addc_u32 s11, s49, 0
	s_add_i32 s77, s72, s56
	global_load_lds_dwordx4 v142, s[48:49]
	s_mov_b32 m0, s77
	ds_read_b128 v[92:95], v151 offset:23552
	global_load_lds_dwordx4 v138, s[10:11]
	s_add_i32 m0, s77, 0x2000
	s_nop 0
	global_load_lds_dwordx4 v142, s[10:11]
	s_waitcnt vmcnt(4)
	s_waitcnt lgkmcnt(0)
	s_setprio 1
	s_barrier
	v_mfma_scale_f32_16x16x128_f8f6f4 v[60:63], v[128:135], v[64:71], v[60:63], v152, v152 op_sel_hi:[0,0,0]
	v_mfma_scale_f32_16x16x128_f8f6f4 v[56:59], v[154:161], v[64:71], v[56:59], v152, v152 op_sel_hi:[0,0,0]
	v_mfma_scale_f32_16x16x128_f8f6f4 v[194:197], v[128:135], v[72:79], v[44:47], v152, v152 op_sel_hi:[0,0,0]
	v_mfma_scale_f32_16x16x128_f8f6f4 v[198:201], v[154:161], v[72:79], v[40:43], v152, v152 op_sel_hi:[0,0,0]
	v_mfma_scale_f32_16x16x128_f8f6f4 v[202:205], v[128:135], v[80:87], v[28:31], v152, v152 op_sel_hi:[0,0,0]
	v_mfma_scale_f32_16x16x128_f8f6f4 v[206:209], v[154:161], v[80:87], v[24:27], v152, v152 op_sel_hi:[0,0,0]
	v_mfma_scale_f32_16x16x128_f8f6f4 v[226:229], v[128:135], v[88:95], v[12:15], v152, v152 op_sel_hi:[0,0,0]
	v_mfma_scale_f32_16x16x128_f8f6f4 v[230:233], v[154:161], v[88:95], v[8:11], v152, v152 op_sel_hi:[0,0,0]
	v_mfma_scale_f32_16x16x128_f8f6f4 v[52:55], v[162:169], v[64:71], v[52:55], v152, v152 op_sel_hi:[0,0,0]
	v_mfma_scale_f32_16x16x128_f8f6f4 v[48:51], v[170:177], v[64:71], v[48:51], v152, v152 op_sel_hi:[0,0,0]
	v_mfma_scale_f32_16x16x128_f8f6f4 v[234:237], v[162:169], v[72:79], v[36:39], v152, v152 op_sel_hi:[0,0,0]
	v_mfma_scale_f32_16x16x128_f8f6f4 v[238:241], v[170:177], v[72:79], v[32:35], v152, v152 op_sel_hi:[0,0,0]
	v_mfma_scale_f32_16x16x128_f8f6f4 v[242:245], v[162:169], v[80:87], v[20:23], v152, v152 op_sel_hi:[0,0,0]
	v_mfma_scale_f32_16x16x128_f8f6f4 v[246:249], v[170:177], v[80:87], v[16:19], v152, v152 op_sel_hi:[0,0,0]
	v_mfma_scale_f32_16x16x128_f8f6f4 v[250:253], v[162:169], v[88:95], v[4:7], v152, v152 op_sel_hi:[0,0,0]
	v_mfma_scale_f32_16x16x128_f8f6f4 v[144:147], v[170:177], v[88:95], v[0:3], v152, v152 op_sel_hi:[0,0,0]
	s_barrier
	s_setprio 0
	s_mov_b32 m0, s57
	s_nop 0
	global_load_lds_dwordx4 v136, s[50:51]
	s_mov_b32 m0, s62
	s_nop 0
	global_load_lds_dwordx4 v140, s[50:51]
	s_add_i32 s77, 0, 0x18000
	v_add_u32_e32 v8, s77, v148
	s_add_i32 s78, 0, 0x1c000
	s_nop 1
	ds_read_b128 v[0:3], v8
	ds_read_b128 v[4:7], v8 offset:1024
	ds_read_b128 v[16:19], v8 offset:2048
	ds_read_b128 v[20:23], v8 offset:3072
	v_add_u32_e32 v8, s78, v148
	ds_read_b128 v[128:131], v8
	ds_read_b128 v[132:135], v8 offset:1024
	ds_read_b128 v[154:157], v8 offset:2048
	ds_read_b128 v[158:161], v8 offset:3072
	s_add_u32 s10, s50, 0x80000
	s_addc_u32 s11, s51, 0
	s_mov_b32 m0, s63
	ds_read_b128 v[8:11], v151 offset:32768
	ds_read_b128 v[12:15], v151 offset:33792
	ds_read_b128 v[24:27], v151 offset:34816
	ds_read_b128 v[28:31], v151 offset:35840
	ds_read_b128 v[32:35], v151 offset:36864
	ds_read_b128 v[36:39], v151 offset:37888
	ds_read_b128 v[40:43], v151 offset:38912

; #define PG8_WAIT_V(n) asm volatile("s_waitcnt vmcnt(" #n ")" ::: "memory")
; #define PG8_WAIT_L(n) asm volatile("s_waitcnt lgkmcnt(" #n ")" ::: "memory")
; #define PG8_BAR __builtin_amdgcn_s_barrier()
; #define PG8_SCHED __builtin_amdgcn_sched_barrier(0)
;     ...
;             PG8_LDB(B0, 1, 0); PG8_LDB(B1, 1, 1); PG8_SCHED; PG8_LDA(At, 1, 0); PG8_STAGE(PG8_SA(0, 1), a2 + hstepA, voffA);
;             PG8_WAIT_V(8); PG8_WAIT_L(0); PG8_BAR; PG8_MMA(0, 0, At, B0); PG8_MMA(0, 1, At, B1); PG8_BAR; PG8_SCHED;
;             if constexpr (!HALFU) PG8_LDA(At, 1, 1); PG8_STAGE(PG8_SB(1, 0), b3, voffB); PG8_STAGE(PG8_SB(1, 1), b3 + hstep, voffB); PG8_STAGE(PG8_SA(1, 0), a3, voffA);
	global_load_lds_dwordx4 v136, s[10:11]
	s_mov_b32 m0, s64
	ds_read_b128 v[44:47], v151 offset:39936
	global_load_lds_dwordx4 v140, s[10:11]
	s_waitcnt vmcnt(8)
	s_waitcnt lgkmcnt(0)
	s_setprio 1
	s_barrier
	v_mfma_scale_f32_16x16x128_f8f6f4 v[124:127], v[0:7], v[8:15], v[124:127], v152, v152 op_sel_hi:[0,0,0]
	v_mfma_scale_f32_16x16x128_f8f6f4 v[120:123], v[16:23], v[8:15], v[120:123], v152, v152 op_sel_hi:[0,0,0]
	v_mfma_scale_f32_16x16x128_f8f6f4 v[108:111], v[0:7], v[24:31], v[108:111], v152, v152 op_sel_hi:[0,0,0]
	v_mfma_scale_f32_16x16x128_f8f6f4 v[104:107], v[16:23], v[24:31], v[104:107], v152, v152 op_sel_hi:[0,0,0]
	v_mfma_scale_f32_16x16x128_f8f6f4 v[92:95], v[0:7], v[32:39], v[210:213], v152, v152 op_sel_hi:[0,0,0]
	v_mfma_scale_f32_16x16x128_f8f6f4 v[88:91], v[16:23], v[32:39], v[214:217], v152, v152 op_sel_hi:[0,0,0]
	v_mfma_scale_f32_16x16x128_f8f6f4 v[76:79], v[0:7], v[40:47], v[218:221], v152, v152 op_sel_hi:[0,0,0]
	v_mfma_scale_f32_16x16x128_f8f6f4 v[72:75], v[16:23], v[40:47], v[222:225], v152, v152 op_sel_hi:[0,0,0]
	v_mfma_scale_f32_16x16x128_f8f6f4 v[116:119], v[128:135], v[8:15], v[116:119], v152, v152 op_sel_hi:[0,0,0]
	v_mfma_scale_f32_16x16x128_f8f6f4 v[112:115], v[154:161], v[8:15], v[112:115], v152, v152 op_sel_hi:[0,0,0]
	v_mfma_scale_f32_16x16x128_f8f6f4 v[100:103], v[128:135], v[24:31], v[100:103], v152, v152 op_sel_hi:[0,0,0]
	v_mfma_scale_f32_16x16x128_f8f6f4 v[96:99], v[154:161], v[24:31], v[96:99], v152, v152 op_sel_hi:[0,0,0]
	v_mfma_scale_f32_16x16x128_f8f6f4 v[84:87], v[128:135], v[32:39], v[178:181], v152, v152 op_sel_hi:[0,0,0]
	v_mfma_scale_f32_16x16x128_f8f6f4 v[80:83], v[154:161], v[32:39], v[182:185], v152, v152 op_sel_hi:[0,0,0]
	v_mfma_scale_f32_16x16x128_f8f6f4 v[68:71], v[128:135], v[40:47], v[186:189], v152, v152 op_sel_hi:[0,0,0]
	v_mfma_scale_f32_16x16x128_f8f6f4 v[64:67], v[154:161], v[40:47], v[190:193], v152, v152 op_sel_hi:[0,0,0]
	s_barrier
	s_setprio 0
	s_add_u32 s10, s48, 0x80
	s_addc_u32 s11, s49, 0
	s_add_i32 s50, s77, s56
	s_mov_b32 m0, s50
	ds_read_b128 v[32:35], v151 offset:49152
	ds_read_b128 v[36:39], v151 offset:50176
	ds_read_b128 v[162:165], v151 offset:51200
	ds_read_b128 v[166:169], v151 offset:52224
	ds_read_b128 v[170:173], v151 offset:53248
	ds_read_b128 v[174:177], v151 offset:54272
	ds_read_b128 v[178:181], v151 offset:55296

; #define PG8_WAIT_V(n) asm volatile("s_waitcnt vmcnt(" #n ")" ::: "memory")
; #define PG8_WAIT_L(n) asm volatile("s_waitcnt lgkmcnt(" #n ")" ::: "memory")
; #define PG8_BAR __builtin_amdgcn_s_barrier()
; #define PG8_SCHED __builtin_amdgcn_sched_barrier(0)
;     ...
;             if constexpr (!HALFU) PG8_LDA(At, 1, 1); PG8_STAGE(PG8_SB(1, 0), b3, voffB); PG8_STAGE(PG8_SB(1, 1), b3 + hstep, voffB); PG8_STAGE(PG8_SA(1, 0), a3, voffA);
;             PG8_WAIT_V(8); PG8_WAIT_L(0); PG8_BAR; if constexpr (!HALFU) { PG8_MMA(1, 0, At, B0); PG8_MMA(1, 1, At, B1); } PG8_BAR; PG8_SCHED;
;     ...
;         if constexpr (ALIGN_EPI) { if (wr == 0) PG8_BAR; }
	global_load_lds_dwordx4 v138, s[10:11]
	s_add_i32 m0, s50, 0x2000
	v_lshl_add_u64 v[8:9], s[10:11], 0, v[142:143]
	s_add_u32 s10, s48, 0x80080
	s_addc_u32 s11, s49, 0
	s_add_i32 s48, s78, s56
	global_load_lds_dwordx4 v[8:9], off
	s_mov_b32 m0, s48
	ds_read_b128 v[182:185], v151 offset:56320
	global_load_lds_dwordx4 v138, s[10:11]
	s_add_i32 m0, s48, 0x2000
	s_nop 0
	global_load_lds_dwordx4 v142, s[10:11]
	s_waitcnt vmcnt(4)
	s_waitcnt lgkmcnt(0)
	s_setprio 1
	s_barrier
	v_mfma_scale_f32_16x16x128_f8f6f4 v[60:63], v[0:7], v[32:39], v[60:63], v152, v152 op_sel_hi:[0,0,0]
	v_mfma_scale_f32_16x16x128_f8f6f4 v[56:59], v[16:23], v[32:39], v[56:59], v152, v152 op_sel_hi:[0,0,0]
	v_mfma_scale_f32_16x16x128_f8f6f4 v[44:47], v[0:7], v[162:169], v[194:197], v152, v152 op_sel_hi:[0,0,0]
	v_mfma_scale_f32_16x16x128_f8f6f4 v[40:43], v[16:23], v[162:169], v[198:201], v152, v152 op_sel_hi:[0,0,0]
	v_mfma_scale_f32_16x16x128_f8f6f4 v[28:31], v[0:7], v[170:177], v[202:205], v152, v152 op_sel_hi:[0,0,0]
	v_mfma_scale_f32_16x16x128_f8f6f4 v[24:27], v[16:23], v[170:177], v[206:209], v152, v152 op_sel_hi:[0,0,0]
	v_mfma_scale_f32_16x16x128_f8f6f4 v[12:15], v[0:7], v[178:185], v[226:229], v152, v152 op_sel_hi:[0,0,0]
	v_mfma_scale_f32_16x16x128_f8f6f4 v[8:11], v[16:23], v[178:185], v[230:233], v152, v152 op_sel_hi:[0,0,0]
	v_mfma_scale_f32_16x16x128_f8f6f4 v[52:55], v[128:135], v[32:39], v[52:55], v152, v152 op_sel_hi:[0,0,0]
	v_mfma_scale_f32_16x16x128_f8f6f4 v[48:51], v[154:161], v[32:39], v[48:51], v152, v152 op_sel_hi:[0,0,0]
	v_mfma_scale_f32_16x16x128_f8f6f4 v[36:39], v[128:135], v[162:169], v[234:237], v152, v152 op_sel_hi:[0,0,0]
	v_mfma_scale_f32_16x16x128_f8f6f4 v[32:35], v[154:161], v[162:169], v[238:241], v152, v152 op_sel_hi:[0,0,0]
	v_mfma_scale_f32_16x16x128_f8f6f4 v[20:23], v[128:135], v[170:177], v[242:245], v152, v152 op_sel_hi:[0,0,0]
	v_mfma_scale_f32_16x16x128_f8f6f4 v[16:19], v[154:161], v[170:177], v[246:249], v152, v152 op_sel_hi:[0,0,0]
	v_mfma_scale_f32_16x16x128_f8f6f4 v[4:7], v[128:135], v[178:185], v[250:253], v152, v152 op_sel_hi:[0,0,0]
	v_mfma_scale_f32_16x16x128_f8f6f4 v[0:3], v[154:161], v[178:185], v[144:147], v152, v152 op_sel_hi:[0,0,0]
	s_barrier
	s_setprio 0
	s_add_i32 s76, s76, 2
	s_add_u32 s74, s74, 0x100
	s_addc_u32 s75, s75, 0
	s_cmp_gt_u32 s76, 29
	s_mov_b64 s[10:11], s[26:27]
	s_cbranch_scc0 .LBB0_1200
	s_and_b64 vcc, exec, s[36:37]
	s_cbranch_vccz .LBB0_1203
	s_barrier

; #define PG8_SCHED __builtin_amdgcn_sched_barrier(0)
;     ...
;         for (int t = 0; t < nt; t += 2) {
;             const bool last = (t == nt - 2);
;             const char* a1 = cA + (size_t)(t + 1) * kstep;
;             const char* a2 = last ? nA : cA + (size_t)(t + 2) * kstep; const char* b2 = last ? nB : cB + (size_t)(t + 2) * kstep;
;             const char* a3 = a2 + kstep; const char* b3 = b2 + kstep;
;             if (last && has_next) S.a_ready(nxt);
;             if constexpr (SP2) {
;             PG8_LDB(B0, 0, 0); PG8_LDB(B1, 0, 1); PG8_SCHED; PG8_LDA(At, 0, 0); PG8_STAGE(PG8_SA(1, 1), a1 + hstepA, voffA);
.LBB0_1370:
	s_add_u32 s98, s10, 0x80
	s_addc_u32 s99, s11, 0
	s_mov_b32 m0, s67
	ds_read_b128 v[128:131], v163
	global_load_lds_dwordx4 v136, s[98:99]
	s_mov_b32 m0, s68
	ds_read_b128 v[132:135], v163 offset:1024
	global_load_lds_dwordx4 v140, s[98:99]


; #define PG8_SCHED __builtin_amdgcn_sched_barrier(0)
;     ...
;             const bool last = (t == nt - 2);
;             const char* a1 = cA + (size_t)(t + 1) * kstep;
;             const char* a2 = last ? nA : cA + (size_t)(t + 2) * kstep; const char* b2 = last ? nB : cB + (size_t)(t + 2) * kstep;
;             const char* a3 = a2 + kstep; const char* b3 = b2 + kstep;
;             if (last && has_next) S.a_ready(nxt);
;             if constexpr (SP2) {
;             PG8_LDB(B0, 0, 0); PG8_LDB(B1, 0, 1); PG8_SCHED; PG8_LDA(At, 0, 0); PG8_STAGE(PG8_SA(1, 1), a1 + hstepA, voffA);
	ds_read_b128 v[150:153], v163 offset:2048
	ds_read_b128 v[154:157], v163 offset:3072
	ds_read_b128 v[158:161], v164
	ds_read_b128 v[166:169], v164 offset:1024
	ds_read_b128 v[170:173], v164 offset:2048
	ds_read_b128 v[174:177], v164 offset:3072
	s_add_u32 s12, s10, 0x100
	s_addc_u32 s13, s11, 0
	s_cmp_eq_u32 s53, 60
	s_cselect_b32 s50, s7, s12
	s_cselect_b32 s51, s0, s13
	s_cselect_b32 s48, s39, s41
	s_cselect_b32 s49, s9, s52
	s_add_u32 s46, s50, 0x80
	s_addc_u32 s47, s51, 0
	s_add_u32 s10, s10, 0x100080
	s_addc_u32 s11, s11, 0
	s_add_i32 m0, s37, 0xc000
	ds_read_b128 v[178:181], v165
	ds_read_b128 v[182:185], v165 offset:1024
	ds_read_b128 v[186:189], v165 offset:2048
	ds_read_b128 v[190:193], v165 offset:3072
	ds_read_b128 v[194:197], v165 offset:4096
	ds_read_b128 v[198:201], v165 offset:5120
	ds_read_b128 v[202:205], v165 offset:6144

; #define PG8_WAIT_V(n) asm volatile("s_waitcnt vmcnt(" #n ")" ::: "memory")
; #define PG8_WAIT_L(n) asm volatile("s_waitcnt lgkmcnt(" #n ")" ::: "memory")
; #define PG8_BAR __builtin_amdgcn_s_barrier()
; #define PG8_SCHED __builtin_amdgcn_sched_barrier(0)
;     ...
;             PG8_LDB(B0, 0, 0); PG8_LDB(B1, 0, 1); PG8_SCHED; PG8_LDA(At, 0, 0); PG8_STAGE(PG8_SA(1, 1), a1 + hstepA, voffA);
;             PG8_WAIT_V(8); PG8_WAIT_L(0); PG8_BAR; PG8_MMA(0, 0, At, B0); PG8_MMA(0, 1, At, B1); PG8_BAR; PG8_SCHED;
;             if constexpr (!HALFU) PG8_LDA(At, 0, 1); PG8_STAGE(PG8_SB(0, 0), b2, voffB); PG8_STAGE(PG8_SB(0, 1), b2 + hstep, voffB); PG8_STAGE(PG8_SA(0, 0), a2, voffA);
	global_load_lds_dwordx4 v136, s[10:11]
	s_add_i32 m0, s37, 0xe000
	ds_read_b128 v[206:209], v165 offset:7168
	global_load_lds_dwordx4 v140, s[10:11]
	s_waitcnt vmcnt(8)
	s_waitcnt lgkmcnt(0)
	s_setprio 1
	s_barrier
	v_mfma_f32_16x16x32_bf16 v[124:127], v[128:131], v[178:181], v[124:127]
	v_mfma_f32_16x16x32_bf16 v[120:123], v[150:153], v[178:181], v[120:123]
	v_mfma_f32_16x16x32_bf16 v[108:111], v[128:131], v[186:189], v[108:111]
	v_mfma_f32_16x16x32_bf16 v[104:107], v[150:153], v[186:189], v[104:107]
	v_mfma_f32_16x16x32_bf16 v[92:95], v[128:131], v[194:197], v[92:95]
	v_mfma_f32_16x16x32_bf16 v[88:91], v[150:153], v[194:197], v[88:91]
	v_mfma_f32_16x16x32_bf16 v[76:79], v[128:131], v[202:205], v[76:79]
	v_mfma_f32_16x16x32_bf16 v[72:75], v[150:153], v[202:205], v[72:75]
	v_mfma_f32_16x16x32_bf16 v[124:127], v[132:135], v[182:185], v[124:127]
	v_mfma_f32_16x16x32_bf16 v[120:123], v[154:157], v[182:185], v[120:123]
	v_mfma_f32_16x16x32_bf16 v[108:111], v[132:135], v[190:193], v[108:111]
	v_mfma_f32_16x16x32_bf16 v[104:107], v[154:157], v[190:193], v[104:107]
	v_mfma_f32_16x16x32_bf16 v[92:95], v[132:135], v[198:201], v[92:95]
	v_mfma_f32_16x16x32_bf16 v[88:91], v[154:157], v[198:201], v[88:91]
	v_mfma_f32_16x16x32_bf16 v[76:79], v[132:135], v[206:209], v[76:79]
	v_mfma_f32_16x16x32_bf16 v[72:75], v[154:157], v[206:209], v[72:75]
	v_mfma_f32_16x16x32_bf16 v[116:119], v[158:161], v[178:181], v[116:119]
	v_mfma_f32_16x16x32_bf16 v[112:115], v[170:173], v[178:181], v[112:115]
	v_mfma_f32_16x16x32_bf16 v[100:103], v[158:161], v[186:189], v[100:103]
	v_mfma_f32_16x16x32_bf16 v[96:99], v[170:173], v[186:189], v[96:99]
	v_mfma_f32_16x16x32_bf16 v[84:87], v[158:161], v[194:197], v[84:87]
	v_mfma_f32_16x16x32_bf16 v[80:83], v[170:173], v[194:197], v[80:83]
	v_mfma_f32_16x16x32_bf16 v[68:71], v[158:161], v[202:205], v[68:71]
	v_mfma_f32_16x16x32_bf16 v[64:67], v[170:173], v[202:205], v[64:67]
	v_mfma_f32_16x16x32_bf16 v[116:119], v[166:169], v[182:185], v[116:119]
	v_mfma_f32_16x16x32_bf16 v[112:115], v[174:177], v[182:185], v[112:115]
	v_mfma_f32_16x16x32_bf16 v[100:103], v[166:169], v[190:193], v[100:103]
	v_mfma_f32_16x16x32_bf16 v[96:99], v[174:177], v[190:193], v[96:99]
	v_mfma_f32_16x16x32_bf16 v[84:87], v[166:169], v[198:201], v[84:87]
	v_mfma_f32_16x16x32_bf16 v[80:83], v[174:177], v[198:201], v[80:83]
	v_mfma_f32_16x16x32_bf16 v[68:71], v[166:169], v[206:209], v[68:71]
	v_mfma_f32_16x16x32_bf16 v[64:67], v[174:177], v[206:209], v[64:67]
	s_barrier
	s_setprio 0
	s_add_i32 s10, s71, s21
	s_mov_b32 m0, s10
	ds_read_b128 v[178:181], v165 offset:16384
	ds_read_b128 v[182:185], v165 offset:17408
	ds_read_b128 v[186:189], v165 offset:18432
	ds_read_b128 v[190:193], v165 offset:19456
	ds_read_b128 v[194:197], v165 offset:20480
	ds_read_b128 v[198:201], v165 offset:21504
	ds_read_b128 v[202:205], v165 offset:22528

; #define PG8_WAIT_V(n) asm volatile("s_waitcnt vmcnt(" #n ")" ::: "memory")
; #define PG8_WAIT_L(n) asm volatile("s_waitcnt lgkmcnt(" #n ")" ::: "memory")
; #define PG8_BAR __builtin_amdgcn_s_barrier()
; #define PG8_SCHED __builtin_amdgcn_sched_barrier(0)
;     ...
;             if constexpr (!HALFU) PG8_LDA(At, 0, 1); PG8_STAGE(PG8_SB(0, 0), b2, voffB); PG8_STAGE(PG8_SB(0, 1), b2 + hstep, voffB); PG8_STAGE(PG8_SA(0, 0), a2, voffA);
;             PG8_WAIT_V(8); PG8_WAIT_L(0); PG8_BAR; if constexpr (!HALFU) { PG8_MMA(1, 0, At, B0); PG8_MMA(1, 1, At, B1); } PG8_BAR; PG8_SCHED;
;             PG8_LDB(B0, 1, 0); PG8_LDB(B1, 1, 1); PG8_SCHED; PG8_LDA(At, 1, 0); PG8_STAGE(PG8_SA(0, 1), a2 + hstepA, voffA);
	global_load_lds_dwordx4 v138, s[48:49]
	s_add_i32 m0, s10, 0x2000
	s_add_u32 s10, s48, 0x100000
	s_addc_u32 s11, s49, 0
	s_add_i32 s54, s72, s21
	global_load_lds_dwordx4 v142, s[48:49]
	s_mov_b32 m0, s54
	ds_read_b128 v[206:209], v165 offset:23552
	global_load_lds_dwordx4 v138, s[10:11]
	s_add_i32 m0, s54, 0x2000
	s_nop 0
	global_load_lds_dwordx4 v142, s[10:11]
	s_waitcnt vmcnt(4)
	s_waitcnt lgkmcnt(0)
	s_setprio 1
	s_barrier
	v_mfma_f32_16x16x32_bf16 v[60:63], v[128:131], v[178:181], v[60:63]
	v_mfma_f32_16x16x32_bf16 v[56:59], v[150:153], v[178:181], v[56:59]
	v_mfma_f32_16x16x32_bf16 v[44:47], v[128:131], v[186:189], v[44:47]
	v_mfma_f32_16x16x32_bf16 v[40:43], v[150:153], v[186:189], v[40:43]
	v_mfma_f32_16x16x32_bf16 v[28:31], v[128:131], v[194:197], v[28:31]
	v_mfma_f32_16x16x32_bf16 v[24:27], v[150:153], v[194:197], v[24:27]
	v_mfma_f32_16x16x32_bf16 v[12:15], v[128:131], v[202:205], v[12:15]
	v_mfma_f32_16x16x32_bf16 v[8:11], v[150:153], v[202:205], v[8:11]
	v_mfma_f32_16x16x32_bf16 v[60:63], v[132:135], v[182:185], v[60:63]
	v_mfma_f32_16x16x32_bf16 v[56:59], v[154:157], v[182:185], v[56:59]
	v_mfma_f32_16x16x32_bf16 v[44:47], v[132:135], v[190:193], v[44:47]
	v_mfma_f32_16x16x32_bf16 v[40:43], v[154:157], v[190:193], v[40:43]
	v_mfma_f32_16x16x32_bf16 v[28:31], v[132:135], v[198:201], v[28:31]
	v_mfma_f32_16x16x32_bf16 v[24:27], v[154:157], v[198:201], v[24:27]
	v_mfma_f32_16x16x32_bf16 v[12:15], v[132:135], v[206:209], v[12:15]
	v_mfma_f32_16x16x32_bf16 v[8:11], v[154:157], v[206:209], v[8:11]
	v_mfma_f32_16x16x32_bf16 v[52:55], v[158:161], v[178:181], v[52:55]
	v_mfma_f32_16x16x32_bf16 v[48:51], v[170:173], v[178:181], v[48:51]
	v_mfma_f32_16x16x32_bf16 v[36:39], v[158:161], v[186:189], v[36:39]
	v_mfma_f32_16x16x32_bf16 v[32:35], v[170:173], v[186:189], v[32:35]
	v_mfma_f32_16x16x32_bf16 v[20:23], v[158:161], v[194:197], v[20:23]
	v_mfma_f32_16x16x32_bf16 v[16:19], v[170:173], v[194:197], v[16:19]
	v_mfma_f32_16x16x32_bf16 v[4:7], v[158:161], v[202:205], v[4:7]
	v_mfma_f32_16x16x32_bf16 v[0:3], v[170:173], v[202:205], v[0:3]
	v_mfma_f32_16x16x32_bf16 v[52:55], v[166:169], v[182:185], v[52:55]
	v_mfma_f32_16x16x32_bf16 v[48:51], v[174:177], v[182:185], v[48:51]
	v_mfma_f32_16x16x32_bf16 v[36:39], v[166:169], v[190:193], v[36:39]
	v_mfma_f32_16x16x32_bf16 v[32:35], v[174:177], v[190:193], v[32:35]
	v_mfma_f32_16x16x32_bf16 v[20:23], v[166:169], v[198:201], v[20:23]
	v_mfma_f32_16x16x32_bf16 v[16:19], v[174:177], v[198:201], v[16:19]
	v_mfma_f32_16x16x32_bf16 v[4:7], v[166:169], v[206:209], v[4:7]
	v_mfma_f32_16x16x32_bf16 v[0:3], v[174:177], v[206:209], v[0:3]
	s_barrier
	s_setprio 0
	s_mov_b32 m0, s37
	ds_read_b128 v[178:181], v165 offset:32768
	global_load_lds_dwordx4 v136, s[50:51]
	s_mov_b32 m0, s62
	ds_read_b128 v[182:185], v165 offset:33792
	global_load_lds_dwordx4 v140, s[50:51]
	s_add_i32 s54, 0, 0x18000
	v_add_u32_e32 v144, s54, v162
	s_add_i32 s55, 0, 0x1c000
	ds_read_b128 v[128:131], v144
	ds_read_b128 v[132:135], v144 offset:1024
	ds_read_b128 v[150:153], v144 offset:2048
	ds_read_b128 v[154:157], v144 offset:3072
	v_add_u32_e32 v144, s55, v162
	ds_read_b128 v[158:161], v144
	ds_read_b128 v[166:169], v144 offset:1024
	ds_read_b128 v[170:173], v144 offset:2048
	ds_read_b128 v[174:177], v144 offset:3072
	s_add_u32 s10, s50, 0x100000
	s_addc_u32 s11, s51, 0
	s_mov_b32 m0, s63


; #define PG8_SCHED __builtin_amdgcn_sched_barrier(0)
;     ...
;             PG8_LDB(B0, 1, 0); PG8_LDB(B1, 1, 1); PG8_SCHED; PG8_LDA(At, 1, 0); PG8_STAGE(PG8_SA(0, 1), a2 + hstepA, voffA);
	ds_read_b128 v[186:189], v165 offset:34816
	ds_read_b128 v[190:193], v165 offset:35840
	ds_read_b128 v[194:197], v165 offset:36864
	ds_read_b128 v[198:201], v165 offset:37888
	ds_read_b128 v[202:205], v165 offset:38912

; #define PG8_WAIT_V(n) asm volatile("s_waitcnt vmcnt(" #n ")" ::: "memory")
; #define PG8_WAIT_L(n) asm volatile("s_waitcnt lgkmcnt(" #n ")" ::: "memory")
; #define PG8_BAR __builtin_amdgcn_s_barrier()
; #define PG8_SCHED __builtin_amdgcn_sched_barrier(0)
;     ...
;             PG8_LDB(B0, 1, 0); PG8_LDB(B1, 1, 1); PG8_SCHED; PG8_LDA(At, 1, 0); PG8_STAGE(PG8_SA(0, 1), a2 + hstepA, voffA);
;             PG8_WAIT_V(8); PG8_WAIT_L(0); PG8_BAR; PG8_MMA(0, 0, At, B0); PG8_MMA(0, 1, At, B1); PG8_BAR; PG8_SCHED;
;             if constexpr (!HALFU) PG8_LDA(At, 1, 1); PG8_STAGE(PG8_SB(1, 0), b3, voffB); PG8_STAGE(PG8_SB(1, 1), b3 + hstep, voffB); PG8_STAGE(PG8_SA(1, 0), a3, voffA);
	global_load_lds_dwordx4 v136, s[10:11]
	s_mov_b32 m0, s64
	ds_read_b128 v[206:209], v165 offset:39936
	global_load_lds_dwordx4 v140, s[10:11]
	s_waitcnt vmcnt(8)
	s_waitcnt lgkmcnt(0)
	s_setprio 1
	s_barrier
	v_mfma_f32_16x16x32_bf16 v[124:127], v[128:131], v[178:181], v[124:127]
	v_mfma_f32_16x16x32_bf16 v[120:123], v[150:153], v[178:181], v[120:123]
	v_mfma_f32_16x16x32_bf16 v[108:111], v[128:131], v[186:189], v[108:111]
	v_mfma_f32_16x16x32_bf16 v[104:107], v[150:153], v[186:189], v[104:107]
	v_mfma_f32_16x16x32_bf16 v[92:95], v[128:131], v[194:197], v[92:95]
	v_mfma_f32_16x16x32_bf16 v[88:91], v[150:153], v[194:197], v[88:91]
	v_mfma_f32_16x16x32_bf16 v[76:79], v[128:131], v[202:205], v[76:79]
	v_mfma_f32_16x16x32_bf16 v[72:75], v[150:153], v[202:205], v[72:75]
	v_mfma_f32_16x16x32_bf16 v[124:127], v[132:135], v[182:185], v[124:127]
	v_mfma_f32_16x16x32_bf16 v[120:123], v[154:157], v[182:185], v[120:123]
	v_mfma_f32_16x16x32_bf16 v[108:111], v[132:135], v[190:193], v[108:111]
	v_mfma_f32_16x16x32_bf16 v[104:107], v[154:157], v[190:193], v[104:107]
	v_mfma_f32_16x16x32_bf16 v[92:95], v[132:135], v[198:201], v[92:95]
	v_mfma_f32_16x16x32_bf16 v[88:91], v[154:157], v[198:201], v[88:91]
	v_mfma_f32_16x16x32_bf16 v[76:79], v[132:135], v[206:209], v[76:79]
	v_mfma_f32_16x16x32_bf16 v[72:75], v[154:157], v[206:209], v[72:75]
	v_mfma_f32_16x16x32_bf16 v[116:119], v[158:161], v[178:181], v[116:119]
	v_mfma_f32_16x16x32_bf16 v[112:115], v[170:173], v[178:181], v[112:115]
	v_mfma_f32_16x16x32_bf16 v[100:103], v[158:161], v[186:189], v[100:103]
	v_mfma_f32_16x16x32_bf16 v[96:99], v[170:173], v[186:189], v[96:99]
	v_mfma_f32_16x16x32_bf16 v[84:87], v[158:161], v[194:197], v[84:87]
	v_mfma_f32_16x16x32_bf16 v[80:83], v[170:173], v[194:197], v[80:83]
	v_mfma_f32_16x16x32_bf16 v[68:71], v[158:161], v[202:205], v[68:71]
	v_mfma_f32_16x16x32_bf16 v[64:67], v[170:173], v[202:205], v[64:67]
	v_mfma_f32_16x16x32_bf16 v[116:119], v[166:169], v[182:185], v[116:119]
	v_mfma_f32_16x16x32_bf16 v[112:115], v[174:177], v[182:185], v[112:115]
	v_mfma_f32_16x16x32_bf16 v[100:103], v[166:169], v[190:193], v[100:103]
	v_mfma_f32_16x16x32_bf16 v[96:99], v[174:177], v[190:193], v[96:99]
	v_mfma_f32_16x16x32_bf16 v[84:87], v[166:169], v[198:201], v[84:87]
	v_mfma_f32_16x16x32_bf16 v[80:83], v[174:177], v[198:201], v[80:83]
	v_mfma_f32_16x16x32_bf16 v[68:71], v[166:169], v[206:209], v[68:71]
	v_mfma_f32_16x16x32_bf16 v[64:67], v[174:177], v[206:209], v[64:67]
	s_barrier
	s_setprio 0
	s_add_u32 s10, s48, 0x80
	s_addc_u32 s11, s49, 0
	s_add_i32 s50, s54, s21
	s_mov_b32 m0, s50
	ds_read_b128 v[178:181], v165 offset:49152
	ds_read_b128 v[182:185], v165 offset:50176
	ds_read_b128 v[186:189], v165 offset:51200
	ds_read_b128 v[190:193], v165 offset:52224
	ds_read_b128 v[194:197], v165 offset:53248
	ds_read_b128 v[198:201], v165 offset:54272
	ds_read_b128 v[202:205], v165 offset:55296

; #define PG8_WAIT_V(n) asm volatile("s_waitcnt vmcnt(" #n ")" ::: "memory")
; #define PG8_WAIT_L(n) asm volatile("s_waitcnt lgkmcnt(" #n ")" ::: "memory")
; #define PG8_BAR __builtin_amdgcn_s_barrier()
; #define PG8_SCHED __builtin_amdgcn_sched_barrier(0)
;     ...
;             if constexpr (!HALFU) PG8_LDA(At, 1, 1); PG8_STAGE(PG8_SB(1, 0), b3, voffB); PG8_STAGE(PG8_SB(1, 1), b3 + hstep, voffB); PG8_STAGE(PG8_SA(1, 0), a3, voffA);
;             PG8_WAIT_V(8); PG8_WAIT_L(0); PG8_BAR; if constexpr (!HALFU) { PG8_MMA(1, 0, At, B0); PG8_MMA(1, 1, At, B1); } PG8_BAR; PG8_SCHED;
;     ...
;         if constexpr (ALIGN_EPI) { if (wr == 0) PG8_BAR; }
	global_load_lds_dwordx4 v138, s[10:11]
	s_add_i32 m0, s50, 0x2000
	v_lshl_add_u64 v[210:211], s[10:11], 0, v[142:143]
	s_add_u32 s10, s48, 0x100080
	s_addc_u32 s11, s49, 0
	s_add_i32 s48, s55, s21
	global_load_lds_dwordx4 v[210:211], off
	s_mov_b32 m0, s48
	ds_read_b128 v[206:209], v165 offset:56320
	global_load_lds_dwordx4 v138, s[10:11]
	s_add_i32 m0, s48, 0x2000
	s_nop 0
	global_load_lds_dwordx4 v142, s[10:11]
	s_waitcnt vmcnt(4)
	s_waitcnt lgkmcnt(0)
	s_setprio 1
	s_barrier
	v_mfma_f32_16x16x32_bf16 v[60:63], v[128:131], v[178:181], v[60:63]
	v_mfma_f32_16x16x32_bf16 v[56:59], v[150:153], v[178:181], v[56:59]
	v_mfma_f32_16x16x32_bf16 v[44:47], v[128:131], v[186:189], v[44:47]
	v_mfma_f32_16x16x32_bf16 v[40:43], v[150:153], v[186:189], v[40:43]
	v_mfma_f32_16x16x32_bf16 v[28:31], v[128:131], v[194:197], v[28:31]
	v_mfma_f32_16x16x32_bf16 v[24:27], v[150:153], v[194:197], v[24:27]
	v_mfma_f32_16x16x32_bf16 v[12:15], v[128:131], v[202:205], v[12:15]
	v_mfma_f32_16x16x32_bf16 v[8:11], v[150:153], v[202:205], v[8:11]
	v_mfma_f32_16x16x32_bf16 v[60:63], v[132:135], v[182:185], v[60:63]
	v_mfma_f32_16x16x32_bf16 v[56:59], v[154:157], v[182:185], v[56:59]
	v_mfma_f32_16x16x32_bf16 v[44:47], v[132:135], v[190:193], v[44:47]
	v_mfma_f32_16x16x32_bf16 v[40:43], v[154:157], v[190:193], v[40:43]
	v_mfma_f32_16x16x32_bf16 v[28:31], v[132:135], v[198:201], v[28:31]
	v_mfma_f32_16x16x32_bf16 v[24:27], v[154:157], v[198:201], v[24:27]
	v_mfma_f32_16x16x32_bf16 v[12:15], v[132:135], v[206:209], v[12:15]
	v_mfma_f32_16x16x32_bf16 v[8:11], v[154:157], v[206:209], v[8:11]
	v_mfma_f32_16x16x32_bf16 v[52:55], v[158:161], v[178:181], v[52:55]
	v_mfma_f32_16x16x32_bf16 v[48:51], v[170:173], v[178:181], v[48:51]
	v_mfma_f32_16x16x32_bf16 v[36:39], v[158:161], v[186:189], v[36:39]
	v_mfma_f32_16x16x32_bf16 v[32:35], v[170:173], v[186:189], v[32:35]
	v_mfma_f32_16x16x32_bf16 v[20:23], v[158:161], v[194:197], v[20:23]
	v_mfma_f32_16x16x32_bf16 v[16:19], v[170:173], v[194:197], v[16:19]
	v_mfma_f32_16x16x32_bf16 v[4:7], v[158:161], v[202:205], v[4:7]
	v_mfma_f32_16x16x32_bf16 v[0:3], v[170:173], v[202:205], v[0:3]
	v_mfma_f32_16x16x32_bf16 v[52:55], v[166:169], v[182:185], v[52:55]
	v_mfma_f32_16x16x32_bf16 v[48:51], v[174:177], v[182:185], v[48:51]
	v_mfma_f32_16x16x32_bf16 v[36:39], v[166:169], v[190:193], v[36:39]
	v_mfma_f32_16x16x32_bf16 v[32:35], v[174:177], v[190:193], v[32:35]
	v_mfma_f32_16x16x32_bf16 v[20:23], v[166:169], v[198:201], v[20:23]
	v_mfma_f32_16x16x32_bf16 v[16:19], v[174:177], v[198:201], v[16:19]
	v_mfma_f32_16x16x32_bf16 v[4:7], v[166:169], v[206:209], v[4:7]
	v_mfma_f32_16x16x32_bf16 v[0:3], v[174:177], v[206:209], v[0:3]
	s_barrier
	s_setprio 0
	s_add_i32 s53, s53, 2
	s_add_u32 s41, s41, 0x100
	s_addc_u32 s52, s52, 0
	s_cmp_gt_u32 s53, 61
	s_mov_b64 s[10:11], s[12:13]
	s_cbranch_scc0 .LBB0_1370
	s_and_b64 vcc, exec, s[28:29]
	s_cbranch_vccz .LBB0_1373
	s_barrier

; #define PG8_SCHED __builtin_amdgcn_sched_barrier(0)
;     ...
;         for (int t = 0; t < nt; t += 2) {
;             const bool last = (t == nt - 2);
;             const char* a1 = cA + (size_t)(t + 1) * kstep;
;             const char* a2 = last ? nA : cA + (size_t)(t + 2) * kstep; const char* b2 = last ? nB : cB + (size_t)(t + 2) * kstep;
;             const char* a3 = a2 + kstep; const char* b3 = b2 + kstep;
;             if (last && has_next) S.a_ready(nxt);
;             if constexpr (SP2) {
;             PG8_LDB(B0, 0, 0); PG8_LDB(B1, 0, 1); PG8_SCHED; PG8_LDA(At, 0, 0); PG8_STAGE(PG8_SA(1, 1), a1 + hstepA, voffA);
.LBB0_3426:
	s_sub_u32 s98, s28, 0x80000
	s_subb_u32 s99, s29, 0
	s_mov_b32 m0, s50
	ds_read_b128 v[142:145], v137
	global_load_lds_dwordx4 v128, s[98:99]
	s_mov_b32 m0, s51
	ds_read_b128 v[146:149], v137 offset:1024
	global_load_lds_dwordx4 v130, s[98:99]


; #define PG8_SCHED __builtin_amdgcn_sched_barrier(0)
;     ...
;             const bool last = (t == nt - 2);
;             const char* a1 = cA + (size_t)(t + 1) * kstep;
;             const char* a2 = last ? nA : cA + (size_t)(t + 2) * kstep; const char* b2 = last ? nB : cB + (size_t)(t + 2) * kstep;
;             const char* a3 = a2 + kstep; const char* b3 = b2 + kstep;
;             if (last && has_next) S.a_ready(nxt);
;             if constexpr (SP2) {
;             PG8_LDB(B0, 0, 0); PG8_LDB(B1, 0, 1); PG8_SCHED; PG8_LDA(At, 0, 0); PG8_STAGE(PG8_SA(1, 1), a1 + hstepA, voffA);
	ds_read_b128 v[150:153], v137 offset:2048
	ds_read_b128 v[154:157], v137 offset:3072
	ds_read_b128 v[158:161], v138
	ds_read_b128 v[162:165], v138 offset:1024
	ds_read_b128 v[166:169], v138 offset:2048
	ds_read_b128 v[170:173], v138 offset:3072
	s_cmp_eq_u32 s62, 28
	s_cselect_b32 s38, s55, s57
	s_cselect_b32 s39, s23, s59
	s_cselect_b32 s36, s56, s60
	s_cselect_b32 s37, s21, s61
	s_add_u32 s30, s38, 0x80
	s_addc_u32 s31, s39, 0
	s_add_i32 m0, s43, 0xc000
	ds_read_b128 v[174:177], v139
	ds_read_b128 v[178:181], v139 offset:1024
	ds_read_b128 v[182:185], v139 offset:2048
	ds_read_b128 v[186:189], v139 offset:3072
	ds_read_b128 v[190:193], v139 offset:4096
	ds_read_b128 v[194:197], v139 offset:5120
	ds_read_b128 v[198:201], v139 offset:6144

; #define PG8_WAIT_V(n) asm volatile("s_waitcnt vmcnt(" #n ")" ::: "memory")
; #define PG8_WAIT_L(n) asm volatile("s_waitcnt lgkmcnt(" #n ")" ::: "memory")
; #define PG8_BAR __builtin_amdgcn_s_barrier()
; #define PG8_SCHED __builtin_amdgcn_sched_barrier(0)
;     ...
;             PG8_LDB(B0, 0, 0); PG8_LDB(B1, 0, 1); PG8_SCHED; PG8_LDA(At, 0, 0); PG8_STAGE(PG8_SA(1, 1), a1 + hstepA, voffA);
;             PG8_WAIT_V(8); PG8_WAIT_L(0); PG8_BAR; PG8_MMA(0, 0, At, B0); PG8_MMA(0, 1, At, B1); PG8_BAR; PG8_SCHED;
;             if constexpr (!HALFU) PG8_LDA(At, 0, 1); PG8_STAGE(PG8_SB(0, 0), b2, voffB); PG8_STAGE(PG8_SB(0, 1), b2 + hstep, voffB); PG8_STAGE(PG8_SA(0, 0), a2, voffA);
	global_load_lds_dwordx4 v128, s[28:29]
	s_add_i32 m0, s43, 0xe000
	ds_read_b128 v[202:205], v139 offset:7168
	global_load_lds_dwordx4 v130, s[28:29]
	s_waitcnt vmcnt(8)
	s_waitcnt lgkmcnt(0)
	s_setprio 1
	s_barrier
	v_mfma_scale_f32_16x16x128_f8f6f4 v[124:127], v[142:149], v[174:181], v[124:127], v140, v140 op_sel_hi:[0,0,0]
	v_mfma_scale_f32_16x16x128_f8f6f4 v[120:123], v[150:157], v[174:181], v[120:123], v140, v140 op_sel_hi:[0,0,0]
	v_mfma_scale_f32_16x16x128_f8f6f4 v[112:115], v[142:149], v[182:189], v[112:115], v140, v140 op_sel_hi:[0,0,0]
	v_mfma_scale_f32_16x16x128_f8f6f4 v[104:107], v[150:157], v[182:189], v[104:107], v140, v140 op_sel_hi:[0,0,0]
	v_mfma_scale_f32_16x16x128_f8f6f4 v[96:99], v[142:149], v[190:197], v[96:99], v140, v140 op_sel_hi:[0,0,0]
	v_mfma_scale_f32_16x16x128_f8f6f4 v[206:209], v[150:157], v[190:197], v[88:91], v140, v140 op_sel_hi:[0,0,0]
	v_mfma_scale_f32_16x16x128_f8f6f4 v[210:213], v[142:149], v[198:205], v[80:83], v140, v140 op_sel_hi:[0,0,0]
	v_mfma_scale_f32_16x16x128_f8f6f4 v[214:217], v[150:157], v[198:205], v[72:75], v140, v140 op_sel_hi:[0,0,0]
	v_mfma_scale_f32_16x16x128_f8f6f4 v[116:119], v[158:165], v[174:181], v[116:119], v140, v140 op_sel_hi:[0,0,0]
	v_mfma_scale_f32_16x16x128_f8f6f4 v[108:111], v[166:173], v[174:181], v[108:111], v140, v140 op_sel_hi:[0,0,0]
	v_mfma_scale_f32_16x16x128_f8f6f4 v[100:103], v[158:165], v[182:189], v[100:103], v140, v140 op_sel_hi:[0,0,0]
	v_mfma_scale_f32_16x16x128_f8f6f4 v[174:177], v[166:173], v[182:189], v[92:95], v140, v140 op_sel_hi:[0,0,0]
	v_mfma_scale_f32_16x16x128_f8f6f4 v[178:181], v[158:165], v[190:197], v[84:87], v140, v140 op_sel_hi:[0,0,0]
	v_mfma_scale_f32_16x16x128_f8f6f4 v[182:185], v[166:173], v[190:197], v[76:79], v140, v140 op_sel_hi:[0,0,0]
	v_mfma_scale_f32_16x16x128_f8f6f4 v[186:189], v[158:165], v[198:205], v[68:71], v140, v140 op_sel_hi:[0,0,0]
	v_mfma_scale_f32_16x16x128_f8f6f4 v[190:193], v[166:173], v[198:205], v[64:67], v140, v140 op_sel_hi:[0,0,0]
	s_barrier
	s_setprio 0
	s_add_i32 s63, s53, s41
	s_mov_b32 m0, s63
	s_nop 1
	ds_read_b128 v[64:67], v139 offset:16384
	ds_read_b128 v[68:71], v139 offset:17408
	ds_read_b128 v[72:75], v139 offset:18432
	ds_read_b128 v[76:79], v139 offset:19456
	ds_read_b128 v[80:83], v139 offset:20480
	ds_read_b128 v[84:87], v139 offset:21504
	ds_read_b128 v[88:91], v139 offset:22528

; #define PG8_WAIT_V(n) asm volatile("s_waitcnt vmcnt(" #n ")" ::: "memory")
; #define PG8_WAIT_L(n) asm volatile("s_waitcnt lgkmcnt(" #n ")" ::: "memory")
; #define PG8_BAR __builtin_amdgcn_s_barrier()
; #define PG8_SCHED __builtin_amdgcn_sched_barrier(0)
;     ...
;             if constexpr (!HALFU) PG8_LDA(At, 0, 1); PG8_STAGE(PG8_SB(0, 0), b2, voffB); PG8_STAGE(PG8_SB(0, 1), b2 + hstep, voffB); PG8_STAGE(PG8_SA(0, 0), a2, voffA);
;             PG8_WAIT_V(8); PG8_WAIT_L(0); PG8_BAR; if constexpr (!HALFU) { PG8_MMA(1, 0, At, B0); PG8_MMA(1, 1, At, B1); } PG8_BAR; PG8_SCHED;
;             PG8_LDB(B0, 1, 0); PG8_LDB(B1, 1, 1); PG8_SCHED; PG8_LDA(At, 1, 0); PG8_STAGE(PG8_SA(0, 1), a2 + hstepA, voffA);
	global_load_lds_dwordx4 v128, s[36:37]
	s_add_i32 m0, s63, 0x2000
	s_add_u32 s64, s36, 0x80000
	s_addc_u32 s65, s37, 0
	s_add_i32 s63, s54, s41
	global_load_lds_dwordx4 v130, s[36:37]
	s_mov_b32 m0, s63
	ds_read_b128 v[92:95], v139 offset:23552
	global_load_lds_dwordx4 v128, s[64:65]
	s_add_i32 m0, s63, 0x2000
	s_nop 0
	global_load_lds_dwordx4 v130, s[64:65]
	s_waitcnt vmcnt(4)
	s_waitcnt lgkmcnt(0)
	s_setprio 1
	s_barrier
	v_mfma_scale_f32_16x16x128_f8f6f4 v[60:63], v[142:149], v[64:71], v[60:63], v140, v140 op_sel_hi:[0,0,0]
	v_mfma_scale_f32_16x16x128_f8f6f4 v[56:59], v[150:157], v[64:71], v[56:59], v140, v140 op_sel_hi:[0,0,0]
	v_mfma_scale_f32_16x16x128_f8f6f4 v[48:51], v[142:149], v[72:79], v[48:51], v140, v140 op_sel_hi:[0,0,0]
	v_mfma_scale_f32_16x16x128_f8f6f4 v[194:197], v[150:157], v[72:79], v[40:43], v140, v140 op_sel_hi:[0,0,0]
	v_mfma_scale_f32_16x16x128_f8f6f4 v[198:201], v[142:149], v[80:87], v[32:35], v140, v140 op_sel_hi:[0,0,0]
	v_mfma_scale_f32_16x16x128_f8f6f4 v[202:205], v[150:157], v[80:87], v[24:27], v140, v140 op_sel_hi:[0,0,0]
	v_mfma_scale_f32_16x16x128_f8f6f4 v[218:221], v[142:149], v[88:95], v[16:19], v140, v140 op_sel_hi:[0,0,0]
	v_mfma_scale_f32_16x16x128_f8f6f4 v[222:225], v[150:157], v[88:95], v[8:11], v140, v140 op_sel_hi:[0,0,0]
	v_mfma_scale_f32_16x16x128_f8f6f4 v[52:55], v[158:165], v[64:71], v[52:55], v140, v140 op_sel_hi:[0,0,0]
	v_mfma_scale_f32_16x16x128_f8f6f4 v[226:229], v[166:173], v[64:71], v[44:47], v140, v140 op_sel_hi:[0,0,0]
	v_mfma_scale_f32_16x16x128_f8f6f4 v[230:233], v[158:165], v[72:79], v[36:39], v140, v140 op_sel_hi:[0,0,0]
	v_mfma_scale_f32_16x16x128_f8f6f4 v[234:237], v[166:173], v[72:79], v[28:31], v140, v140 op_sel_hi:[0,0,0]
	v_mfma_scale_f32_16x16x128_f8f6f4 v[238:241], v[158:165], v[80:87], v[20:23], v140, v140 op_sel_hi:[0,0,0]
	v_mfma_scale_f32_16x16x128_f8f6f4 v[242:245], v[166:173], v[80:87], v[12:15], v140, v140 op_sel_hi:[0,0,0]
	v_mfma_scale_f32_16x16x128_f8f6f4 v[246:249], v[158:165], v[88:95], v[4:7], v140, v140 op_sel_hi:[0,0,0]
	v_mfma_scale_f32_16x16x128_f8f6f4 v[250:253], v[166:173], v[88:95], v[0:3], v140, v140 op_sel_hi:[0,0,0]
	s_barrier
	s_setprio 0
	s_mov_b32 m0, s43
	s_nop 0
	global_load_lds_dwordx4 v128, s[38:39]
	s_mov_b32 m0, s44
	s_nop 0
	global_load_lds_dwordx4 v130, s[38:39]
	s_add_i32 s63, 0, 0x18000
	s_add_i32 s64, 0, 0x1c000
	s_nop 0
	v_add_u32_e32 v12, s63, v136
	v_add_u32_e32 v16, s64, v136
	ds_read_b128 v[0:3], v12
	ds_read_b128 v[4:7], v12 offset:1024
	ds_read_b128 v[8:11], v12 offset:2048
	ds_read_b128 v[12:15], v12 offset:3072
	ds_read_b128 v[142:145], v16
	ds_read_b128 v[146:149], v16 offset:1024
	ds_read_b128 v[150:153], v16 offset:2048
	ds_read_b128 v[154:157], v16 offset:3072
	s_add_u32 s38, s38, 0x80000
	s_addc_u32 s39, s39, 0
	s_mov_b32 m0, s45
	ds_read_b128 v[16:19], v139 offset:32768
	ds_read_b128 v[20:23], v139 offset:33792
	ds_read_b128 v[24:27], v139 offset:34816
	ds_read_b128 v[28:31], v139 offset:35840
	ds_read_b128 v[32:35], v139 offset:36864
	ds_read_b128 v[36:39], v139 offset:37888
	ds_read_b128 v[40:43], v139 offset:38912

; #define PG8_WAIT_V(n) asm volatile("s_waitcnt vmcnt(" #n ")" ::: "memory")
; #define PG8_WAIT_L(n) asm volatile("s_waitcnt lgkmcnt(" #n ")" ::: "memory")
; #define PG8_BAR __builtin_amdgcn_s_barrier()
; #define PG8_SCHED __builtin_amdgcn_sched_barrier(0)
;     ...
;             PG8_LDB(B0, 1, 0); PG8_LDB(B1, 1, 1); PG8_SCHED; PG8_LDA(At, 1, 0); PG8_STAGE(PG8_SA(0, 1), a2 + hstepA, voffA);
;             PG8_WAIT_V(8); PG8_WAIT_L(0); PG8_BAR; PG8_MMA(0, 0, At, B0); PG8_MMA(0, 1, At, B1); PG8_BAR; PG8_SCHED;
;             if constexpr (!HALFU) PG8_LDA(At, 1, 1); PG8_STAGE(PG8_SB(1, 0), b3, voffB); PG8_STAGE(PG8_SB(1, 1), b3 + hstep, voffB); PG8_STAGE(PG8_SA(1, 0), a3, voffA);
	global_load_lds_dwordx4 v128, s[38:39]
	s_mov_b32 m0, s46
	ds_read_b128 v[44:47], v139 offset:39936
	global_load_lds_dwordx4 v130, s[38:39]
	s_waitcnt vmcnt(8)
	s_waitcnt lgkmcnt(0)
	s_setprio 1
	s_barrier
	v_mfma_scale_f32_16x16x128_f8f6f4 v[124:127], v[0:7], v[16:23], v[124:127], v140, v140 op_sel_hi:[0,0,0]
	v_mfma_scale_f32_16x16x128_f8f6f4 v[120:123], v[8:15], v[16:23], v[120:123], v140, v140 op_sel_hi:[0,0,0]
	v_mfma_scale_f32_16x16x128_f8f6f4 v[112:115], v[0:7], v[24:31], v[112:115], v140, v140 op_sel_hi:[0,0,0]
	v_mfma_scale_f32_16x16x128_f8f6f4 v[104:107], v[8:15], v[24:31], v[104:107], v140, v140 op_sel_hi:[0,0,0]
	v_mfma_scale_f32_16x16x128_f8f6f4 v[96:99], v[0:7], v[32:39], v[96:99], v140, v140 op_sel_hi:[0,0,0]
	v_mfma_scale_f32_16x16x128_f8f6f4 v[88:91], v[8:15], v[32:39], v[206:209], v140, v140 op_sel_hi:[0,0,0]
	v_mfma_scale_f32_16x16x128_f8f6f4 v[80:83], v[0:7], v[40:47], v[210:213], v140, v140 op_sel_hi:[0,0,0]
	v_mfma_scale_f32_16x16x128_f8f6f4 v[72:75], v[8:15], v[40:47], v[214:217], v140, v140 op_sel_hi:[0,0,0]
	v_mfma_scale_f32_16x16x128_f8f6f4 v[116:119], v[142:149], v[16:23], v[116:119], v140, v140 op_sel_hi:[0,0,0]
	v_mfma_scale_f32_16x16x128_f8f6f4 v[108:111], v[150:157], v[16:23], v[108:111], v140, v140 op_sel_hi:[0,0,0]
	v_mfma_scale_f32_16x16x128_f8f6f4 v[100:103], v[142:149], v[24:31], v[100:103], v140, v140 op_sel_hi:[0,0,0]
	v_mfma_scale_f32_16x16x128_f8f6f4 v[92:95], v[150:157], v[24:31], v[174:177], v140, v140 op_sel_hi:[0,0,0]
	v_mfma_scale_f32_16x16x128_f8f6f4 v[84:87], v[142:149], v[32:39], v[178:181], v140, v140 op_sel_hi:[0,0,0]
	v_mfma_scale_f32_16x16x128_f8f6f4 v[76:79], v[150:157], v[32:39], v[182:185], v140, v140 op_sel_hi:[0,0,0]
	v_mfma_scale_f32_16x16x128_f8f6f4 v[68:71], v[142:149], v[40:47], v[186:189], v140, v140 op_sel_hi:[0,0,0]
	v_mfma_scale_f32_16x16x128_f8f6f4 v[64:67], v[150:157], v[40:47], v[190:193], v140, v140 op_sel_hi:[0,0,0]
	s_barrier
	s_setprio 0
	s_add_u32 s38, s36, 0x80
	s_addc_u32 s39, s37, 0
	s_add_i32 s63, s63, s41
	s_mov_b32 m0, s63
	ds_read_b128 v[158:161], v139 offset:49152
	ds_read_b128 v[162:165], v139 offset:50176
	ds_read_b128 v[166:169], v139 offset:51200
	ds_read_b128 v[170:173], v139 offset:52224
	ds_read_b128 v[174:177], v139 offset:53248
	ds_read_b128 v[178:181], v139 offset:54272
	ds_read_b128 v[182:185], v139 offset:55296

; #define PG8_WAIT_V(n) asm volatile("s_waitcnt vmcnt(" #n ")" ::: "memory")
; #define PG8_WAIT_L(n) asm volatile("s_waitcnt lgkmcnt(" #n ")" ::: "memory")
; #define PG8_BAR __builtin_amdgcn_s_barrier()
; #define PG8_SCHED __builtin_amdgcn_sched_barrier(0)
;     ...
;             if constexpr (!HALFU) PG8_LDA(At, 1, 1); PG8_STAGE(PG8_SB(1, 0), b3, voffB); PG8_STAGE(PG8_SB(1, 1), b3 + hstep, voffB); PG8_STAGE(PG8_SA(1, 0), a3, voffA);
;             PG8_WAIT_V(8); PG8_WAIT_L(0); PG8_BAR; if constexpr (!HALFU) { PG8_MMA(1, 0, At, B0); PG8_MMA(1, 1, At, B1); } PG8_BAR; PG8_SCHED;
;     ...
;         if constexpr (ALIGN_EPI) { if (wr == 0) PG8_BAR; }
	global_load_lds_dwordx4 v128, s[38:39]
	s_add_i32 m0, s63, 0x2000
	s_add_u32 s36, s36, 0x80080
	v_lshl_add_u64 v[16:17], s[38:39], 0, v[130:131]
	s_addc_u32 s37, s37, 0
	s_add_i32 s38, s64, s41
	global_load_lds_dwordx4 v[16:17], off
	s_mov_b32 m0, s38
	ds_read_b128 v[186:189], v139 offset:56320
	global_load_lds_dwordx4 v128, s[36:37]
	s_add_i32 m0, s38, 0x2000
	s_nop 0
	global_load_lds_dwordx4 v130, s[36:37]
	s_waitcnt vmcnt(4)
	s_waitcnt lgkmcnt(0)
	s_setprio 1
	s_barrier
	v_mfma_scale_f32_16x16x128_f8f6f4 v[60:63], v[0:7], v[158:165], v[60:63], v140, v140 op_sel_hi:[0,0,0]
	v_mfma_scale_f32_16x16x128_f8f6f4 v[56:59], v[8:15], v[158:165], v[56:59], v140, v140 op_sel_hi:[0,0,0]
	v_mfma_scale_f32_16x16x128_f8f6f4 v[48:51], v[0:7], v[166:173], v[48:51], v140, v140 op_sel_hi:[0,0,0]
	v_mfma_scale_f32_16x16x128_f8f6f4 v[40:43], v[8:15], v[166:173], v[194:197], v140, v140 op_sel_hi:[0,0,0]
	v_mfma_scale_f32_16x16x128_f8f6f4 v[32:35], v[0:7], v[174:181], v[198:201], v140, v140 op_sel_hi:[0,0,0]
	v_mfma_scale_f32_16x16x128_f8f6f4 v[24:27], v[8:15], v[174:181], v[202:205], v140, v140 op_sel_hi:[0,0,0]
	v_mfma_scale_f32_16x16x128_f8f6f4 v[16:19], v[0:7], v[182:189], v[218:221], v140, v140 op_sel_hi:[0,0,0]
	v_mfma_scale_f32_16x16x128_f8f6f4 v[8:11], v[8:15], v[182:189], v[222:225], v140, v140 op_sel_hi:[0,0,0]
	v_mfma_scale_f32_16x16x128_f8f6f4 v[52:55], v[142:149], v[158:165], v[52:55], v140, v140 op_sel_hi:[0,0,0]
	v_mfma_scale_f32_16x16x128_f8f6f4 v[44:47], v[150:157], v[158:165], v[226:229], v140, v140 op_sel_hi:[0,0,0]
	v_mfma_scale_f32_16x16x128_f8f6f4 v[36:39], v[142:149], v[166:173], v[230:233], v140, v140 op_sel_hi:[0,0,0]
	v_mfma_scale_f32_16x16x128_f8f6f4 v[28:31], v[150:157], v[166:173], v[234:237], v140, v140 op_sel_hi:[0,0,0]
	v_mfma_scale_f32_16x16x128_f8f6f4 v[20:23], v[142:149], v[174:181], v[238:241], v140, v140 op_sel_hi:[0,0,0]
	v_mfma_scale_f32_16x16x128_f8f6f4 v[12:15], v[150:157], v[174:181], v[242:245], v140, v140 op_sel_hi:[0,0,0]
	v_mfma_scale_f32_16x16x128_f8f6f4 v[4:7], v[142:149], v[182:189], v[246:249], v140, v140 op_sel_hi:[0,0,0]
	v_mfma_scale_f32_16x16x128_f8f6f4 v[0:3], v[150:157], v[182:189], v[250:253], v140, v140 op_sel_hi:[0,0,0]
	s_barrier
	s_setprio 0
	s_add_i32 s62, s62, 2
	s_add_u32 s57, s57, 0x100
	s_addc_u32 s59, s59, 0
	s_add_u32 s60, s60, 0x100
	s_addc_u32 s61, s61, 0
	s_add_u32 s28, s28, 0x100
	s_addc_u32 s29, s29, 0
	s_cmp_gt_u32 s62, 29
	s_cbranch_scc0 .LBB0_3426
	s_and_b64 vcc, exec, s[6:7]
	s_cbranch_vccz .LBB0_3429
	s_barrier

; #define PG8_SCHED __builtin_amdgcn_sched_barrier(0)
;     ...
;         for (int t = 0; t < nt; t += 2) {
;             const bool last = (t == nt - 2);
;             const char* a1 = cA + (size_t)(t + 1) * kstep;
;             const char* a2 = last ? nA : cA + (size_t)(t + 2) * kstep; const char* b2 = last ? nB : cB + (size_t)(t + 2) * kstep;
;             const char* a3 = a2 + kstep; const char* b3 = b2 + kstep;
;             if (last && has_next) S.a_ready(nxt);
;             if constexpr (SP2) {
;             PG8_LDB(B0, 0, 0); PG8_LDB(B1, 0, 1); PG8_SCHED; PG8_LDA(At, 0, 0); PG8_STAGE(PG8_SA(1, 1), a1 + hstepA, voffA);
.LBB0_3554:
	s_add_u32 s98, s24, 0x80
	s_addc_u32 s99, s25, 0
	s_mov_b32 m0, s49
	ds_read_b128 v[144:147], v141
	global_load_lds_dwordx4 v134, s[98:99]
	s_mov_b32 m0, s50
	ds_read_b128 v[148:151], v141 offset:1024
	global_load_lds_dwordx4 v132, s[98:99]


; #define PG8_SCHED __builtin_amdgcn_sched_barrier(0)
;     ...
;             const bool last = (t == nt - 2);
;             const char* a1 = cA + (size_t)(t + 1) * kstep;
;             const char* a2 = last ? nA : cA + (size_t)(t + 2) * kstep; const char* b2 = last ? nB : cB + (size_t)(t + 2) * kstep;
;             const char* a3 = a2 + kstep; const char* b3 = b2 + kstep;
;             if (last && has_next) S.a_ready(nxt);
;             if constexpr (SP2) {
;             PG8_LDB(B0, 0, 0); PG8_LDB(B1, 0, 1); PG8_SCHED; PG8_LDA(At, 0, 0); PG8_STAGE(PG8_SA(1, 1), a1 + hstepA, voffA);
	ds_read_b128 v[152:155], v141 offset:2048
	ds_read_b128 v[156:159], v141 offset:3072
	ds_read_b128 v[160:163], v142
	ds_read_b128 v[164:167], v142 offset:1024
	ds_read_b128 v[168:171], v142 offset:2048
	ds_read_b128 v[172:175], v142 offset:3072
	s_add_u32 s26, s24, 0x100
	s_addc_u32 s27, s25, 0
	s_cmp_eq_u32 s59, 60
	s_cselect_b32 s36, s54, s26
	s_cselect_b32 s37, s15, s27
	s_cselect_b32 s30, s55, s56
	s_cselect_b32 s31, s13, s57
	s_add_u32 s28, s36, 0x80
	s_addc_u32 s29, s37, 0
	s_add_u32 s24, s24, 0x100080
	s_addc_u32 s25, s25, 0
	s_add_i32 m0, s23, 0xc000
	ds_read_b128 v[176:179], v143
	ds_read_b128 v[180:183], v143 offset:1024
	ds_read_b128 v[184:187], v143 offset:2048
	ds_read_b128 v[188:191], v143 offset:3072
	ds_read_b128 v[192:195], v143 offset:4096
	ds_read_b128 v[196:199], v143 offset:5120
	ds_read_b128 v[200:203], v143 offset:6144

; #define PG8_WAIT_V(n) asm volatile("s_waitcnt vmcnt(" #n ")" ::: "memory")
; #define PG8_WAIT_L(n) asm volatile("s_waitcnt lgkmcnt(" #n ")" ::: "memory")
; #define PG8_BAR __builtin_amdgcn_s_barrier()
; #define PG8_SCHED __builtin_amdgcn_sched_barrier(0)
;     ...
;             PG8_LDB(B0, 0, 0); PG8_LDB(B1, 0, 1); PG8_SCHED; PG8_LDA(At, 0, 0); PG8_STAGE(PG8_SA(1, 1), a1 + hstepA, voffA);
;             PG8_WAIT_V(8); PG8_WAIT_L(0); PG8_BAR; PG8_MMA(0, 0, At, B0); PG8_MMA(0, 1, At, B1); PG8_BAR; PG8_SCHED;
;             if constexpr (!HALFU) PG8_LDA(At, 0, 1); PG8_STAGE(PG8_SB(0, 0), b2, voffB); PG8_STAGE(PG8_SB(0, 1), b2 + hstep, voffB); PG8_STAGE(PG8_SA(0, 0), a2, voffA);
	global_load_lds_dwordx4 v134, s[24:25]
	s_add_i32 m0, s23, 0xe000
	ds_read_b128 v[204:207], v143 offset:7168
	global_load_lds_dwordx4 v132, s[24:25]
	s_waitcnt vmcnt(8)
	s_waitcnt lgkmcnt(0)
	s_setprio 1
	s_barrier
	v_mfma_f32_16x16x32_bf16 v[124:127], v[144:147], v[176:179], v[124:127]
	v_mfma_f32_16x16x32_bf16 v[120:123], v[152:155], v[176:179], v[120:123]
	v_mfma_f32_16x16x32_bf16 v[108:111], v[144:147], v[184:187], v[108:111]
	v_mfma_f32_16x16x32_bf16 v[104:107], v[152:155], v[184:187], v[104:107]
	v_mfma_f32_16x16x32_bf16 v[92:95], v[144:147], v[192:195], v[92:95]
	v_mfma_f32_16x16x32_bf16 v[88:91], v[152:155], v[192:195], v[88:91]
	v_mfma_f32_16x16x32_bf16 v[76:79], v[144:147], v[200:203], v[76:79]
	v_mfma_f32_16x16x32_bf16 v[72:75], v[152:155], v[200:203], v[72:75]
	v_mfma_f32_16x16x32_bf16 v[124:127], v[148:151], v[180:183], v[124:127]
	v_mfma_f32_16x16x32_bf16 v[120:123], v[156:159], v[180:183], v[120:123]
	v_mfma_f32_16x16x32_bf16 v[108:111], v[148:151], v[188:191], v[108:111]
	v_mfma_f32_16x16x32_bf16 v[104:107], v[156:159], v[188:191], v[104:107]
	v_mfma_f32_16x16x32_bf16 v[92:95], v[148:151], v[196:199], v[92:95]
	v_mfma_f32_16x16x32_bf16 v[88:91], v[156:159], v[196:199], v[88:91]
	v_mfma_f32_16x16x32_bf16 v[76:79], v[148:151], v[204:207], v[76:79]
	v_mfma_f32_16x16x32_bf16 v[72:75], v[156:159], v[204:207], v[72:75]
	v_mfma_f32_16x16x32_bf16 v[116:119], v[160:163], v[176:179], v[116:119]
	v_mfma_f32_16x16x32_bf16 v[112:115], v[168:171], v[176:179], v[112:115]
	v_mfma_f32_16x16x32_bf16 v[100:103], v[160:163], v[184:187], v[100:103]
	v_mfma_f32_16x16x32_bf16 v[96:99], v[168:171], v[184:187], v[96:99]
	v_mfma_f32_16x16x32_bf16 v[84:87], v[160:163], v[192:195], v[84:87]
	v_mfma_f32_16x16x32_bf16 v[80:83], v[168:171], v[192:195], v[80:83]
	v_mfma_f32_16x16x32_bf16 v[68:71], v[160:163], v[200:203], v[68:71]
	v_mfma_f32_16x16x32_bf16 v[64:67], v[168:171], v[200:203], v[64:67]
	v_mfma_f32_16x16x32_bf16 v[116:119], v[164:167], v[180:183], v[116:119]
	v_mfma_f32_16x16x32_bf16 v[112:115], v[172:175], v[180:183], v[112:115]
	v_mfma_f32_16x16x32_bf16 v[100:103], v[164:167], v[188:191], v[100:103]
	v_mfma_f32_16x16x32_bf16 v[96:99], v[172:175], v[188:191], v[96:99]
	v_mfma_f32_16x16x32_bf16 v[84:87], v[164:167], v[196:199], v[84:87]
	v_mfma_f32_16x16x32_bf16 v[80:83], v[172:175], v[196:199], v[80:83]
	v_mfma_f32_16x16x32_bf16 v[68:71], v[164:167], v[204:207], v[68:71]
	v_mfma_f32_16x16x32_bf16 v[64:67], v[172:175], v[204:207], v[64:67]
	s_barrier
	s_setprio 0
	s_add_i32 s24, s6, s40
	s_mov_b32 m0, s24
	ds_read_b128 v[176:179], v143 offset:16384
	ds_read_b128 v[180:183], v143 offset:17408
	ds_read_b128 v[184:187], v143 offset:18432
	ds_read_b128 v[188:191], v143 offset:19456
	ds_read_b128 v[192:195], v143 offset:20480
	ds_read_b128 v[196:199], v143 offset:21504
	ds_read_b128 v[200:203], v143 offset:22528

; #define PG8_WAIT_V(n) asm volatile("s_waitcnt vmcnt(" #n ")" ::: "memory")
; #define PG8_WAIT_L(n) asm volatile("s_waitcnt lgkmcnt(" #n ")" ::: "memory")
; #define PG8_BAR __builtin_amdgcn_s_barrier()
; #define PG8_SCHED __builtin_amdgcn_sched_barrier(0)
;     ...
;             if constexpr (!HALFU) PG8_LDA(At, 0, 1); PG8_STAGE(PG8_SB(0, 0), b2, voffB); PG8_STAGE(PG8_SB(0, 1), b2 + hstep, voffB); PG8_STAGE(PG8_SA(0, 0), a2, voffA);
;             PG8_WAIT_V(8); PG8_WAIT_L(0); PG8_BAR; if constexpr (!HALFU) { PG8_MMA(1, 0, At, B0); PG8_MMA(1, 1, At, B1); } PG8_BAR; PG8_SCHED;
;             PG8_LDB(B0, 1, 0); PG8_LDB(B1, 1, 1); PG8_SCHED; PG8_LDA(At, 1, 0); PG8_STAGE(PG8_SA(0, 1), a2 + hstepA, voffA);
	global_load_lds_dwordx4 v128, s[30:31]
	s_add_i32 m0, s24, 0x2000
	s_add_u32 s24, s30, 0x100000
	s_addc_u32 s25, s31, 0
	s_add_i32 s60, s51, s40
	global_load_lds_dwordx4 v130, s[30:31]
	s_mov_b32 m0, s60
	ds_read_b128 v[204:207], v143 offset:23552
	global_load_lds_dwordx4 v128, s[24:25]
	s_add_i32 m0, s60, 0x2000
	s_nop 0
	global_load_lds_dwordx4 v130, s[24:25]
	s_waitcnt vmcnt(4)
	s_waitcnt lgkmcnt(0)
	s_setprio 1
	s_barrier
	v_mfma_f32_16x16x32_bf16 v[60:63], v[144:147], v[176:179], v[60:63]
	v_mfma_f32_16x16x32_bf16 v[56:59], v[152:155], v[176:179], v[56:59]
	v_mfma_f32_16x16x32_bf16 v[44:47], v[144:147], v[184:187], v[44:47]
	v_mfma_f32_16x16x32_bf16 v[40:43], v[152:155], v[184:187], v[40:43]
	v_mfma_f32_16x16x32_bf16 v[28:31], v[144:147], v[192:195], v[28:31]
	v_mfma_f32_16x16x32_bf16 v[24:27], v[152:155], v[192:195], v[24:27]
	v_mfma_f32_16x16x32_bf16 v[12:15], v[144:147], v[200:203], v[12:15]
	v_mfma_f32_16x16x32_bf16 v[8:11], v[152:155], v[200:203], v[8:11]
	v_mfma_f32_16x16x32_bf16 v[60:63], v[148:151], v[180:183], v[60:63]
	v_mfma_f32_16x16x32_bf16 v[56:59], v[156:159], v[180:183], v[56:59]
	v_mfma_f32_16x16x32_bf16 v[44:47], v[148:151], v[188:191], v[44:47]
	v_mfma_f32_16x16x32_bf16 v[40:43], v[156:159], v[188:191], v[40:43]
	v_mfma_f32_16x16x32_bf16 v[28:31], v[148:151], v[196:199], v[28:31]
	v_mfma_f32_16x16x32_bf16 v[24:27], v[156:159], v[196:199], v[24:27]
	v_mfma_f32_16x16x32_bf16 v[12:15], v[148:151], v[204:207], v[12:15]
	v_mfma_f32_16x16x32_bf16 v[8:11], v[156:159], v[204:207], v[8:11]
	v_mfma_f32_16x16x32_bf16 v[52:55], v[160:163], v[176:179], v[52:55]
	v_mfma_f32_16x16x32_bf16 v[48:51], v[168:171], v[176:179], v[48:51]
	v_mfma_f32_16x16x32_bf16 v[36:39], v[160:163], v[184:187], v[36:39]
	v_mfma_f32_16x16x32_bf16 v[32:35], v[168:171], v[184:187], v[32:35]
	v_mfma_f32_16x16x32_bf16 v[20:23], v[160:163], v[192:195], v[20:23]
	v_mfma_f32_16x16x32_bf16 v[16:19], v[168:171], v[192:195], v[16:19]
	v_mfma_f32_16x16x32_bf16 v[4:7], v[160:163], v[200:203], v[4:7]
	v_mfma_f32_16x16x32_bf16 v[0:3], v[168:171], v[200:203], v[0:3]
	v_mfma_f32_16x16x32_bf16 v[52:55], v[164:167], v[180:183], v[52:55]
	v_mfma_f32_16x16x32_bf16 v[48:51], v[172:175], v[180:183], v[48:51]
	v_mfma_f32_16x16x32_bf16 v[36:39], v[164:167], v[188:191], v[36:39]
	v_mfma_f32_16x16x32_bf16 v[32:35], v[172:175], v[188:191], v[32:35]
	v_mfma_f32_16x16x32_bf16 v[20:23], v[164:167], v[196:199], v[20:23]
	v_mfma_f32_16x16x32_bf16 v[16:19], v[172:175], v[196:199], v[16:19]
	v_mfma_f32_16x16x32_bf16 v[4:7], v[164:167], v[204:207], v[4:7]
	v_mfma_f32_16x16x32_bf16 v[0:3], v[172:175], v[204:207], v[0:3]
	s_barrier
	s_setprio 0
	s_mov_b32 m0, s23
	ds_read_b128 v[176:179], v143 offset:32768
	global_load_lds_dwordx4 v134, s[36:37]
	s_mov_b32 m0, s43
	ds_read_b128 v[180:183], v143 offset:33792
	global_load_lds_dwordx4 v132, s[36:37]
	s_add_i32 s60, 0, 0x18000
	v_add_u32_e32 v138, s60, v140
	s_add_i32 s61, 0, 0x1c000
	ds_read_b128 v[144:147], v138
	ds_read_b128 v[148:151], v138 offset:1024
	ds_read_b128 v[152:155], v138 offset:2048
	ds_read_b128 v[156:159], v138 offset:3072
	v_add_u32_e32 v138, s61, v140
	ds_read_b128 v[160:163], v138
	ds_read_b128 v[164:167], v138 offset:1024
	ds_read_b128 v[168:171], v138 offset:2048
	ds_read_b128 v[172:175], v138 offset:3072
	s_add_u32 s24, s36, 0x100000
	s_addc_u32 s25, s37, 0
	s_mov_b32 m0, s44


; #define PG8_SCHED __builtin_amdgcn_sched_barrier(0)
;     ...
;             PG8_LDB(B0, 1, 0); PG8_LDB(B1, 1, 1); PG8_SCHED; PG8_LDA(At, 1, 0); PG8_STAGE(PG8_SA(0, 1), a2 + hstepA, voffA);
	ds_read_b128 v[184:187], v143 offset:34816
	ds_read_b128 v[188:191], v143 offset:35840
	ds_read_b128 v[192:195], v143 offset:36864
	ds_read_b128 v[196:199], v143 offset:37888
	ds_read_b128 v[200:203], v143 offset:38912

; #define PG8_WAIT_V(n) asm volatile("s_waitcnt vmcnt(" #n ")" ::: "memory")
; #define PG8_WAIT_L(n) asm volatile("s_waitcnt lgkmcnt(" #n ")" ::: "memory")
; #define PG8_BAR __builtin_amdgcn_s_barrier()
; #define PG8_SCHED __builtin_amdgcn_sched_barrier(0)
;     ...
;             PG8_LDB(B0, 1, 0); PG8_LDB(B1, 1, 1); PG8_SCHED; PG8_LDA(At, 1, 0); PG8_STAGE(PG8_SA(0, 1), a2 + hstepA, voffA);
;             PG8_WAIT_V(8); PG8_WAIT_L(0); PG8_BAR; PG8_MMA(0, 0, At, B0); PG8_MMA(0, 1, At, B1); PG8_BAR; PG8_SCHED;
;             if constexpr (!HALFU) PG8_LDA(At, 1, 1); PG8_STAGE(PG8_SB(1, 0), b3, voffB); PG8_STAGE(PG8_SB(1, 1), b3 + hstep, voffB); PG8_STAGE(PG8_SA(1, 0), a3, voffA);
	global_load_lds_dwordx4 v134, s[24:25]
	s_mov_b32 m0, s45
	ds_read_b128 v[204:207], v143 offset:39936
	global_load_lds_dwordx4 v132, s[24:25]
	s_waitcnt vmcnt(8)
	s_waitcnt lgkmcnt(0)
	s_setprio 1
	s_barrier
	v_mfma_f32_16x16x32_bf16 v[124:127], v[144:147], v[176:179], v[124:127]
	v_mfma_f32_16x16x32_bf16 v[120:123], v[152:155], v[176:179], v[120:123]
	v_mfma_f32_16x16x32_bf16 v[108:111], v[144:147], v[184:187], v[108:111]
	v_mfma_f32_16x16x32_bf16 v[104:107], v[152:155], v[184:187], v[104:107]
	v_mfma_f32_16x16x32_bf16 v[92:95], v[144:147], v[192:195], v[92:95]
	v_mfma_f32_16x16x32_bf16 v[88:91], v[152:155], v[192:195], v[88:91]
	v_mfma_f32_16x16x32_bf16 v[76:79], v[144:147], v[200:203], v[76:79]
	v_mfma_f32_16x16x32_bf16 v[72:75], v[152:155], v[200:203], v[72:75]
	v_mfma_f32_16x16x32_bf16 v[124:127], v[148:151], v[180:183], v[124:127]
	v_mfma_f32_16x16x32_bf16 v[120:123], v[156:159], v[180:183], v[120:123]
	v_mfma_f32_16x16x32_bf16 v[108:111], v[148:151], v[188:191], v[108:111]
	v_mfma_f32_16x16x32_bf16 v[104:107], v[156:159], v[188:191], v[104:107]
	v_mfma_f32_16x16x32_bf16 v[92:95], v[148:151], v[196:199], v[92:95]
	v_mfma_f32_16x16x32_bf16 v[88:91], v[156:159], v[196:199], v[88:91]
	v_mfma_f32_16x16x32_bf16 v[76:79], v[148:151], v[204:207], v[76:79]
	v_mfma_f32_16x16x32_bf16 v[72:75], v[156:159], v[204:207], v[72:75]
	v_mfma_f32_16x16x32_bf16 v[116:119], v[160:163], v[176:179], v[116:119]
	v_mfma_f32_16x16x32_bf16 v[112:115], v[168:171], v[176:179], v[112:115]
	v_mfma_f32_16x16x32_bf16 v[100:103], v[160:163], v[184:187], v[100:103]
	v_mfma_f32_16x16x32_bf16 v[96:99], v[168:171], v[184:187], v[96:99]
	v_mfma_f32_16x16x32_bf16 v[84:87], v[160:163], v[192:195], v[84:87]
	v_mfma_f32_16x16x32_bf16 v[80:83], v[168:171], v[192:195], v[80:83]
	v_mfma_f32_16x16x32_bf16 v[68:71], v[160:163], v[200:203], v[68:71]
	v_mfma_f32_16x16x32_bf16 v[64:67], v[168:171], v[200:203], v[64:67]
	v_mfma_f32_16x16x32_bf16 v[116:119], v[164:167], v[180:183], v[116:119]
	v_mfma_f32_16x16x32_bf16 v[112:115], v[172:175], v[180:183], v[112:115]
	v_mfma_f32_16x16x32_bf16 v[100:103], v[164:167], v[188:191], v[100:103]
	v_mfma_f32_16x16x32_bf16 v[96:99], v[172:175], v[188:191], v[96:99]
	v_mfma_f32_16x16x32_bf16 v[84:87], v[164:167], v[196:199], v[84:87]
	v_mfma_f32_16x16x32_bf16 v[80:83], v[172:175], v[196:199], v[80:83]
	v_mfma_f32_16x16x32_bf16 v[68:71], v[164:167], v[204:207], v[68:71]
	v_mfma_f32_16x16x32_bf16 v[64:67], v[172:175], v[204:207], v[64:67]
	s_barrier
	s_setprio 0
	s_add_u32 s24, s30, 0x80
	s_addc_u32 s25, s31, 0
	s_add_i32 s36, s60, s40
	s_mov_b32 m0, s36
	ds_read_b128 v[176:179], v143 offset:49152
	ds_read_b128 v[180:183], v143 offset:50176
	ds_read_b128 v[184:187], v143 offset:51200
	ds_read_b128 v[188:191], v143 offset:52224
	ds_read_b128 v[192:195], v143 offset:53248
	ds_read_b128 v[196:199], v143 offset:54272
	ds_read_b128 v[200:203], v143 offset:55296

; #define PG8_WAIT_V(n) asm volatile("s_waitcnt vmcnt(" #n ")" ::: "memory")
; #define PG8_WAIT_L(n) asm volatile("s_waitcnt lgkmcnt(" #n ")" ::: "memory")
; #define PG8_BAR __builtin_amdgcn_s_barrier()
; #define PG8_SCHED __builtin_amdgcn_sched_barrier(0)
;     ...
;             if constexpr (!HALFU) PG8_LDA(At, 1, 1); PG8_STAGE(PG8_SB(1, 0), b3, voffB); PG8_STAGE(PG8_SB(1, 1), b3 + hstep, voffB); PG8_STAGE(PG8_SA(1, 0), a3, voffA);
;             PG8_WAIT_V(8); PG8_WAIT_L(0); PG8_BAR; if constexpr (!HALFU) { PG8_MMA(1, 0, At, B0); PG8_MMA(1, 1, At, B1); } PG8_BAR; PG8_SCHED;
;     ...
;         if constexpr (ALIGN_EPI) { if (wr == 0) PG8_BAR; }
	global_load_lds_dwordx4 v128, s[24:25]
	s_add_i32 m0, s36, 0x2000
	v_lshl_add_u64 v[138:139], s[24:25], 0, v[130:131]
	s_add_u32 s24, s30, 0x100080
	s_addc_u32 s25, s31, 0
	s_add_i32 s30, s61, s40
	global_load_lds_dwordx4 v[138:139], off
	s_mov_b32 m0, s30
	ds_read_b128 v[204:207], v143 offset:56320
	global_load_lds_dwordx4 v128, s[24:25]
	s_add_i32 m0, s30, 0x2000
	s_nop 0
	global_load_lds_dwordx4 v130, s[24:25]
	s_waitcnt vmcnt(4)
	s_waitcnt lgkmcnt(0)
	s_setprio 1
	s_barrier
	v_mfma_f32_16x16x32_bf16 v[60:63], v[144:147], v[176:179], v[60:63]
	v_mfma_f32_16x16x32_bf16 v[56:59], v[152:155], v[176:179], v[56:59]
	v_mfma_f32_16x16x32_bf16 v[44:47], v[144:147], v[184:187], v[44:47]
	v_mfma_f32_16x16x32_bf16 v[40:43], v[152:155], v[184:187], v[40:43]
	v_mfma_f32_16x16x32_bf16 v[28:31], v[144:147], v[192:195], v[28:31]
	v_mfma_f32_16x16x32_bf16 v[24:27], v[152:155], v[192:195], v[24:27]
	v_mfma_f32_16x16x32_bf16 v[12:15], v[144:147], v[200:203], v[12:15]
	v_mfma_f32_16x16x32_bf16 v[8:11], v[152:155], v[200:203], v[8:11]
	v_mfma_f32_16x16x32_bf16 v[60:63], v[148:151], v[180:183], v[60:63]
	v_mfma_f32_16x16x32_bf16 v[56:59], v[156:159], v[180:183], v[56:59]
	v_mfma_f32_16x16x32_bf16 v[44:47], v[148:151], v[188:191], v[44:47]
	v_mfma_f32_16x16x32_bf16 v[40:43], v[156:159], v[188:191], v[40:43]
	v_mfma_f32_16x16x32_bf16 v[28:31], v[148:151], v[196:199], v[28:31]
	v_mfma_f32_16x16x32_bf16 v[24:27], v[156:159], v[196:199], v[24:27]
	v_mfma_f32_16x16x32_bf16 v[12:15], v[148:151], v[204:207], v[12:15]
	v_mfma_f32_16x16x32_bf16 v[8:11], v[156:159], v[204:207], v[8:11]
	v_mfma_f32_16x16x32_bf16 v[52:55], v[160:163], v[176:179], v[52:55]
	v_mfma_f32_16x16x32_bf16 v[48:51], v[168:171], v[176:179], v[48:51]
	v_mfma_f32_16x16x32_bf16 v[36:39], v[160:163], v[184:187], v[36:39]
	v_mfma_f32_16x16x32_bf16 v[32:35], v[168:171], v[184:187], v[32:35]
	v_mfma_f32_16x16x32_bf16 v[20:23], v[160:163], v[192:195], v[20:23]
	v_mfma_f32_16x16x32_bf16 v[16:19], v[168:171], v[192:195], v[16:19]
	v_mfma_f32_16x16x32_bf16 v[4:7], v[160:163], v[200:203], v[4:7]
	v_mfma_f32_16x16x32_bf16 v[0:3], v[168:171], v[200:203], v[0:3]
	v_mfma_f32_16x16x32_bf16 v[52:55], v[164:167], v[180:183], v[52:55]
	v_mfma_f32_16x16x32_bf16 v[48:51], v[172:175], v[180:183], v[48:51]
	v_mfma_f32_16x16x32_bf16 v[36:39], v[164:167], v[188:191], v[36:39]
	v_mfma_f32_16x16x32_bf16 v[32:35], v[172:175], v[188:191], v[32:35]
	v_mfma_f32_16x16x32_bf16 v[20:23], v[164:167], v[196:199], v[20:23]
	v_mfma_f32_16x16x32_bf16 v[16:19], v[172:175], v[196:199], v[16:19]
	v_mfma_f32_16x16x32_bf16 v[4:7], v[164:167], v[204:207], v[4:7]
	v_mfma_f32_16x16x32_bf16 v[0:3], v[172:175], v[204:207], v[0:3]
	s_barrier
	s_setprio 0
	s_add_i32 s59, s59, 2
	s_add_u32 s56, s56, 0x100
	s_addc_u32 s57, s57, 0
	s_cmp_gt_u32 s59, 61
	s_mov_b64 s[24:25], s[26:27]
	s_cbranch_scc0 .LBB0_3554
	s_and_b64 vcc, exec, s[10:11]
	s_cbranch_vccz .LBB0_3557
	s_barrier

; #define PG8_SCHED __builtin_amdgcn_sched_barrier(0)
;     ...
;         for (int t = 0; t < nt; t += 2) {
;             const bool last = (t == nt - 2);
;             const char* a1 = cA + (size_t)(t + 1) * kstep;
;             const char* a2 = last ? nA : cA + (size_t)(t + 2) * kstep; const char* b2 = last ? nB : cB + (size_t)(t + 2) * kstep;
;             const char* a3 = a2 + kstep; const char* b3 = b2 + kstep;
;             if (last && has_next) S.a_ready(nxt);
;             if constexpr (SP2) {
;             PG8_LDB(B0, 0, 0); PG8_LDB(B1, 0, 1); PG8_SCHED; PG8_LDA(At, 0, 0); PG8_STAGE(PG8_SA(1, 1), a1 + hstepA, voffA);
.LBB0_3640:
	s_sub_u32 s98, s10, 0x158000
	s_subb_u32 s99, s11, 0
	s_mov_b32 m0, s42
	ds_read_b128 v[142:145], v137
	global_load_lds_dwordx4 v128, s[98:99]
	s_mov_b32 m0, s43
	ds_read_b128 v[146:149], v137 offset:1024
	global_load_lds_dwordx4 v130, s[98:99]


; #define PG8_SCHED __builtin_amdgcn_sched_barrier(0)
;     ...
;             const bool last = (t == nt - 2);
;             const char* a1 = cA + (size_t)(t + 1) * kstep;
;             const char* a2 = last ? nA : cA + (size_t)(t + 2) * kstep; const char* b2 = last ? nB : cB + (size_t)(t + 2) * kstep;
;             const char* a3 = a2 + kstep; const char* b3 = b2 + kstep;
;             if (last && has_next) S.a_ready(nxt);
;             if constexpr (SP2) {
;             PG8_LDB(B0, 0, 0); PG8_LDB(B1, 0, 1); PG8_SCHED; PG8_LDA(At, 0, 0); PG8_STAGE(PG8_SA(1, 1), a1 + hstepA, voffA);
	ds_read_b128 v[150:153], v137 offset:2048
	ds_read_b128 v[154:157], v137 offset:3072
	ds_read_b128 v[158:161], v138
	ds_read_b128 v[162:165], v138 offset:1024
	ds_read_b128 v[166:169], v138 offset:2048
	ds_read_b128 v[170:173], v138 offset:3072
	s_cmpk_eq_i32 s55, 0x52
	s_cselect_b32 s28, s6, s51
	s_cselect_b32 s29, s7, s52
	s_cselect_b32 s26, s22, s53
	s_cselect_b32 s27, s23, s54
	s_add_u32 s24, s28, 0x80
	s_addc_u32 s25, s29, 0
	s_add_i32 m0, s33, 0xc000
	ds_read_b128 v[174:177], v139
	ds_read_b128 v[178:181], v139 offset:1024
	ds_read_b128 v[182:185], v139 offset:2048
	ds_read_b128 v[186:189], v139 offset:3072
	ds_read_b128 v[190:193], v139 offset:4096
	ds_read_b128 v[194:197], v139 offset:5120
	ds_read_b128 v[198:201], v139 offset:6144

; #define PG8_WAIT_V(n) asm volatile("s_waitcnt vmcnt(" #n ")" ::: "memory")
; #define PG8_WAIT_L(n) asm volatile("s_waitcnt lgkmcnt(" #n ")" ::: "memory")
; #define PG8_BAR __builtin_amdgcn_s_barrier()
; #define PG8_SCHED __builtin_amdgcn_sched_barrier(0)
;     ...
;             PG8_LDB(B0, 0, 0); PG8_LDB(B1, 0, 1); PG8_SCHED; PG8_LDA(At, 0, 0); PG8_STAGE(PG8_SA(1, 1), a1 + hstepA, voffA);
;             PG8_WAIT_V(8); PG8_WAIT_L(0); PG8_BAR; PG8_MMA(0, 0, At, B0); PG8_MMA(0, 1, At, B1); PG8_BAR; PG8_SCHED;
;             if constexpr (!HALFU) PG8_LDA(At, 0, 1); PG8_STAGE(PG8_SB(0, 0), b2, voffB); PG8_STAGE(PG8_SB(0, 1), b2 + hstep, voffB); PG8_STAGE(PG8_SA(0, 0), a2, voffA);
	global_load_lds_dwordx4 v128, s[10:11]
	s_add_i32 m0, s33, 0xe000
	ds_read_b128 v[202:205], v139 offset:7168
	global_load_lds_dwordx4 v130, s[10:11]
	s_waitcnt vmcnt(8)
	s_waitcnt lgkmcnt(0)
	s_setprio 1
	s_barrier
	v_mfma_scale_f32_16x16x128_f8f6f4 v[124:127], v[142:149], v[174:181], v[124:127], v140, v140 op_sel_hi:[0,0,0]
	v_mfma_scale_f32_16x16x128_f8f6f4 v[120:123], v[150:157], v[174:181], v[120:123], v140, v140 op_sel_hi:[0,0,0]
	v_mfma_scale_f32_16x16x128_f8f6f4 v[112:115], v[142:149], v[182:189], v[112:115], v140, v140 op_sel_hi:[0,0,0]
	v_mfma_scale_f32_16x16x128_f8f6f4 v[104:107], v[150:157], v[182:189], v[104:107], v140, v140 op_sel_hi:[0,0,0]
	v_mfma_scale_f32_16x16x128_f8f6f4 v[96:99], v[142:149], v[190:197], v[96:99], v140, v140 op_sel_hi:[0,0,0]
	v_mfma_scale_f32_16x16x128_f8f6f4 v[206:209], v[150:157], v[190:197], v[88:91], v140, v140 op_sel_hi:[0,0,0]
	v_mfma_scale_f32_16x16x128_f8f6f4 v[210:213], v[142:149], v[198:205], v[80:83], v140, v140 op_sel_hi:[0,0,0]
	v_mfma_scale_f32_16x16x128_f8f6f4 v[214:217], v[150:157], v[198:205], v[72:75], v140, v140 op_sel_hi:[0,0,0]
	v_mfma_scale_f32_16x16x128_f8f6f4 v[116:119], v[158:165], v[174:181], v[116:119], v140, v140 op_sel_hi:[0,0,0]
	v_mfma_scale_f32_16x16x128_f8f6f4 v[108:111], v[166:173], v[174:181], v[108:111], v140, v140 op_sel_hi:[0,0,0]
	v_mfma_scale_f32_16x16x128_f8f6f4 v[100:103], v[158:165], v[182:189], v[100:103], v140, v140 op_sel_hi:[0,0,0]
	v_mfma_scale_f32_16x16x128_f8f6f4 v[174:177], v[166:173], v[182:189], v[92:95], v140, v140 op_sel_hi:[0,0,0]
	v_mfma_scale_f32_16x16x128_f8f6f4 v[178:181], v[158:165], v[190:197], v[84:87], v140, v140 op_sel_hi:[0,0,0]
	v_mfma_scale_f32_16x16x128_f8f6f4 v[182:185], v[166:173], v[190:197], v[76:79], v140, v140 op_sel_hi:[0,0,0]
	v_mfma_scale_f32_16x16x128_f8f6f4 v[186:189], v[158:165], v[198:205], v[68:71], v140, v140 op_sel_hi:[0,0,0]
	v_mfma_scale_f32_16x16x128_f8f6f4 v[190:193], v[166:173], v[198:205], v[64:67], v140, v140 op_sel_hi:[0,0,0]
	s_barrier
	s_setprio 0
	s_add_i32 s56, s45, s30
	s_mov_b32 m0, s56
	s_nop 1
	ds_read_b128 v[64:67], v139 offset:16384
	ds_read_b128 v[68:71], v139 offset:17408
	ds_read_b128 v[72:75], v139 offset:18432
	ds_read_b128 v[76:79], v139 offset:19456
	ds_read_b128 v[80:83], v139 offset:20480
	ds_read_b128 v[84:87], v139 offset:21504
	ds_read_b128 v[88:91], v139 offset:22528

; #define PG8_WAIT_V(n) asm volatile("s_waitcnt vmcnt(" #n ")" ::: "memory")
; #define PG8_WAIT_L(n) asm volatile("s_waitcnt lgkmcnt(" #n ")" ::: "memory")
; #define PG8_BAR __builtin_amdgcn_s_barrier()
; #define PG8_SCHED __builtin_amdgcn_sched_barrier(0)
;     ...
;             if constexpr (!HALFU) PG8_LDA(At, 0, 1); PG8_STAGE(PG8_SB(0, 0), b2, voffB); PG8_STAGE(PG8_SB(0, 1), b2 + hstep, voffB); PG8_STAGE(PG8_SA(0, 0), a2, voffA);
;             PG8_WAIT_V(8); PG8_WAIT_L(0); PG8_BAR; if constexpr (!HALFU) { PG8_MMA(1, 0, At, B0); PG8_MMA(1, 1, At, B1); } PG8_BAR; PG8_SCHED;
;             PG8_LDB(B0, 1, 0); PG8_LDB(B1, 1, 1); PG8_SCHED; PG8_LDA(At, 1, 0); PG8_STAGE(PG8_SA(0, 1), a2 + hstepA, voffA);
	global_load_lds_dwordx4 v128, s[26:27]
	s_add_i32 m0, s56, 0x2000
	s_add_u32 s56, s26, 0x158000
	s_addc_u32 s57, s27, 0
	s_add_i32 s58, s46, s30
	global_load_lds_dwordx4 v130, s[26:27]
	s_mov_b32 m0, s58
	ds_read_b128 v[92:95], v139 offset:23552
	global_load_lds_dwordx4 v128, s[56:57]
	s_add_i32 m0, s58, 0x2000
	s_nop 0
	global_load_lds_dwordx4 v130, s[56:57]
	s_waitcnt vmcnt(4)
	s_waitcnt lgkmcnt(0)
	s_setprio 1
	s_barrier
	v_mfma_scale_f32_16x16x128_f8f6f4 v[60:63], v[142:149], v[64:71], v[60:63], v140, v140 op_sel_hi:[0,0,0]
	v_mfma_scale_f32_16x16x128_f8f6f4 v[56:59], v[150:157], v[64:71], v[56:59], v140, v140 op_sel_hi:[0,0,0]
	v_mfma_scale_f32_16x16x128_f8f6f4 v[48:51], v[142:149], v[72:79], v[48:51], v140, v140 op_sel_hi:[0,0,0]
	v_mfma_scale_f32_16x16x128_f8f6f4 v[194:197], v[150:157], v[72:79], v[40:43], v140, v140 op_sel_hi:[0,0,0]
	v_mfma_scale_f32_16x16x128_f8f6f4 v[198:201], v[142:149], v[80:87], v[32:35], v140, v140 op_sel_hi:[0,0,0]
	v_mfma_scale_f32_16x16x128_f8f6f4 v[202:205], v[150:157], v[80:87], v[24:27], v140, v140 op_sel_hi:[0,0,0]
	v_mfma_scale_f32_16x16x128_f8f6f4 v[218:221], v[142:149], v[88:95], v[16:19], v140, v140 op_sel_hi:[0,0,0]
	v_mfma_scale_f32_16x16x128_f8f6f4 v[222:225], v[150:157], v[88:95], v[8:11], v140, v140 op_sel_hi:[0,0,0]
	v_mfma_scale_f32_16x16x128_f8f6f4 v[52:55], v[158:165], v[64:71], v[52:55], v140, v140 op_sel_hi:[0,0,0]
	v_mfma_scale_f32_16x16x128_f8f6f4 v[226:229], v[166:173], v[64:71], v[44:47], v140, v140 op_sel_hi:[0,0,0]
	v_mfma_scale_f32_16x16x128_f8f6f4 v[230:233], v[158:165], v[72:79], v[36:39], v140, v140 op_sel_hi:[0,0,0]
	v_mfma_scale_f32_16x16x128_f8f6f4 v[234:237], v[166:173], v[72:79], v[28:31], v140, v140 op_sel_hi:[0,0,0]
	v_mfma_scale_f32_16x16x128_f8f6f4 v[238:241], v[158:165], v[80:87], v[20:23], v140, v140 op_sel_hi:[0,0,0]
	v_mfma_scale_f32_16x16x128_f8f6f4 v[242:245], v[166:173], v[80:87], v[12:15], v140, v140 op_sel_hi:[0,0,0]
	v_mfma_scale_f32_16x16x128_f8f6f4 v[246:249], v[158:165], v[88:95], v[4:7], v140, v140 op_sel_hi:[0,0,0]
	v_mfma_scale_f32_16x16x128_f8f6f4 v[250:253], v[166:173], v[88:95], v[0:3], v140, v140 op_sel_hi:[0,0,0]
	s_barrier
	s_setprio 0
	s_mov_b32 m0, s33
	s_nop 0
	global_load_lds_dwordx4 v128, s[28:29]
	s_mov_b32 m0, s36
	s_nop 0
	global_load_lds_dwordx4 v130, s[28:29]
	s_add_i32 s56, 0, 0x18000
	s_add_i32 s57, 0, 0x1c000
	s_nop 0
	v_add_u32_e32 v12, s56, v136
	v_add_u32_e32 v16, s57, v136
	ds_read_b128 v[0:3], v12
	ds_read_b128 v[4:7], v12 offset:1024
	ds_read_b128 v[8:11], v12 offset:2048
	ds_read_b128 v[12:15], v12 offset:3072
	ds_read_b128 v[142:145], v16
	ds_read_b128 v[146:149], v16 offset:1024
	ds_read_b128 v[150:153], v16 offset:2048
	ds_read_b128 v[154:157], v16 offset:3072
	s_add_u32 s28, s28, 0x158000
	s_addc_u32 s29, s29, 0
	s_mov_b32 m0, s37
	ds_read_b128 v[16:19], v139 offset:32768
	ds_read_b128 v[20:23], v139 offset:33792
	ds_read_b128 v[24:27], v139 offset:34816
	ds_read_b128 v[28:31], v139 offset:35840
	ds_read_b128 v[32:35], v139 offset:36864
	ds_read_b128 v[36:39], v139 offset:37888
	ds_read_b128 v[40:43], v139 offset:38912

; #define PG8_WAIT_V(n) asm volatile("s_waitcnt vmcnt(" #n ")" ::: "memory")
; #define PG8_WAIT_L(n) asm volatile("s_waitcnt lgkmcnt(" #n ")" ::: "memory")
; #define PG8_BAR __builtin_amdgcn_s_barrier()
; #define PG8_SCHED __builtin_amdgcn_sched_barrier(0)
;     ...
;             PG8_LDB(B0, 1, 0); PG8_LDB(B1, 1, 1); PG8_SCHED; PG8_LDA(At, 1, 0); PG8_STAGE(PG8_SA(0, 1), a2 + hstepA, voffA);
;             PG8_WAIT_V(8); PG8_WAIT_L(0); PG8_BAR; PG8_MMA(0, 0, At, B0); PG8_MMA(0, 1, At, B1); PG8_BAR; PG8_SCHED;
;             if constexpr (!HALFU) PG8_LDA(At, 1, 1); PG8_STAGE(PG8_SB(1, 0), b3, voffB); PG8_STAGE(PG8_SB(1, 1), b3 + hstep, voffB); PG8_STAGE(PG8_SA(1, 0), a3, voffA);
	global_load_lds_dwordx4 v128, s[28:29]
	s_mov_b32 m0, s38
	ds_read_b128 v[44:47], v139 offset:39936
	global_load_lds_dwordx4 v130, s[28:29]
	s_waitcnt vmcnt(8)
	s_waitcnt lgkmcnt(0)
	s_setprio 1
	s_barrier
	v_mfma_scale_f32_16x16x128_f8f6f4 v[124:127], v[0:7], v[16:23], v[124:127], v140, v140 op_sel_hi:[0,0,0]
	v_mfma_scale_f32_16x16x128_f8f6f4 v[120:123], v[8:15], v[16:23], v[120:123], v140, v140 op_sel_hi:[0,0,0]
	v_mfma_scale_f32_16x16x128_f8f6f4 v[112:115], v[0:7], v[24:31], v[112:115], v140, v140 op_sel_hi:[0,0,0]
	v_mfma_scale_f32_16x16x128_f8f6f4 v[104:107], v[8:15], v[24:31], v[104:107], v140, v140 op_sel_hi:[0,0,0]
	v_mfma_scale_f32_16x16x128_f8f6f4 v[96:99], v[0:7], v[32:39], v[96:99], v140, v140 op_sel_hi:[0,0,0]
	v_mfma_scale_f32_16x16x128_f8f6f4 v[88:91], v[8:15], v[32:39], v[206:209], v140, v140 op_sel_hi:[0,0,0]
	v_mfma_scale_f32_16x16x128_f8f6f4 v[80:83], v[0:7], v[40:47], v[210:213], v140, v140 op_sel_hi:[0,0,0]
	v_mfma_scale_f32_16x16x128_f8f6f4 v[72:75], v[8:15], v[40:47], v[214:217], v140, v140 op_sel_hi:[0,0,0]
	v_mfma_scale_f32_16x16x128_f8f6f4 v[116:119], v[142:149], v[16:23], v[116:119], v140, v140 op_sel_hi:[0,0,0]
	v_mfma_scale_f32_16x16x128_f8f6f4 v[108:111], v[150:157], v[16:23], v[108:111], v140, v140 op_sel_hi:[0,0,0]
	v_mfma_scale_f32_16x16x128_f8f6f4 v[100:103], v[142:149], v[24:31], v[100:103], v140, v140 op_sel_hi:[0,0,0]
	v_mfma_scale_f32_16x16x128_f8f6f4 v[92:95], v[150:157], v[24:31], v[174:177], v140, v140 op_sel_hi:[0,0,0]
	v_mfma_scale_f32_16x16x128_f8f6f4 v[84:87], v[142:149], v[32:39], v[178:181], v140, v140 op_sel_hi:[0,0,0]
	v_mfma_scale_f32_16x16x128_f8f6f4 v[76:79], v[150:157], v[32:39], v[182:185], v140, v140 op_sel_hi:[0,0,0]
	v_mfma_scale_f32_16x16x128_f8f6f4 v[68:71], v[142:149], v[40:47], v[186:189], v140, v140 op_sel_hi:[0,0,0]
	v_mfma_scale_f32_16x16x128_f8f6f4 v[64:67], v[150:157], v[40:47], v[190:193], v140, v140 op_sel_hi:[0,0,0]
	s_barrier
	s_setprio 0
	s_add_u32 s28, s26, 0x80
	s_addc_u32 s29, s27, 0
	s_add_i32 s56, s56, s30
	s_mov_b32 m0, s56
	ds_read_b128 v[158:161], v139 offset:49152
	ds_read_b128 v[162:165], v139 offset:50176
	ds_read_b128 v[166:169], v139 offset:51200
	ds_read_b128 v[170:173], v139 offset:52224
	ds_read_b128 v[174:177], v139 offset:53248
	ds_read_b128 v[178:181], v139 offset:54272
	ds_read_b128 v[182:185], v139 offset:55296

; #define PG8_WAIT_V(n) asm volatile("s_waitcnt vmcnt(" #n ")" ::: "memory")
; #define PG8_WAIT_L(n) asm volatile("s_waitcnt lgkmcnt(" #n ")" ::: "memory")
; #define PG8_BAR __builtin_amdgcn_s_barrier()
; #define PG8_SCHED __builtin_amdgcn_sched_barrier(0)
;     ...
;             PG8_LDB(B0, 0, 0); PG8_LDB(B1, 0, 1); PG8_SCHED; PG8_LDA(At, 0, 0); PG8_STAGE(PG8_SA(1, 1), a1 + hstepA, voffA);
;             PG8_WAIT_V(8); PG8_WAIT_L(0); PG8_BAR; PG8_MMA(0, 0, At, B0); PG8_MMA(0, 1, At, B1); PG8_BAR; PG8_SCHED;
;             if constexpr (!HALFU) PG8_LDA(At, 0, 1); PG8_STAGE(PG8_SB(0, 0), b2, voffB); PG8_STAGE(PG8_SB(0, 1), b2 + hstep, voffB); PG8_STAGE(PG8_SA(0, 0), a2, voffA);
;             PG8_WAIT_V(8); PG8_WAIT_L(0); PG8_BAR; if constexpr (!HALFU) { PG8_MMA(1, 0, At, B0); PG8_MMA(1, 1, At, B1); } PG8_BAR; PG8_SCHED;
;             PG8_LDB(B0, 1, 0); PG8_LDB(B1, 1, 1); PG8_SCHED; PG8_LDA(At, 1, 0); PG8_STAGE(PG8_SA(0, 1), a2 + hstepA, voffA);
;             PG8_WAIT_V(8); PG8_WAIT_L(0); PG8_BAR; PG8_MMA(0, 0, At, B0); PG8_MMA(0, 1, At, B1); PG8_BAR; PG8_SCHED;
;             if constexpr (!HALFU) PG8_LDA(At, 1, 1); PG8_STAGE(PG8_SB(1, 0), b3, voffB); PG8_STAGE(PG8_SB(1, 1), b3 + hstep, voffB); PG8_STAGE(PG8_SA(1, 0), a3, voffA);
;             PG8_WAIT_V(8); PG8_WAIT_L(0); PG8_BAR; if constexpr (!HALFU) { PG8_MMA(1, 0, At, B0); PG8_MMA(1, 1, At, B1); } PG8_BAR; PG8_SCHED;
	global_load_lds_dwordx4 v128, s[28:29]
	s_add_i32 m0, s56, 0x2000
	s_add_u32 s26, s26, 0x158080
	v_lshl_add_u64 v[16:17], s[28:29], 0, v[130:131]
	s_addc_u32 s27, s27, 0
	s_add_i32 s28, s57, s30
	global_load_lds_dwordx4 v[16:17], off
	s_mov_b32 m0, s28
	ds_read_b128 v[186:189], v139 offset:56320
	global_load_lds_dwordx4 v128, s[26:27]
	s_add_i32 m0, s28, 0x2000
	s_nop 0
	global_load_lds_dwordx4 v130, s[26:27]
	s_waitcnt vmcnt(4)
	s_waitcnt lgkmcnt(0)
	s_setprio 1
	s_barrier
	v_mfma_scale_f32_16x16x128_f8f6f4 v[60:63], v[0:7], v[158:165], v[60:63], v140, v140 op_sel_hi:[0,0,0]
	v_mfma_scale_f32_16x16x128_f8f6f4 v[56:59], v[8:15], v[158:165], v[56:59], v140, v140 op_sel_hi:[0,0,0]
	v_mfma_scale_f32_16x16x128_f8f6f4 v[48:51], v[0:7], v[166:173], v[48:51], v140, v140 op_sel_hi:[0,0,0]
	v_mfma_scale_f32_16x16x128_f8f6f4 v[40:43], v[8:15], v[166:173], v[194:197], v140, v140 op_sel_hi:[0,0,0]
	v_mfma_scale_f32_16x16x128_f8f6f4 v[32:35], v[0:7], v[174:181], v[198:201], v140, v140 op_sel_hi:[0,0,0]
	v_mfma_scale_f32_16x16x128_f8f6f4 v[24:27], v[8:15], v[174:181], v[202:205], v140, v140 op_sel_hi:[0,0,0]
	v_mfma_scale_f32_16x16x128_f8f6f4 v[16:19], v[0:7], v[182:189], v[218:221], v140, v140 op_sel_hi:[0,0,0]
	v_mfma_scale_f32_16x16x128_f8f6f4 v[8:11], v[8:15], v[182:189], v[222:225], v140, v140 op_sel_hi:[0,0,0]
	v_mfma_scale_f32_16x16x128_f8f6f4 v[52:55], v[142:149], v[158:165], v[52:55], v140, v140 op_sel_hi:[0,0,0]
	v_mfma_scale_f32_16x16x128_f8f6f4 v[44:47], v[150:157], v[158:165], v[226:229], v140, v140 op_sel_hi:[0,0,0]
	v_mfma_scale_f32_16x16x128_f8f6f4 v[36:39], v[142:149], v[166:173], v[230:233], v140, v140 op_sel_hi:[0,0,0]
	v_mfma_scale_f32_16x16x128_f8f6f4 v[28:31], v[150:157], v[166:173], v[234:237], v140, v140 op_sel_hi:[0,0,0]
	v_mfma_scale_f32_16x16x128_f8f6f4 v[20:23], v[142:149], v[174:181], v[238:241], v140, v140 op_sel_hi:[0,0,0]
	v_mfma_scale_f32_16x16x128_f8f6f4 v[12:15], v[150:157], v[174:181], v[242:245], v140, v140 op_sel_hi:[0,0,0]
	v_mfma_scale_f32_16x16x128_f8f6f4 v[4:7], v[142:149], v[182:189], v[246:249], v140, v140 op_sel_hi:[0,0,0]
	v_mfma_scale_f32_16x16x128_f8f6f4 v[0:3], v[150:157], v[182:189], v[250:253], v140, v140 op_sel_hi:[0,0,0]
	s_barrier
	s_setprio 0
	s_add_i32 s55, s55, 2
	s_add_u32 s51, s51, 0x100
	s_addc_u32 s52, s52, 0
	s_add_u32 s53, s53, 0x100
	s_addc_u32 s54, s54, 0
	s_add_u32 s10, s10, 0x100
	s_addc_u32 s11, s11, 0
	s_cmpk_gt_u32 s55, 0x53
	s_cbranch_scc0 .LBB0_3640
	s_and_b64 vcc, exec, s[12:13]
	s_cbranch_vccz .LBB0_3643
	s_barrier
